# GEMM K-loops: removed the s_nop 0 fillers left where VALU address adds and s_setprio were deleted (kept the m0->LDS-DMA wait states)
# baseline (speedup 1.0000x reference)
; #define PG8_STAGE(bufoff, gbase, voff) do { _Pragma("unroll") for (int _i = 0; _i < 2; ++_i) \
;         __builtin_amdgcn_global_load_lds((const unsigned*)((const char*)(gbase) + (voff)[_i]), (LAS unsigned*)(lds + (bufoff) + ldsw + _i * 8192), 16, 0, 0); } while (0)
; #define PG8_LDA(dst, b, h) do { _Pragma("unroll") for (int m = 0; m < 4; ++m) _Pragma("unroll") for (int k = 0; k < 2; ++k) dst[m][k] = *(const LAS bf16x8*)(lds + PG8_SA(b, h) + aoff + m * 2048 + k * 1024); } while (0)
; #define PG8_LDB(dst, b, h) do { _Pragma("unroll") for (int n = 0; n < 2; ++n) _Pragma("unroll") for (int k = 0; k < 2; ++k) dst[n][k] = *(const LAS bf16x8*)(lds + PG8_SB(b, h) + boff + n * 2048 + k * 1024); } while (0)
; #define PG8_MMA(ai, bj, At, Bt) do { __builtin_amdgcn_s_setprio(1); _Pragma("unroll") for (int m = 0; m < 4; ++m) _Pragma("unroll") for (int n = 0; n < 2; ++n) _Pragma("unroll") for (int k = 0; k < 2; ++k) \
;         acc[ai][bj][m][n] = __builtin_amdgcn_mfma_f32_16x16x32_bf16(Bt[n][k], At[m][k], acc[ai][bj][m][n], 0, 0, 0); __builtin_amdgcn_s_setprio(0); } while (0)
; #define PG8_WAIT_V(n) asm volatile("s_waitcnt vmcnt(" #n ")" ::: "memory")
; #define PG8_WAIT_L(n) asm volatile("s_waitcnt lgkmcnt(" #n ")" ::: "memory")
; #define PG8_BAR __builtin_amdgcn_s_barrier()
; #define PG8_SCHED __builtin_amdgcn_sched_barrier(0)
; template <class Epi, class Sched>
; DI void gemm_phase(LAS unsigned char* lds, const int K, const Sched& S, const Epi& E) {
;     ...
;             const char* a1 = cA + (size_t)(t + 1) * kstep;
;             const char* a2 = last ? nA : cA + (size_t)(t + 2) * kstep; const char* b2 = last ? nB : cB + (size_t)(t + 2) * kstep;
;             const char* a3 = a2 + kstep; const char* b3 = b2 + kstep;
;             PG8_LDB(B0, 0, 0); PG8_LDB(B1, 0, 1); PG8_SCHED; PG8_LDA(At, 0, 0); PG8_STAGE(PG8_SA(1, 1), a1 + hstep, voffA);
;             PG8_WAIT_V(8); PG8_WAIT_L(0); PG8_BAR; PG8_MMA(0, 0, At, B0); PG8_MMA(0, 1, At, B1); PG8_BAR; PG8_SCHED;
;             PG8_LDA(At, 0, 1); PG8_STAGE(PG8_SB(0, 0), b2, voffB); PG8_STAGE(PG8_SB(0, 1), b2 + hstep, voffB); PG8_STAGE(PG8_SA(0, 0), a2, voffA);
;             PG8_WAIT_V(8); PG8_WAIT_L(0); PG8_BAR; PG8_MMA(1, 0, At, B0); PG8_MMA(1, 1, At, B1); PG8_BAR; PG8_SCHED;
.LBB0_218:
	s_add_u32 s80, s78, 0xfffc0080
	s_addc_u32 s81, s79, -1
	s_add_i32 vcc_lo, 0, 0x10000
	s_cmp_eq_u32 s87, 12
	s_cselect_b32 s83, s45, s81
	s_cselect_b32 s82, s73, s80
	s_cselect_b32 s81, s77, s86
	s_cselect_b32 s80, s84, s85
	s_add_i32 s63, 0, 0x14000
	v_add_u32_e32 v142, vcc_lo, v201
	v_add_u32_e32 v158, s63, v201
	ds_read_b128 v[130:133], v142
	ds_read_b128 v[134:137], v142 offset:1024
	ds_read_b128 v[138:141], v142 offset:2048
	ds_read_b128 v[142:145], v142 offset:3072
	ds_read_b128 v[146:149], v158
	ds_read_b128 v[150:153], v158 offset:1024
	ds_read_b128 v[154:157], v158 offset:2048
	ds_read_b128 v[158:161], v158 offset:3072
	s_add_i32 m0, s56, 0xc000
	ds_read_b128 v[174:177], v202
	ds_read_b128 v[182:185], v202 offset:1024
	ds_read_b128 v[190:193], v202 offset:2048
	ds_read_b128 v[194:197], v202 offset:3072
	ds_read_b128 v[212:215], v202 offset:4096
	ds_read_b128 v[216:219], v202 offset:5120
	ds_read_b128 v[220:223], v202 offset:6144
	ds_read_b128 v[224:227], v202 offset:7168
	global_load_lds_dwordx4 v172, s[78:79]
	s_add_i32 m0, s56, 0xe000
	s_nop 0
	global_load_lds_dwordx4 v170, s[78:79]
	s_waitcnt vmcnt(8)
	s_waitcnt lgkmcnt(0)
	s_barrier
	s_waitcnt lgkmcnt(0)
	v_mfma_f32_16x16x32_bf16 v[126:129], v[130:133], v[174:177], v[126:129]
	v_mfma_f32_16x16x32_bf16 v[122:125], v[138:141], v[174:177], v[122:125]
	v_mfma_f32_16x16x32_bf16 v[110:113], v[130:133], v[190:193], v[110:113]
	v_mfma_f32_16x16x32_bf16 v[106:109], v[138:141], v[190:193], v[106:109]
	v_mfma_f32_16x16x32_bf16 v[94:97], v[130:133], v[212:215], v[94:97]
	v_mfma_f32_16x16x32_bf16 v[90:93], v[138:141], v[212:215], v[90:93]
	v_mfma_f32_16x16x32_bf16 v[78:81], v[130:133], v[220:223], v[78:81]
	v_mfma_f32_16x16x32_bf16 v[74:77], v[138:141], v[220:223], v[74:77]
	v_mfma_f32_16x16x32_bf16 v[126:129], v[134:137], v[182:185], v[126:129]
	v_mfma_f32_16x16x32_bf16 v[122:125], v[142:145], v[182:185], v[122:125]
	v_mfma_f32_16x16x32_bf16 v[110:113], v[134:137], v[194:197], v[110:113]
	v_mfma_f32_16x16x32_bf16 v[106:109], v[142:145], v[194:197], v[106:109]
	v_mfma_f32_16x16x32_bf16 v[94:97], v[134:137], v[216:219], v[94:97]
	v_mfma_f32_16x16x32_bf16 v[90:93], v[142:145], v[216:219], v[90:93]
	v_mfma_f32_16x16x32_bf16 v[78:81], v[134:137], v[224:227], v[78:81]
	v_mfma_f32_16x16x32_bf16 v[74:77], v[142:145], v[224:227], v[74:77]
	v_mfma_f32_16x16x32_bf16 v[118:121], v[146:149], v[174:177], v[118:121]
	v_mfma_f32_16x16x32_bf16 v[114:117], v[154:157], v[174:177], v[114:117]
	v_mfma_f32_16x16x32_bf16 v[102:105], v[146:149], v[190:193], v[102:105]
	v_mfma_f32_16x16x32_bf16 v[98:101], v[154:157], v[190:193], v[98:101]
	v_mfma_f32_16x16x32_bf16 v[86:89], v[146:149], v[212:215], v[86:89]
	v_mfma_f32_16x16x32_bf16 v[82:85], v[154:157], v[212:215], v[82:85]
	v_mfma_f32_16x16x32_bf16 v[70:73], v[146:149], v[220:223], v[70:73]
	v_mfma_f32_16x16x32_bf16 v[66:69], v[154:157], v[220:223], v[66:69]
	v_mfma_f32_16x16x32_bf16 v[118:121], v[150:153], v[182:185], v[118:121]
	v_mfma_f32_16x16x32_bf16 v[114:117], v[158:161], v[182:185], v[114:117]
	v_mfma_f32_16x16x32_bf16 v[102:105], v[150:153], v[194:197], v[102:105]
	v_mfma_f32_16x16x32_bf16 v[98:101], v[158:161], v[194:197], v[98:101]
	v_mfma_f32_16x16x32_bf16 v[86:89], v[150:153], v[216:219], v[86:89]
	v_mfma_f32_16x16x32_bf16 v[82:85], v[158:161], v[216:219], v[82:85]
	v_mfma_f32_16x16x32_bf16 v[70:73], v[150:153], v[224:227], v[70:73]
	v_mfma_f32_16x16x32_bf16 v[66:69], v[158:161], v[224:227], v[66:69]
	s_barrier
	s_add_i32 vcc_lo, vcc_lo, s55
	s_mov_b32 m0, vcc_lo
	ds_read_b128 v[174:177], v202 offset:16384
	ds_read_b128 v[182:185], v202 offset:17408
	ds_read_b128 v[190:193], v202 offset:18432
	ds_read_b128 v[194:197], v202 offset:19456
	ds_read_b128 v[212:215], v202 offset:20480
	ds_read_b128 v[216:219], v202 offset:21504
	ds_read_b128 v[220:223], v202 offset:22528
	ds_read_b128 v[224:227], v202 offset:23552
	global_load_lds_dwordx4 v164, s[80:81]
	s_add_i32 m0, vcc_lo, 0x2000
	s_add_u32 vcc_lo, s80, 0x40000
	s_addc_u32 vcc_hi, s81, 0
	s_add_i32 s63, s63, s55
	global_load_lds_dwordx4 v168, s[80:81]
	s_mov_b32 m0, s63
	s_nop 0
	global_load_lds_dwordx4 v164, vcc
	s_add_i32 m0, s63, 0x2000
	s_nop 0
	global_load_lds_dwordx4 v168, vcc
	s_add_u32 s98, s82, s90
	s_addc_u32 s99, s83, s91
	s_waitcnt vmcnt(6)
	s_waitcnt lgkmcnt(0)
	s_barrier
	s_waitcnt lgkmcnt(0)
	v_mfma_f32_16x16x32_bf16 v[62:65], v[130:133], v[174:177], v[62:65]
	v_mfma_f32_16x16x32_bf16 v[58:61], v[138:141], v[174:177], v[58:61]
	v_mfma_f32_16x16x32_bf16 v[46:49], v[130:133], v[190:193], v[46:49]
	v_mfma_f32_16x16x32_bf16 v[42:45], v[138:141], v[190:193], v[42:45]
	v_mfma_f32_16x16x32_bf16 v[30:33], v[130:133], v[212:215], v[30:33]
	v_mfma_f32_16x16x32_bf16 v[26:29], v[138:141], v[212:215], v[26:29]
	v_mfma_f32_16x16x32_bf16 v[14:17], v[130:133], v[220:223], v[14:17]
	v_mfma_f32_16x16x32_bf16 v[10:13], v[138:141], v[220:223], v[10:13]
	v_mfma_f32_16x16x32_bf16 v[62:65], v[134:137], v[182:185], v[62:65]
	v_mfma_f32_16x16x32_bf16 v[58:61], v[142:145], v[182:185], v[58:61]
	v_mfma_f32_16x16x32_bf16 v[46:49], v[134:137], v[194:197], v[46:49]
	v_mfma_f32_16x16x32_bf16 v[42:45], v[142:145], v[194:197], v[42:45]
	v_mfma_f32_16x16x32_bf16 v[30:33], v[134:137], v[216:219], v[30:33]
	v_mfma_f32_16x16x32_bf16 v[26:29], v[142:145], v[216:219], v[26:29]
	v_mfma_f32_16x16x32_bf16 v[14:17], v[134:137], v[224:227], v[14:17]
	v_mfma_f32_16x16x32_bf16 v[10:13], v[142:145], v[224:227], v[10:13]
	v_mfma_f32_16x16x32_bf16 v[54:57], v[146:149], v[174:177], v[54:57]
	v_mfma_f32_16x16x32_bf16 v[50:53], v[154:157], v[174:177], v[50:53]
	v_mfma_f32_16x16x32_bf16 v[38:41], v[146:149], v[190:193], v[38:41]
	v_mfma_f32_16x16x32_bf16 v[34:37], v[154:157], v[190:193], v[34:37]
	v_mfma_f32_16x16x32_bf16 v[22:25], v[146:149], v[212:215], v[22:25]
	v_mfma_f32_16x16x32_bf16 v[18:21], v[154:157], v[212:215], v[18:21]
	v_mfma_f32_16x16x32_bf16 v[6:9], v[146:149], v[220:223], v[6:9]
	v_mfma_f32_16x16x32_bf16 v[2:5], v[154:157], v[220:223], v[2:5]
	v_mfma_f32_16x16x32_bf16 v[54:57], v[150:153], v[182:185], v[54:57]
	v_mfma_f32_16x16x32_bf16 v[50:53], v[158:161], v[182:185], v[50:53]
	v_mfma_f32_16x16x32_bf16 v[38:41], v[150:153], v[194:197], v[38:41]
	v_mfma_f32_16x16x32_bf16 v[34:37], v[158:161], v[194:197], v[34:37]
	v_mfma_f32_16x16x32_bf16 v[22:25], v[150:153], v[216:219], v[22:25]
	v_mfma_f32_16x16x32_bf16 v[18:21], v[158:161], v[216:219], v[18:21]
	v_mfma_f32_16x16x32_bf16 v[6:9], v[150:153], v[224:227], v[6:9]
	v_mfma_f32_16x16x32_bf16 v[2:5], v[158:161], v[224:227], v[2:5]
	s_barrier
; #define PG8_STAGE(bufoff, gbase, voff) do { _Pragma("unroll") for (int _i = 0; _i < 2; ++_i) \
;         __builtin_amdgcn_global_load_lds((const unsigned*)((const char*)(gbase) + (voff)[_i]), (LAS unsigned*)(lds + (bufoff) + ldsw + _i * 8192), 16, 0, 0); } while (0)
; #define PG8_LDA(dst, b, h) do { _Pragma("unroll") for (int m = 0; m < 4; ++m) _Pragma("unroll") for (int k = 0; k < 2; ++k) dst[m][k] = *(const LAS bf16x8*)(lds + PG8_SA(b, h) + aoff + m * 2048 + k * 1024); } while (0)
; #define PG8_LDB(dst, b, h) do { _Pragma("unroll") for (int n = 0; n < 2; ++n) _Pragma("unroll") for (int k = 0; k < 2; ++k) dst[n][k] = *(const LAS bf16x8*)(lds + PG8_SB(b, h) + boff + n * 2048 + k * 1024); } while (0)
; #define PG8_MMA(ai, bj, At, Bt) do { __builtin_amdgcn_s_setprio(1); _Pragma("unroll") for (int m = 0; m < 4; ++m) _Pragma("unroll") for (int n = 0; n < 2; ++n) _Pragma("unroll") for (int k = 0; k < 2; ++k) \
;         acc[ai][bj][m][n] = __builtin_amdgcn_mfma_f32_16x16x32_bf16(Bt[n][k], At[m][k], acc[ai][bj][m][n], 0, 0, 0); __builtin_amdgcn_s_setprio(0); } while (0)
; #define PG8_WAIT_V(n) asm volatile("s_waitcnt vmcnt(" #n ")" ::: "memory")
; #define PG8_WAIT_L(n) asm volatile("s_waitcnt lgkmcnt(" #n ")" ::: "memory")
; #define PG8_BAR __builtin_amdgcn_s_barrier()
; #define PG8_SCHED __builtin_amdgcn_sched_barrier(0)
; template <class Epi, class Sched>
; DI void gemm_phase(LAS unsigned char* lds, const int K, const Sched& S, const Epi& E) {
;     ...
;             PG8_LDB(B0, 1, 0); PG8_LDB(B1, 1, 1); PG8_SCHED; PG8_LDA(At, 1, 0); PG8_STAGE(PG8_SA(0, 1), a2 + hstep, voffA);
;             PG8_WAIT_V(8); PG8_WAIT_L(0); PG8_BAR; PG8_MMA(0, 0, At, B0); PG8_MMA(0, 1, At, B1); PG8_BAR; PG8_SCHED;
;             PG8_LDA(At, 1, 1); PG8_STAGE(PG8_SB(1, 0), b3, voffB); PG8_STAGE(PG8_SB(1, 1), b3 + hstep, voffB); PG8_STAGE(PG8_SA(1, 0), a3, voffA);
;             PG8_WAIT_V(8); PG8_WAIT_L(0); PG8_BAR; PG8_MMA(1, 0, At, B0); PG8_MMA(1, 1, At, B1); PG8_BAR; PG8_SCHED;
;         }
;         if (wr == 0) PG8_BAR;
	s_add_i32 s63, 0, 0x18000
	s_add_i32 vcc_lo, 0, 0x1c000
	v_add_u32_e32 v142, s63, v201
	v_add_u32_e32 v158, vcc_lo, v201
	ds_read_b128 v[130:133], v142
	ds_read_b128 v[134:137], v142 offset:1024
	ds_read_b128 v[138:141], v142 offset:2048
	ds_read_b128 v[142:145], v142 offset:3072
	ds_read_b128 v[146:149], v158
	ds_read_b128 v[150:153], v158 offset:1024
	ds_read_b128 v[154:157], v158 offset:2048
	ds_read_b128 v[158:161], v158 offset:3072
	s_mov_b32 m0, s56
	ds_read_b128 v[174:177], v202 offset:32768
	ds_read_b128 v[182:185], v202 offset:33792
	ds_read_b128 v[190:193], v202 offset:34816
	ds_read_b128 v[194:197], v202 offset:35840
	ds_read_b128 v[212:215], v202 offset:36864
	ds_read_b128 v[216:219], v202 offset:37888
	ds_read_b128 v[220:223], v202 offset:38912
	ds_read_b128 v[224:227], v202 offset:39936
	global_load_lds_dwordx4 v162, s[82:83]
	s_mov_b32 m0, s57
	s_nop 0
	global_load_lds_dwordx4 v166, s[82:83]
	s_add_u32 s82, s82, 0x40000
	s_addc_u32 s83, s83, 0
	s_mov_b32 m0, s58
	s_nop 0
	global_load_lds_dwordx4 v162, s[82:83]
	s_mov_b32 m0, s59
	s_nop 0
	global_load_lds_dwordx4 v166, s[82:83]
	s_waitcnt vmcnt(8)
	s_waitcnt lgkmcnt(0)
	s_barrier
	s_waitcnt lgkmcnt(0)
	v_mfma_f32_16x16x32_bf16 v[126:129], v[130:133], v[174:177], v[126:129]
	v_mfma_f32_16x16x32_bf16 v[122:125], v[138:141], v[174:177], v[122:125]
	v_mfma_f32_16x16x32_bf16 v[110:113], v[130:133], v[190:193], v[110:113]
	v_mfma_f32_16x16x32_bf16 v[106:109], v[138:141], v[190:193], v[106:109]
	v_mfma_f32_16x16x32_bf16 v[94:97], v[130:133], v[212:215], v[94:97]
	v_mfma_f32_16x16x32_bf16 v[90:93], v[138:141], v[212:215], v[90:93]
	v_mfma_f32_16x16x32_bf16 v[78:81], v[130:133], v[220:223], v[78:81]
	v_mfma_f32_16x16x32_bf16 v[74:77], v[138:141], v[220:223], v[74:77]
	v_mfma_f32_16x16x32_bf16 v[126:129], v[134:137], v[182:185], v[126:129]
	v_mfma_f32_16x16x32_bf16 v[122:125], v[142:145], v[182:185], v[122:125]
	v_mfma_f32_16x16x32_bf16 v[110:113], v[134:137], v[194:197], v[110:113]
	v_mfma_f32_16x16x32_bf16 v[106:109], v[142:145], v[194:197], v[106:109]
	v_mfma_f32_16x16x32_bf16 v[94:97], v[134:137], v[216:219], v[94:97]
	v_mfma_f32_16x16x32_bf16 v[90:93], v[142:145], v[216:219], v[90:93]
	v_mfma_f32_16x16x32_bf16 v[78:81], v[134:137], v[224:227], v[78:81]
	v_mfma_f32_16x16x32_bf16 v[74:77], v[142:145], v[224:227], v[74:77]
	v_mfma_f32_16x16x32_bf16 v[118:121], v[146:149], v[174:177], v[118:121]
	v_mfma_f32_16x16x32_bf16 v[114:117], v[154:157], v[174:177], v[114:117]
	v_mfma_f32_16x16x32_bf16 v[102:105], v[146:149], v[190:193], v[102:105]
	v_mfma_f32_16x16x32_bf16 v[98:101], v[154:157], v[190:193], v[98:101]
	v_mfma_f32_16x16x32_bf16 v[86:89], v[146:149], v[212:215], v[86:89]
	v_mfma_f32_16x16x32_bf16 v[82:85], v[154:157], v[212:215], v[82:85]
	v_mfma_f32_16x16x32_bf16 v[70:73], v[146:149], v[220:223], v[70:73]
	v_mfma_f32_16x16x32_bf16 v[66:69], v[154:157], v[220:223], v[66:69]
	v_mfma_f32_16x16x32_bf16 v[118:121], v[150:153], v[182:185], v[118:121]
	v_mfma_f32_16x16x32_bf16 v[114:117], v[158:161], v[182:185], v[114:117]
	v_mfma_f32_16x16x32_bf16 v[102:105], v[150:153], v[194:197], v[102:105]
	v_mfma_f32_16x16x32_bf16 v[98:101], v[158:161], v[194:197], v[98:101]
	v_mfma_f32_16x16x32_bf16 v[86:89], v[150:153], v[216:219], v[86:89]
	v_mfma_f32_16x16x32_bf16 v[82:85], v[158:161], v[216:219], v[82:85]
	v_mfma_f32_16x16x32_bf16 v[70:73], v[150:153], v[224:227], v[70:73]
	v_mfma_f32_16x16x32_bf16 v[66:69], v[158:161], v[224:227], v[66:69]
	s_barrier
	s_add_i32 s63, s63, s55
	s_add_u32 s80, s80, 0x80
	s_addc_u32 s81, s81, 0
	s_mov_b32 m0, s63
	ds_read_b128 v[174:177], v202 offset:49152
	ds_read_b128 v[182:185], v202 offset:50176
	ds_read_b128 v[190:193], v202 offset:51200
	ds_read_b128 v[194:197], v202 offset:52224
	ds_read_b128 v[212:215], v202 offset:53248
	ds_read_b128 v[216:219], v202 offset:54272
	ds_read_b128 v[220:223], v202 offset:55296
	ds_read_b128 v[224:227], v202 offset:56320
	global_load_lds_dwordx4 v164, s[80:81]
	s_add_i32 m0, s63, 0x2000
	s_add_i32 s63, vcc_lo, s55
	global_load_lds_dwordx4 v168, s[80:81]
	s_add_u32 s80, s80, 0x40000
	s_addc_u32 s81, s81, 0
	s_mov_b32 m0, s63
	s_nop 0
	global_load_lds_dwordx4 v164, s[80:81]
	s_add_i32 m0, s63, 0x2000
	s_nop 0
	global_load_lds_dwordx4 v168, s[80:81]
	s_mov_b32 m0, s47
	s_nop 0
	global_load_lds_dwordx4 v162, s[98:99]
	s_mov_b32 m0, s62
	s_nop 0
	global_load_lds_dwordx4 v166, s[98:99]
	s_waitcnt vmcnt(8)
	s_waitcnt lgkmcnt(0)
	s_barrier
	s_waitcnt lgkmcnt(0)
	v_mfma_f32_16x16x32_bf16 v[62:65], v[130:133], v[174:177], v[62:65]
	v_mfma_f32_16x16x32_bf16 v[58:61], v[138:141], v[174:177], v[58:61]
	v_mfma_f32_16x16x32_bf16 v[46:49], v[130:133], v[190:193], v[46:49]
	v_mfma_f32_16x16x32_bf16 v[42:45], v[138:141], v[190:193], v[42:45]
	v_mfma_f32_16x16x32_bf16 v[30:33], v[130:133], v[212:215], v[30:33]
	v_mfma_f32_16x16x32_bf16 v[26:29], v[138:141], v[212:215], v[26:29]
	v_mfma_f32_16x16x32_bf16 v[14:17], v[130:133], v[220:223], v[14:17]
	v_mfma_f32_16x16x32_bf16 v[10:13], v[138:141], v[220:223], v[10:13]
	v_mfma_f32_16x16x32_bf16 v[62:65], v[134:137], v[182:185], v[62:65]
	v_mfma_f32_16x16x32_bf16 v[58:61], v[142:145], v[182:185], v[58:61]
	v_mfma_f32_16x16x32_bf16 v[46:49], v[134:137], v[194:197], v[46:49]
	v_mfma_f32_16x16x32_bf16 v[42:45], v[142:145], v[194:197], v[42:45]
	v_mfma_f32_16x16x32_bf16 v[30:33], v[134:137], v[216:219], v[30:33]
	v_mfma_f32_16x16x32_bf16 v[26:29], v[142:145], v[216:219], v[26:29]
	v_mfma_f32_16x16x32_bf16 v[14:17], v[134:137], v[224:227], v[14:17]
	v_mfma_f32_16x16x32_bf16 v[10:13], v[142:145], v[224:227], v[10:13]
	v_mfma_f32_16x16x32_bf16 v[54:57], v[146:149], v[174:177], v[54:57]
	v_mfma_f32_16x16x32_bf16 v[50:53], v[154:157], v[174:177], v[50:53]
	v_mfma_f32_16x16x32_bf16 v[38:41], v[146:149], v[190:193], v[38:41]
	v_mfma_f32_16x16x32_bf16 v[34:37], v[154:157], v[190:193], v[34:37]
	v_mfma_f32_16x16x32_bf16 v[22:25], v[146:149], v[212:215], v[22:25]
	v_mfma_f32_16x16x32_bf16 v[18:21], v[154:157], v[212:215], v[18:21]
	v_mfma_f32_16x16x32_bf16 v[6:9], v[146:149], v[220:223], v[6:9]
	v_mfma_f32_16x16x32_bf16 v[2:5], v[154:157], v[220:223], v[2:5]
	v_mfma_f32_16x16x32_bf16 v[54:57], v[150:153], v[182:185], v[54:57]
	v_mfma_f32_16x16x32_bf16 v[50:53], v[158:161], v[182:185], v[50:53]
	v_mfma_f32_16x16x32_bf16 v[38:41], v[150:153], v[194:197], v[38:41]
	v_mfma_f32_16x16x32_bf16 v[34:37], v[158:161], v[194:197], v[34:37]
	v_mfma_f32_16x16x32_bf16 v[22:25], v[150:153], v[216:219], v[22:25]
	v_mfma_f32_16x16x32_bf16 v[18:21], v[158:161], v[216:219], v[18:21]
	v_mfma_f32_16x16x32_bf16 v[6:9], v[150:153], v[224:227], v[6:9]
	v_mfma_f32_16x16x32_bf16 v[2:5], v[158:161], v[224:227], v[2:5]
	s_barrier
	s_add_i32 s87, s87, 2
	s_add_u32 s85, s85, 0x100
	s_addc_u32 s86, s86, 0
	s_add_u32 s78, s78, 0x100
	s_addc_u32 s79, s79, 0
	s_cmp_gt_u32 s87, 13
	s_cbranch_scc0 .LBB0_218
	s_and_b64 vcc, exec, s[50:51]
	s_cbranch_vccz .LBB0_221
	s_barrier

; #define PG8_STAGE(bufoff, gbase, voff) do { _Pragma("unroll") for (int _i = 0; _i < 2; ++_i) \
;         __builtin_amdgcn_global_load_lds((const unsigned*)((const char*)(gbase) + (voff)[_i]), (LAS unsigned*)(lds + (bufoff) + ldsw + _i * 8192), 16, 0, 0); } while (0)
; #define PG8_LDA(dst, b, h) do { _Pragma("unroll") for (int m = 0; m < 4; ++m) _Pragma("unroll") for (int k = 0; k < 2; ++k) dst[m][k] = *(const LAS bf16x8*)(lds + PG8_SA(b, h) + aoff + m * 2048 + k * 1024); } while (0)
; #define PG8_LDB(dst, b, h) do { _Pragma("unroll") for (int n = 0; n < 2; ++n) _Pragma("unroll") for (int k = 0; k < 2; ++k) dst[n][k] = *(const LAS bf16x8*)(lds + PG8_SB(b, h) + boff + n * 2048 + k * 1024); } while (0)
; #define PG8_MMA(ai, bj, At, Bt) do { __builtin_amdgcn_s_setprio(1); _Pragma("unroll") for (int m = 0; m < 4; ++m) _Pragma("unroll") for (int n = 0; n < 2; ++n) _Pragma("unroll") for (int k = 0; k < 2; ++k) \
;         acc[ai][bj][m][n] = __builtin_amdgcn_mfma_f32_16x16x32_bf16(Bt[n][k], At[m][k], acc[ai][bj][m][n], 0, 0, 0); __builtin_amdgcn_s_setprio(0); } while (0)
; #define PG8_WAIT_V(n) asm volatile("s_waitcnt vmcnt(" #n ")" ::: "memory")
; #define PG8_WAIT_L(n) asm volatile("s_waitcnt lgkmcnt(" #n ")" ::: "memory")
; #define PG8_BAR __builtin_amdgcn_s_barrier()
; #define PG8_SCHED __builtin_amdgcn_sched_barrier(0)
; template <class Epi, class Sched>
; DI void gemm_phase(LAS unsigned char* lds, const int K, const Sched& S, const Epi& E) {
;     ...
;             const char* a1 = cA + (size_t)(t + 1) * kstep;
;             const char* a2 = last ? nA : cA + (size_t)(t + 2) * kstep; const char* b2 = last ? nB : cB + (size_t)(t + 2) * kstep;
;             const char* a3 = a2 + kstep; const char* b3 = b2 + kstep;
;             PG8_LDB(B0, 0, 0); PG8_LDB(B1, 0, 1); PG8_SCHED; PG8_LDA(At, 0, 0); PG8_STAGE(PG8_SA(1, 1), a1 + hstep, voffA);
;             PG8_WAIT_V(8); PG8_WAIT_L(0); PG8_BAR; PG8_MMA(0, 0, At, B0); PG8_MMA(0, 1, At, B1); PG8_BAR; PG8_SCHED;
;             PG8_LDA(At, 0, 1); PG8_STAGE(PG8_SB(0, 0), b2, voffB); PG8_STAGE(PG8_SB(0, 1), b2 + hstep, voffB); PG8_STAGE(PG8_SA(0, 0), a2, voffA);
;             PG8_WAIT_V(8); PG8_WAIT_L(0); PG8_BAR; PG8_MMA(1, 0, At, B0); PG8_MMA(1, 1, At, B1); PG8_BAR; PG8_SCHED;
.LBB0_338:
	s_add_u32 s58, s56, 0xfffc0080
	s_addc_u32 s59, s57, -1
	s_add_i32 s79, 0, 0x10000
	s_cmp_eq_u32 s78, 12
	s_cselect_b32 s61, s53, s59
	s_cselect_b32 s60, s52, s58
	v_add_u32_e32 v142, s79, v145
	s_cselect_b32 s59, s55, s51
	s_cselect_b32 s58, s54, s49
	s_add_i32 s82, 0, 0x14000
	ds_read_b128 v[148:151], v142
	ds_read_b128 v[152:155], v142 offset:1024
	ds_read_b128 v[156:159], v142 offset:2048
	ds_read_b128 v[160:163], v142 offset:3072
	v_add_u32_e32 v142, s82, v145
	ds_read_b128 v[164:167], v142
	ds_read_b128 v[168:171], v142 offset:1024
	ds_read_b128 v[172:175], v142 offset:2048
	ds_read_b128 v[182:185], v142 offset:3072
	s_add_i32 m0, s67, 0xc000
	ds_read_b128 v[190:193], v146
	ds_read_b128 v[194:197], v146 offset:1024
	ds_read_b128 v[198:201], v146 offset:2048
	ds_read_b128 v[202:205], v146 offset:3072
	ds_read_b128 v[212:215], v146 offset:4096
	ds_read_b128 v[216:219], v146 offset:5120
	ds_read_b128 v[220:223], v146 offset:6144
	ds_read_b128 v[224:227], v146 offset:7168
	global_load_lds_dwordx4 v140, s[56:57]
	s_add_i32 m0, s67, 0xe000
	s_nop 0
	global_load_lds_dwordx4 v138, s[56:57]
	s_waitcnt vmcnt(8)
	s_waitcnt lgkmcnt(0)
	s_barrier
	s_waitcnt lgkmcnt(0)
	v_mfma_f32_16x16x32_bf16 v[126:129], v[148:151], v[190:193], v[126:129]
	v_mfma_f32_16x16x32_bf16 v[122:125], v[156:159], v[190:193], v[122:125]
	v_mfma_f32_16x16x32_bf16 v[110:113], v[148:151], v[198:201], v[110:113]
	v_mfma_f32_16x16x32_bf16 v[106:109], v[156:159], v[198:201], v[106:109]
	v_mfma_f32_16x16x32_bf16 v[94:97], v[148:151], v[212:215], v[94:97]
	v_mfma_f32_16x16x32_bf16 v[90:93], v[156:159], v[212:215], v[90:93]
	v_mfma_f32_16x16x32_bf16 v[78:81], v[148:151], v[220:223], v[78:81]
	v_mfma_f32_16x16x32_bf16 v[74:77], v[156:159], v[220:223], v[74:77]
	v_mfma_f32_16x16x32_bf16 v[126:129], v[152:155], v[194:197], v[126:129]
	v_mfma_f32_16x16x32_bf16 v[122:125], v[160:163], v[194:197], v[122:125]
	v_mfma_f32_16x16x32_bf16 v[110:113], v[152:155], v[202:205], v[110:113]
	v_mfma_f32_16x16x32_bf16 v[106:109], v[160:163], v[202:205], v[106:109]
	v_mfma_f32_16x16x32_bf16 v[94:97], v[152:155], v[216:219], v[94:97]
	v_mfma_f32_16x16x32_bf16 v[90:93], v[160:163], v[216:219], v[90:93]
	v_mfma_f32_16x16x32_bf16 v[78:81], v[152:155], v[224:227], v[78:81]
	v_mfma_f32_16x16x32_bf16 v[74:77], v[160:163], v[224:227], v[74:77]
	v_mfma_f32_16x16x32_bf16 v[118:121], v[164:167], v[190:193], v[118:121]
	v_mfma_f32_16x16x32_bf16 v[114:117], v[172:175], v[190:193], v[114:117]
	v_mfma_f32_16x16x32_bf16 v[102:105], v[164:167], v[198:201], v[102:105]
	v_mfma_f32_16x16x32_bf16 v[98:101], v[172:175], v[198:201], v[98:101]
	v_mfma_f32_16x16x32_bf16 v[86:89], v[164:167], v[212:215], v[86:89]
	v_mfma_f32_16x16x32_bf16 v[82:85], v[172:175], v[212:215], v[82:85]
	v_mfma_f32_16x16x32_bf16 v[70:73], v[164:167], v[220:223], v[70:73]
	v_mfma_f32_16x16x32_bf16 v[66:69], v[172:175], v[220:223], v[66:69]
	v_mfma_f32_16x16x32_bf16 v[118:121], v[168:171], v[194:197], v[118:121]
	v_mfma_f32_16x16x32_bf16 v[114:117], v[182:185], v[194:197], v[114:117]
	v_mfma_f32_16x16x32_bf16 v[102:105], v[168:171], v[202:205], v[102:105]
	v_mfma_f32_16x16x32_bf16 v[98:101], v[182:185], v[202:205], v[98:101]
	v_mfma_f32_16x16x32_bf16 v[86:89], v[168:171], v[216:219], v[86:89]
	v_mfma_f32_16x16x32_bf16 v[82:85], v[182:185], v[216:219], v[82:85]
	v_mfma_f32_16x16x32_bf16 v[70:73], v[168:171], v[224:227], v[70:73]
	v_mfma_f32_16x16x32_bf16 v[66:69], v[182:185], v[224:227], v[66:69]
	s_barrier
	s_add_i32 s79, s79, s66
	s_mov_b32 m0, s79
	ds_read_b128 v[190:193], v146 offset:16384
	ds_read_b128 v[194:197], v146 offset:17408
	ds_read_b128 v[198:201], v146 offset:18432
	ds_read_b128 v[202:205], v146 offset:19456
	ds_read_b128 v[212:215], v146 offset:20480
	ds_read_b128 v[216:219], v146 offset:21504
	ds_read_b128 v[220:223], v146 offset:22528
	ds_read_b128 v[224:227], v146 offset:23552
	global_load_lds_dwordx4 v134, s[58:59]
	s_add_i32 m0, s79, 0x2000
	s_add_u32 s80, s58, 0x40000
	s_addc_u32 s81, s59, 0
	s_add_i32 s79, s82, s66
	global_load_lds_dwordx4 v130, s[58:59]
	s_mov_b32 m0, s79
	s_nop 0
	global_load_lds_dwordx4 v134, s[80:81]
	s_add_i32 m0, s79, 0x2000
	s_nop 0
	global_load_lds_dwordx4 v130, s[80:81]
	s_add_u32 s98, s60, s90
	s_addc_u32 s99, s61, s91
	s_waitcnt vmcnt(6)
	s_waitcnt lgkmcnt(0)
	s_barrier
	s_waitcnt lgkmcnt(0)
	v_mfma_f32_16x16x32_bf16 v[62:65], v[148:151], v[190:193], v[62:65]
	v_mfma_f32_16x16x32_bf16 v[58:61], v[156:159], v[190:193], v[58:61]
	v_mfma_f32_16x16x32_bf16 v[46:49], v[148:151], v[198:201], v[46:49]
	v_mfma_f32_16x16x32_bf16 v[42:45], v[156:159], v[198:201], v[42:45]
	v_mfma_f32_16x16x32_bf16 v[30:33], v[148:151], v[212:215], v[30:33]
	v_mfma_f32_16x16x32_bf16 v[26:29], v[156:159], v[212:215], v[26:29]
	v_mfma_f32_16x16x32_bf16 v[14:17], v[148:151], v[220:223], v[14:17]
	v_mfma_f32_16x16x32_bf16 v[10:13], v[156:159], v[220:223], v[10:13]
	v_mfma_f32_16x16x32_bf16 v[62:65], v[152:155], v[194:197], v[62:65]
	v_mfma_f32_16x16x32_bf16 v[58:61], v[160:163], v[194:197], v[58:61]
	v_mfma_f32_16x16x32_bf16 v[46:49], v[152:155], v[202:205], v[46:49]
	v_mfma_f32_16x16x32_bf16 v[42:45], v[160:163], v[202:205], v[42:45]
	v_mfma_f32_16x16x32_bf16 v[30:33], v[152:155], v[216:219], v[30:33]
	v_mfma_f32_16x16x32_bf16 v[26:29], v[160:163], v[216:219], v[26:29]
	v_mfma_f32_16x16x32_bf16 v[14:17], v[152:155], v[224:227], v[14:17]
	v_mfma_f32_16x16x32_bf16 v[10:13], v[160:163], v[224:227], v[10:13]
	v_mfma_f32_16x16x32_bf16 v[54:57], v[164:167], v[190:193], v[54:57]
	v_mfma_f32_16x16x32_bf16 v[50:53], v[172:175], v[190:193], v[50:53]
	v_mfma_f32_16x16x32_bf16 v[38:41], v[164:167], v[198:201], v[38:41]
	v_mfma_f32_16x16x32_bf16 v[34:37], v[172:175], v[198:201], v[34:37]
	v_mfma_f32_16x16x32_bf16 v[22:25], v[164:167], v[212:215], v[22:25]
	v_mfma_f32_16x16x32_bf16 v[18:21], v[172:175], v[212:215], v[18:21]
	v_mfma_f32_16x16x32_bf16 v[6:9], v[164:167], v[220:223], v[6:9]
	v_mfma_f32_16x16x32_bf16 v[2:5], v[172:175], v[220:223], v[2:5]
	v_mfma_f32_16x16x32_bf16 v[54:57], v[168:171], v[194:197], v[54:57]
	v_mfma_f32_16x16x32_bf16 v[50:53], v[182:185], v[194:197], v[50:53]
	v_mfma_f32_16x16x32_bf16 v[38:41], v[168:171], v[202:205], v[38:41]
	v_mfma_f32_16x16x32_bf16 v[34:37], v[182:185], v[202:205], v[34:37]
	v_mfma_f32_16x16x32_bf16 v[22:25], v[168:171], v[216:219], v[22:25]
	v_mfma_f32_16x16x32_bf16 v[18:21], v[182:185], v[216:219], v[18:21]
	v_mfma_f32_16x16x32_bf16 v[6:9], v[168:171], v[224:227], v[6:9]
	v_mfma_f32_16x16x32_bf16 v[2:5], v[182:185], v[224:227], v[2:5]
	s_barrier
; #define PG8_STAGE(bufoff, gbase, voff) do { _Pragma("unroll") for (int _i = 0; _i < 2; ++_i) \
;         __builtin_amdgcn_global_load_lds((const unsigned*)((const char*)(gbase) + (voff)[_i]), (LAS unsigned*)(lds + (bufoff) + ldsw + _i * 8192), 16, 0, 0); } while (0)
; #define PG8_LDA(dst, b, h) do { _Pragma("unroll") for (int m = 0; m < 4; ++m) _Pragma("unroll") for (int k = 0; k < 2; ++k) dst[m][k] = *(const LAS bf16x8*)(lds + PG8_SA(b, h) + aoff + m * 2048 + k * 1024); } while (0)
; #define PG8_LDB(dst, b, h) do { _Pragma("unroll") for (int n = 0; n < 2; ++n) _Pragma("unroll") for (int k = 0; k < 2; ++k) dst[n][k] = *(const LAS bf16x8*)(lds + PG8_SB(b, h) + boff + n * 2048 + k * 1024); } while (0)
; #define PG8_MMA(ai, bj, At, Bt) do { __builtin_amdgcn_s_setprio(1); _Pragma("unroll") for (int m = 0; m < 4; ++m) _Pragma("unroll") for (int n = 0; n < 2; ++n) _Pragma("unroll") for (int k = 0; k < 2; ++k) \
;         acc[ai][bj][m][n] = __builtin_amdgcn_mfma_f32_16x16x32_bf16(Bt[n][k], At[m][k], acc[ai][bj][m][n], 0, 0, 0); __builtin_amdgcn_s_setprio(0); } while (0)
; #define PG8_WAIT_V(n) asm volatile("s_waitcnt vmcnt(" #n ")" ::: "memory")
; #define PG8_WAIT_L(n) asm volatile("s_waitcnt lgkmcnt(" #n ")" ::: "memory")
; #define PG8_BAR __builtin_amdgcn_s_barrier()
; #define PG8_SCHED __builtin_amdgcn_sched_barrier(0)
; template <class Epi, class Sched>
; DI void gemm_phase(LAS unsigned char* lds, const int K, const Sched& S, const Epi& E) {
;     ...
;             PG8_LDB(B0, 1, 0); PG8_LDB(B1, 1, 1); PG8_SCHED; PG8_LDA(At, 1, 0); PG8_STAGE(PG8_SA(0, 1), a2 + hstep, voffA);
;             PG8_WAIT_V(8); PG8_WAIT_L(0); PG8_BAR; PG8_MMA(0, 0, At, B0); PG8_MMA(0, 1, At, B1); PG8_BAR; PG8_SCHED;
;             PG8_LDA(At, 1, 1); PG8_STAGE(PG8_SB(1, 0), b3, voffB); PG8_STAGE(PG8_SB(1, 1), b3 + hstep, voffB); PG8_STAGE(PG8_SA(1, 0), a3, voffA);
;             PG8_WAIT_V(8); PG8_WAIT_L(0); PG8_BAR; PG8_MMA(1, 0, At, B0); PG8_MMA(1, 1, At, B1); PG8_BAR; PG8_SCHED;
;         }
;         if (wr == 0) PG8_BAR;
	s_add_i32 s79, 0, 0x18000
	v_add_u32_e32 v147, s79, v145
	s_add_i32 s80, 0, 0x1c000
	ds_read_b128 v[148:151], v147
	ds_read_b128 v[152:155], v147 offset:1024
	ds_read_b128 v[156:159], v147 offset:2048
	ds_read_b128 v[160:163], v147 offset:3072
	v_add_u32_e32 v147, s80, v145
	ds_read_b128 v[164:167], v147
	ds_read_b128 v[168:171], v147 offset:1024
	ds_read_b128 v[172:175], v147 offset:2048
	ds_read_b128 v[182:185], v147 offset:3072
	s_mov_b32 m0, s67
	ds_read_b128 v[190:193], v146 offset:32768
	ds_read_b128 v[194:197], v146 offset:33792
	ds_read_b128 v[198:201], v146 offset:34816
	ds_read_b128 v[202:205], v146 offset:35840
	ds_read_b128 v[212:215], v146 offset:36864
	ds_read_b128 v[216:219], v146 offset:37888
	ds_read_b128 v[220:223], v146 offset:38912
	ds_read_b128 v[224:227], v146 offset:39936
	global_load_lds_dwordx4 v136, s[60:61]
	s_mov_b32 m0, s68
	s_nop 0
	global_load_lds_dwordx4 v132, s[60:61]
	s_add_u32 s60, s60, 0x40000
	s_addc_u32 s61, s61, 0
	s_mov_b32 m0, s69
	s_nop 0
	global_load_lds_dwordx4 v136, s[60:61]
	s_mov_b32 m0, s70
	s_nop 0
	global_load_lds_dwordx4 v132, s[60:61]
	s_waitcnt vmcnt(8)
	s_waitcnt lgkmcnt(0)
	s_barrier
	s_waitcnt lgkmcnt(0)
	v_mfma_f32_16x16x32_bf16 v[126:129], v[148:151], v[190:193], v[126:129]
	v_mfma_f32_16x16x32_bf16 v[122:125], v[156:159], v[190:193], v[122:125]
	v_mfma_f32_16x16x32_bf16 v[110:113], v[148:151], v[198:201], v[110:113]
	v_mfma_f32_16x16x32_bf16 v[106:109], v[156:159], v[198:201], v[106:109]
	v_mfma_f32_16x16x32_bf16 v[94:97], v[148:151], v[212:215], v[94:97]
	v_mfma_f32_16x16x32_bf16 v[90:93], v[156:159], v[212:215], v[90:93]
	v_mfma_f32_16x16x32_bf16 v[78:81], v[148:151], v[220:223], v[78:81]
	v_mfma_f32_16x16x32_bf16 v[74:77], v[156:159], v[220:223], v[74:77]
	v_mfma_f32_16x16x32_bf16 v[126:129], v[152:155], v[194:197], v[126:129]
	v_mfma_f32_16x16x32_bf16 v[122:125], v[160:163], v[194:197], v[122:125]
	v_mfma_f32_16x16x32_bf16 v[110:113], v[152:155], v[202:205], v[110:113]
	v_mfma_f32_16x16x32_bf16 v[106:109], v[160:163], v[202:205], v[106:109]
	v_mfma_f32_16x16x32_bf16 v[94:97], v[152:155], v[216:219], v[94:97]
	v_mfma_f32_16x16x32_bf16 v[90:93], v[160:163], v[216:219], v[90:93]
	v_mfma_f32_16x16x32_bf16 v[78:81], v[152:155], v[224:227], v[78:81]
	v_mfma_f32_16x16x32_bf16 v[74:77], v[160:163], v[224:227], v[74:77]
	v_mfma_f32_16x16x32_bf16 v[118:121], v[164:167], v[190:193], v[118:121]
	v_mfma_f32_16x16x32_bf16 v[114:117], v[172:175], v[190:193], v[114:117]
	v_mfma_f32_16x16x32_bf16 v[102:105], v[164:167], v[198:201], v[102:105]
	v_mfma_f32_16x16x32_bf16 v[98:101], v[172:175], v[198:201], v[98:101]
	v_mfma_f32_16x16x32_bf16 v[86:89], v[164:167], v[212:215], v[86:89]
	v_mfma_f32_16x16x32_bf16 v[82:85], v[172:175], v[212:215], v[82:85]
	v_mfma_f32_16x16x32_bf16 v[70:73], v[164:167], v[220:223], v[70:73]
	v_mfma_f32_16x16x32_bf16 v[66:69], v[172:175], v[220:223], v[66:69]
	v_mfma_f32_16x16x32_bf16 v[118:121], v[168:171], v[194:197], v[118:121]
	v_mfma_f32_16x16x32_bf16 v[114:117], v[182:185], v[194:197], v[114:117]
	v_mfma_f32_16x16x32_bf16 v[102:105], v[168:171], v[202:205], v[102:105]
	v_mfma_f32_16x16x32_bf16 v[98:101], v[182:185], v[202:205], v[98:101]
	v_mfma_f32_16x16x32_bf16 v[86:89], v[168:171], v[216:219], v[86:89]
	v_mfma_f32_16x16x32_bf16 v[82:85], v[182:185], v[216:219], v[82:85]
	v_mfma_f32_16x16x32_bf16 v[70:73], v[168:171], v[224:227], v[70:73]
	v_mfma_f32_16x16x32_bf16 v[66:69], v[182:185], v[224:227], v[66:69]
	s_barrier
	s_add_i32 s60, s79, s66
	s_add_u32 s58, s58, 0x80
	s_addc_u32 s59, s59, 0
	s_mov_b32 m0, s60
	ds_read_b128 v[190:193], v146 offset:49152
	ds_read_b128 v[194:197], v146 offset:50176
	ds_read_b128 v[198:201], v146 offset:51200
	ds_read_b128 v[202:205], v146 offset:52224
	ds_read_b128 v[212:215], v146 offset:53248
	ds_read_b128 v[216:219], v146 offset:54272
	ds_read_b128 v[220:223], v146 offset:55296
	ds_read_b128 v[224:227], v146 offset:56320
	global_load_lds_dwordx4 v134, s[58:59]
	s_add_i32 m0, s60, 0x2000
	s_add_i32 s60, s80, s66
	global_load_lds_dwordx4 v130, s[58:59]
	s_add_u32 s58, s58, 0x40000
	s_addc_u32 s59, s59, 0
	s_mov_b32 m0, s60
	s_nop 0
	global_load_lds_dwordx4 v134, s[58:59]
	s_add_i32 m0, s60, 0x2000
	s_nop 0
	global_load_lds_dwordx4 v130, s[58:59]
	s_mov_b32 m0, s73
	s_nop 0
	global_load_lds_dwordx4 v136, s[98:99]
	s_mov_b32 m0, s74
	s_nop 0
	global_load_lds_dwordx4 v132, s[98:99]
	s_waitcnt vmcnt(8)
	s_waitcnt lgkmcnt(0)
	s_barrier
	s_waitcnt lgkmcnt(0)
	v_mfma_f32_16x16x32_bf16 v[62:65], v[148:151], v[190:193], v[62:65]
	v_mfma_f32_16x16x32_bf16 v[58:61], v[156:159], v[190:193], v[58:61]
	v_mfma_f32_16x16x32_bf16 v[46:49], v[148:151], v[198:201], v[46:49]
	v_mfma_f32_16x16x32_bf16 v[42:45], v[156:159], v[198:201], v[42:45]
	v_mfma_f32_16x16x32_bf16 v[30:33], v[148:151], v[212:215], v[30:33]
	v_mfma_f32_16x16x32_bf16 v[26:29], v[156:159], v[212:215], v[26:29]
	v_mfma_f32_16x16x32_bf16 v[14:17], v[148:151], v[220:223], v[14:17]
	v_mfma_f32_16x16x32_bf16 v[10:13], v[156:159], v[220:223], v[10:13]
	v_mfma_f32_16x16x32_bf16 v[62:65], v[152:155], v[194:197], v[62:65]
	v_mfma_f32_16x16x32_bf16 v[58:61], v[160:163], v[194:197], v[58:61]
	v_mfma_f32_16x16x32_bf16 v[46:49], v[152:155], v[202:205], v[46:49]
	v_mfma_f32_16x16x32_bf16 v[42:45], v[160:163], v[202:205], v[42:45]
	v_mfma_f32_16x16x32_bf16 v[30:33], v[152:155], v[216:219], v[30:33]
	v_mfma_f32_16x16x32_bf16 v[26:29], v[160:163], v[216:219], v[26:29]
	v_mfma_f32_16x16x32_bf16 v[14:17], v[152:155], v[224:227], v[14:17]
	v_mfma_f32_16x16x32_bf16 v[10:13], v[160:163], v[224:227], v[10:13]
	v_mfma_f32_16x16x32_bf16 v[54:57], v[164:167], v[190:193], v[54:57]
	v_mfma_f32_16x16x32_bf16 v[50:53], v[172:175], v[190:193], v[50:53]
	v_mfma_f32_16x16x32_bf16 v[38:41], v[164:167], v[198:201], v[38:41]
	v_mfma_f32_16x16x32_bf16 v[34:37], v[172:175], v[198:201], v[34:37]
	v_mfma_f32_16x16x32_bf16 v[22:25], v[164:167], v[212:215], v[22:25]
	v_mfma_f32_16x16x32_bf16 v[18:21], v[172:175], v[212:215], v[18:21]
	v_mfma_f32_16x16x32_bf16 v[6:9], v[164:167], v[220:223], v[6:9]
	v_mfma_f32_16x16x32_bf16 v[2:5], v[172:175], v[220:223], v[2:5]
	v_mfma_f32_16x16x32_bf16 v[54:57], v[168:171], v[194:197], v[54:57]
	v_mfma_f32_16x16x32_bf16 v[50:53], v[182:185], v[194:197], v[50:53]
	v_mfma_f32_16x16x32_bf16 v[38:41], v[168:171], v[202:205], v[38:41]
	v_mfma_f32_16x16x32_bf16 v[34:37], v[182:185], v[202:205], v[34:37]
	v_mfma_f32_16x16x32_bf16 v[22:25], v[168:171], v[216:219], v[22:25]
	v_mfma_f32_16x16x32_bf16 v[18:21], v[182:185], v[216:219], v[18:21]
	v_mfma_f32_16x16x32_bf16 v[6:9], v[168:171], v[224:227], v[6:9]
	v_mfma_f32_16x16x32_bf16 v[2:5], v[182:185], v[224:227], v[2:5]
	s_barrier
	s_add_i32 s78, s78, 2
	s_add_u32 s49, s49, 0x100
	s_addc_u32 s51, s51, 0
	s_add_u32 s56, s56, 0x100
	s_addc_u32 s57, s57, 0
	s_cmp_gt_u32 s78, 13
	s_cbranch_scc0 .LBB0_338
	s_and_b64 vcc, exec, s[44:45]
	s_cbranch_vccz .LBB0_341
	s_barrier

; #define PG8_STAGE(bufoff, gbase, voff) do { _Pragma("unroll") for (int _i = 0; _i < 2; ++_i) \
;         __builtin_amdgcn_global_load_lds((const unsigned*)((const char*)(gbase) + (voff)[_i]), (LAS unsigned*)(lds + (bufoff) + ldsw + _i * 8192), 16, 0, 0); } while (0)
; #define PG8_LDA(dst, b, h) do { _Pragma("unroll") for (int m = 0; m < 4; ++m) _Pragma("unroll") for (int k = 0; k < 2; ++k) dst[m][k] = *(const LAS bf16x8*)(lds + PG8_SA(b, h) + aoff + m * 2048 + k * 1024); } while (0)
; #define PG8_LDB(dst, b, h) do { _Pragma("unroll") for (int n = 0; n < 2; ++n) _Pragma("unroll") for (int k = 0; k < 2; ++k) dst[n][k] = *(const LAS bf16x8*)(lds + PG8_SB(b, h) + boff + n * 2048 + k * 1024); } while (0)
; #define PG8_MMA(ai, bj, At, Bt) do { __builtin_amdgcn_s_setprio(1); _Pragma("unroll") for (int m = 0; m < 4; ++m) _Pragma("unroll") for (int n = 0; n < 2; ++n) _Pragma("unroll") for (int k = 0; k < 2; ++k) \
;         acc[ai][bj][m][n] = __builtin_amdgcn_mfma_f32_16x16x32_bf16(Bt[n][k], At[m][k], acc[ai][bj][m][n], 0, 0, 0); __builtin_amdgcn_s_setprio(0); } while (0)
; #define PG8_WAIT_V(n) asm volatile("s_waitcnt vmcnt(" #n ")" ::: "memory")
; #define PG8_WAIT_L(n) asm volatile("s_waitcnt lgkmcnt(" #n ")" ::: "memory")
; #define PG8_BAR __builtin_amdgcn_s_barrier()
; #define PG8_SCHED __builtin_amdgcn_sched_barrier(0)
; template <class Epi, class Sched>
; DI void gemm_phase(LAS unsigned char* lds, const int K, const Sched& S, const Epi& E) {
;     ...
;             const char* a1 = cA + (size_t)(t + 1) * kstep;
;             const char* a2 = last ? nA : cA + (size_t)(t + 2) * kstep; const char* b2 = last ? nB : cB + (size_t)(t + 2) * kstep;
;             const char* a3 = a2 + kstep; const char* b3 = b2 + kstep;
;             PG8_LDB(B0, 0, 0); PG8_LDB(B1, 0, 1); PG8_SCHED; PG8_LDA(At, 0, 0); PG8_STAGE(PG8_SA(1, 1), a1 + hstep, voffA);
;             PG8_WAIT_V(8); PG8_WAIT_L(0); PG8_BAR; PG8_MMA(0, 0, At, B0); PG8_MMA(0, 1, At, B1); PG8_BAR; PG8_SCHED;
;             PG8_LDA(At, 0, 1); PG8_STAGE(PG8_SB(0, 0), b2, voffB); PG8_STAGE(PG8_SB(0, 1), b2 + hstep, voffB); PG8_STAGE(PG8_SA(0, 0), a2, voffA);
;             PG8_WAIT_V(8); PG8_WAIT_L(0); PG8_BAR; PG8_MMA(1, 0, At, B0); PG8_MMA(1, 1, At, B1); PG8_BAR; PG8_SCHED;
.LBB0_465:
	s_add_u32 s70, s68, 0xfffc0080
	s_addc_u32 s71, s69, -1
	s_add_i32 vcc_lo, 0, 0x10000
	s_cmp_eq_u32 s79, 12
	s_cselect_b32 s73, s65, s71
	s_cselect_b32 s72, s67, s70
	s_cselect_b32 s71, s74, s78
	s_cselect_b32 s70, s76, s77
	s_add_i32 s42, 0, 0x14000
	v_add_u32_e32 v142, vcc_lo, v203
	v_add_u32_e32 v158, s42, v203
	ds_read_b128 v[130:133], v142
	ds_read_b128 v[134:137], v142 offset:1024
	ds_read_b128 v[138:141], v142 offset:2048
	ds_read_b128 v[142:145], v142 offset:3072
	ds_read_b128 v[146:149], v158
	ds_read_b128 v[150:153], v158 offset:1024
	ds_read_b128 v[154:157], v158 offset:2048
	ds_read_b128 v[158:161], v158 offset:3072
	s_add_i32 m0, s86, 0xc000
	ds_read_b128 v[174:177], v204
	ds_read_b128 v[182:185], v204 offset:1024
	ds_read_b128 v[190:193], v204 offset:2048
	ds_read_b128 v[194:197], v204 offset:3072
	ds_read_b128 v[198:201], v204 offset:4096
	ds_read_b128 v[212:215], v204 offset:5120
	ds_read_b128 v[216:219], v204 offset:6144
	ds_read_b128 v[220:223], v204 offset:7168
	global_load_lds_dwordx4 v172, s[68:69]
	s_add_i32 m0, s86, 0xe000
	s_nop 0
	global_load_lds_dwordx4 v170, s[68:69]
	s_waitcnt vmcnt(8)
	s_waitcnt lgkmcnt(0)
	s_barrier
	s_waitcnt lgkmcnt(0)
	v_mfma_f32_16x16x32_bf16 v[126:129], v[130:133], v[174:177], v[126:129]
	v_mfma_f32_16x16x32_bf16 v[122:125], v[138:141], v[174:177], v[122:125]
	v_mfma_f32_16x16x32_bf16 v[110:113], v[130:133], v[190:193], v[110:113]
	v_mfma_f32_16x16x32_bf16 v[106:109], v[138:141], v[190:193], v[106:109]
	v_mfma_f32_16x16x32_bf16 v[94:97], v[130:133], v[198:201], v[94:97]
	v_mfma_f32_16x16x32_bf16 v[90:93], v[138:141], v[198:201], v[90:93]
	v_mfma_f32_16x16x32_bf16 v[78:81], v[130:133], v[216:219], v[78:81]
	v_mfma_f32_16x16x32_bf16 v[74:77], v[138:141], v[216:219], v[74:77]
	v_mfma_f32_16x16x32_bf16 v[126:129], v[134:137], v[182:185], v[126:129]
	v_mfma_f32_16x16x32_bf16 v[122:125], v[142:145], v[182:185], v[122:125]
	v_mfma_f32_16x16x32_bf16 v[110:113], v[134:137], v[194:197], v[110:113]
	v_mfma_f32_16x16x32_bf16 v[106:109], v[142:145], v[194:197], v[106:109]
	v_mfma_f32_16x16x32_bf16 v[94:97], v[134:137], v[212:215], v[94:97]
	v_mfma_f32_16x16x32_bf16 v[90:93], v[142:145], v[212:215], v[90:93]
	v_mfma_f32_16x16x32_bf16 v[78:81], v[134:137], v[220:223], v[78:81]
	v_mfma_f32_16x16x32_bf16 v[74:77], v[142:145], v[220:223], v[74:77]
	v_mfma_f32_16x16x32_bf16 v[118:121], v[146:149], v[174:177], v[118:121]
	v_mfma_f32_16x16x32_bf16 v[114:117], v[154:157], v[174:177], v[114:117]
	v_mfma_f32_16x16x32_bf16 v[102:105], v[146:149], v[190:193], v[102:105]
	v_mfma_f32_16x16x32_bf16 v[98:101], v[154:157], v[190:193], v[98:101]
	v_mfma_f32_16x16x32_bf16 v[86:89], v[146:149], v[198:201], v[86:89]
	v_mfma_f32_16x16x32_bf16 v[82:85], v[154:157], v[198:201], v[82:85]
	v_mfma_f32_16x16x32_bf16 v[70:73], v[146:149], v[216:219], v[70:73]
	v_mfma_f32_16x16x32_bf16 v[66:69], v[154:157], v[216:219], v[66:69]
	v_mfma_f32_16x16x32_bf16 v[118:121], v[150:153], v[182:185], v[118:121]
	v_mfma_f32_16x16x32_bf16 v[114:117], v[158:161], v[182:185], v[114:117]
	v_mfma_f32_16x16x32_bf16 v[102:105], v[150:153], v[194:197], v[102:105]
	v_mfma_f32_16x16x32_bf16 v[98:101], v[158:161], v[194:197], v[98:101]
	v_mfma_f32_16x16x32_bf16 v[86:89], v[150:153], v[212:215], v[86:89]
	v_mfma_f32_16x16x32_bf16 v[82:85], v[158:161], v[212:215], v[82:85]
	v_mfma_f32_16x16x32_bf16 v[70:73], v[150:153], v[220:223], v[70:73]
	v_mfma_f32_16x16x32_bf16 v[66:69], v[158:161], v[220:223], v[66:69]
	s_barrier
	s_add_i32 s43, vcc_lo, s85
	s_mov_b32 m0, s43
	ds_read_b128 v[174:177], v204 offset:16384
	ds_read_b128 v[182:185], v204 offset:17408
	ds_read_b128 v[190:193], v204 offset:18432
	ds_read_b128 v[194:197], v204 offset:19456
	ds_read_b128 v[198:201], v204 offset:20480
	ds_read_b128 v[212:215], v204 offset:21504
	ds_read_b128 v[216:219], v204 offset:22528
	ds_read_b128 v[220:223], v204 offset:23552
	global_load_lds_dwordx4 v164, s[70:71]
	s_add_i32 m0, s43, 0x2000
	s_add_u32 vcc_lo, s70, 0x40000
	s_addc_u32 vcc_hi, s71, 0
	s_add_i32 s42, s42, s85
	global_load_lds_dwordx4 v168, s[70:71]
	s_mov_b32 m0, s42
	s_nop 0
	global_load_lds_dwordx4 v164, vcc
	s_add_i32 m0, s42, 0x2000
	s_nop 0
	global_load_lds_dwordx4 v168, vcc
	s_add_u32 s98, s72, s90
	s_addc_u32 s99, s73, s91
	s_waitcnt vmcnt(6)
	s_waitcnt lgkmcnt(0)
	s_barrier
	s_waitcnt lgkmcnt(0)
	v_mfma_f32_16x16x32_bf16 v[62:65], v[130:133], v[174:177], v[62:65]
	v_mfma_f32_16x16x32_bf16 v[58:61], v[138:141], v[174:177], v[58:61]
	v_mfma_f32_16x16x32_bf16 v[46:49], v[130:133], v[190:193], v[46:49]
	v_mfma_f32_16x16x32_bf16 v[42:45], v[138:141], v[190:193], v[42:45]
	v_mfma_f32_16x16x32_bf16 v[30:33], v[130:133], v[198:201], v[30:33]
	v_mfma_f32_16x16x32_bf16 v[26:29], v[138:141], v[198:201], v[26:29]
	v_mfma_f32_16x16x32_bf16 v[14:17], v[130:133], v[216:219], v[14:17]
	v_mfma_f32_16x16x32_bf16 v[10:13], v[138:141], v[216:219], v[10:13]
	v_mfma_f32_16x16x32_bf16 v[62:65], v[134:137], v[182:185], v[62:65]
	v_mfma_f32_16x16x32_bf16 v[58:61], v[142:145], v[182:185], v[58:61]
	v_mfma_f32_16x16x32_bf16 v[46:49], v[134:137], v[194:197], v[46:49]
	v_mfma_f32_16x16x32_bf16 v[42:45], v[142:145], v[194:197], v[42:45]
	v_mfma_f32_16x16x32_bf16 v[30:33], v[134:137], v[212:215], v[30:33]
	v_mfma_f32_16x16x32_bf16 v[26:29], v[142:145], v[212:215], v[26:29]
	v_mfma_f32_16x16x32_bf16 v[14:17], v[134:137], v[220:223], v[14:17]
	v_mfma_f32_16x16x32_bf16 v[10:13], v[142:145], v[220:223], v[10:13]
	v_mfma_f32_16x16x32_bf16 v[54:57], v[146:149], v[174:177], v[54:57]
	v_mfma_f32_16x16x32_bf16 v[50:53], v[154:157], v[174:177], v[50:53]
	v_mfma_f32_16x16x32_bf16 v[38:41], v[146:149], v[190:193], v[38:41]
	v_mfma_f32_16x16x32_bf16 v[34:37], v[154:157], v[190:193], v[34:37]
	v_mfma_f32_16x16x32_bf16 v[22:25], v[146:149], v[198:201], v[22:25]
	v_mfma_f32_16x16x32_bf16 v[18:21], v[154:157], v[198:201], v[18:21]
	v_mfma_f32_16x16x32_bf16 v[6:9], v[146:149], v[216:219], v[6:9]
	v_mfma_f32_16x16x32_bf16 v[2:5], v[154:157], v[216:219], v[2:5]
	v_mfma_f32_16x16x32_bf16 v[54:57], v[150:153], v[182:185], v[54:57]
	v_mfma_f32_16x16x32_bf16 v[50:53], v[158:161], v[182:185], v[50:53]
	v_mfma_f32_16x16x32_bf16 v[38:41], v[150:153], v[194:197], v[38:41]
	v_mfma_f32_16x16x32_bf16 v[34:37], v[158:161], v[194:197], v[34:37]
	v_mfma_f32_16x16x32_bf16 v[22:25], v[150:153], v[212:215], v[22:25]
	v_mfma_f32_16x16x32_bf16 v[18:21], v[158:161], v[212:215], v[18:21]
	v_mfma_f32_16x16x32_bf16 v[6:9], v[150:153], v[220:223], v[6:9]
	v_mfma_f32_16x16x32_bf16 v[2:5], v[158:161], v[220:223], v[2:5]
	s_barrier
; #define PG8_STAGE(bufoff, gbase, voff) do { _Pragma("unroll") for (int _i = 0; _i < 2; ++_i) \
;         __builtin_amdgcn_global_load_lds((const unsigned*)((const char*)(gbase) + (voff)[_i]), (LAS unsigned*)(lds + (bufoff) + ldsw + _i * 8192), 16, 0, 0); } while (0)
; #define PG8_LDA(dst, b, h) do { _Pragma("unroll") for (int m = 0; m < 4; ++m) _Pragma("unroll") for (int k = 0; k < 2; ++k) dst[m][k] = *(const LAS bf16x8*)(lds + PG8_SA(b, h) + aoff + m * 2048 + k * 1024); } while (0)
; #define PG8_LDB(dst, b, h) do { _Pragma("unroll") for (int n = 0; n < 2; ++n) _Pragma("unroll") for (int k = 0; k < 2; ++k) dst[n][k] = *(const LAS bf16x8*)(lds + PG8_SB(b, h) + boff + n * 2048 + k * 1024); } while (0)
; #define PG8_MMA(ai, bj, At, Bt) do { __builtin_amdgcn_s_setprio(1); _Pragma("unroll") for (int m = 0; m < 4; ++m) _Pragma("unroll") for (int n = 0; n < 2; ++n) _Pragma("unroll") for (int k = 0; k < 2; ++k) \
;         acc[ai][bj][m][n] = __builtin_amdgcn_mfma_f32_16x16x32_bf16(Bt[n][k], At[m][k], acc[ai][bj][m][n], 0, 0, 0); __builtin_amdgcn_s_setprio(0); } while (0)
; #define PG8_WAIT_V(n) asm volatile("s_waitcnt vmcnt(" #n ")" ::: "memory")
; #define PG8_WAIT_L(n) asm volatile("s_waitcnt lgkmcnt(" #n ")" ::: "memory")
; #define PG8_BAR __builtin_amdgcn_s_barrier()
; #define PG8_SCHED __builtin_amdgcn_sched_barrier(0)
; template <class Epi, class Sched>
; DI void gemm_phase(LAS unsigned char* lds, const int K, const Sched& S, const Epi& E) {
;     ...
;             PG8_LDB(B0, 1, 0); PG8_LDB(B1, 1, 1); PG8_SCHED; PG8_LDA(At, 1, 0); PG8_STAGE(PG8_SA(0, 1), a2 + hstep, voffA);
;             PG8_WAIT_V(8); PG8_WAIT_L(0); PG8_BAR; PG8_MMA(0, 0, At, B0); PG8_MMA(0, 1, At, B1); PG8_BAR; PG8_SCHED;
;             PG8_LDA(At, 1, 1); PG8_STAGE(PG8_SB(1, 0), b3, voffB); PG8_STAGE(PG8_SB(1, 1), b3 + hstep, voffB); PG8_STAGE(PG8_SA(1, 0), a3, voffA);
;             PG8_WAIT_V(8); PG8_WAIT_L(0); PG8_BAR; PG8_MMA(1, 0, At, B0); PG8_MMA(1, 1, At, B1); PG8_BAR; PG8_SCHED;
;         }
;         if (wr == 0) PG8_BAR;
	s_add_i32 s42, 0, 0x18000
	s_add_i32 s43, 0, 0x1c000
	v_add_u32_e32 v142, s42, v203
	v_add_u32_e32 v158, s43, v203
	ds_read_b128 v[130:133], v142
	ds_read_b128 v[134:137], v142 offset:1024
	ds_read_b128 v[138:141], v142 offset:2048
	ds_read_b128 v[142:145], v142 offset:3072
	ds_read_b128 v[146:149], v158
	ds_read_b128 v[150:153], v158 offset:1024
	ds_read_b128 v[154:157], v158 offset:2048
	ds_read_b128 v[158:161], v158 offset:3072
	s_mov_b32 m0, s86
	ds_read_b128 v[174:177], v204 offset:32768
	ds_read_b128 v[182:185], v204 offset:33792
	ds_read_b128 v[190:193], v204 offset:34816
	ds_read_b128 v[194:197], v204 offset:35840
	ds_read_b128 v[198:201], v204 offset:36864
	ds_read_b128 v[212:215], v204 offset:37888
	ds_read_b128 v[216:219], v204 offset:38912
	ds_read_b128 v[220:223], v204 offset:39936
	global_load_lds_dwordx4 v162, s[72:73]
	s_mov_b32 m0, s87
	s_nop 0
	global_load_lds_dwordx4 v166, s[72:73]
	s_add_u32 s72, s72, 0x40000
	s_addc_u32 s73, s73, 0
	s_mov_b32 m0, s92
	s_nop 0
	global_load_lds_dwordx4 v162, s[72:73]
	s_mov_b32 m0, s94
	s_nop 0
	global_load_lds_dwordx4 v166, s[72:73]
	s_waitcnt vmcnt(8)
	s_waitcnt lgkmcnt(0)
	s_barrier
	s_waitcnt lgkmcnt(0)
	v_mfma_f32_16x16x32_bf16 v[126:129], v[130:133], v[174:177], v[126:129]
	v_mfma_f32_16x16x32_bf16 v[122:125], v[138:141], v[174:177], v[122:125]
	v_mfma_f32_16x16x32_bf16 v[110:113], v[130:133], v[190:193], v[110:113]
	v_mfma_f32_16x16x32_bf16 v[106:109], v[138:141], v[190:193], v[106:109]
	v_mfma_f32_16x16x32_bf16 v[94:97], v[130:133], v[198:201], v[94:97]
	v_mfma_f32_16x16x32_bf16 v[90:93], v[138:141], v[198:201], v[90:93]
	v_mfma_f32_16x16x32_bf16 v[78:81], v[130:133], v[216:219], v[78:81]
	v_mfma_f32_16x16x32_bf16 v[74:77], v[138:141], v[216:219], v[74:77]
	v_mfma_f32_16x16x32_bf16 v[126:129], v[134:137], v[182:185], v[126:129]
	v_mfma_f32_16x16x32_bf16 v[122:125], v[142:145], v[182:185], v[122:125]
	v_mfma_f32_16x16x32_bf16 v[110:113], v[134:137], v[194:197], v[110:113]
	v_mfma_f32_16x16x32_bf16 v[106:109], v[142:145], v[194:197], v[106:109]
	v_mfma_f32_16x16x32_bf16 v[94:97], v[134:137], v[212:215], v[94:97]
	v_mfma_f32_16x16x32_bf16 v[90:93], v[142:145], v[212:215], v[90:93]
	v_mfma_f32_16x16x32_bf16 v[78:81], v[134:137], v[220:223], v[78:81]
	v_mfma_f32_16x16x32_bf16 v[74:77], v[142:145], v[220:223], v[74:77]
	v_mfma_f32_16x16x32_bf16 v[118:121], v[146:149], v[174:177], v[118:121]
	v_mfma_f32_16x16x32_bf16 v[114:117], v[154:157], v[174:177], v[114:117]
	v_mfma_f32_16x16x32_bf16 v[102:105], v[146:149], v[190:193], v[102:105]
	v_mfma_f32_16x16x32_bf16 v[98:101], v[154:157], v[190:193], v[98:101]
	v_mfma_f32_16x16x32_bf16 v[86:89], v[146:149], v[198:201], v[86:89]
	v_mfma_f32_16x16x32_bf16 v[82:85], v[154:157], v[198:201], v[82:85]
	v_mfma_f32_16x16x32_bf16 v[70:73], v[146:149], v[216:219], v[70:73]
	v_mfma_f32_16x16x32_bf16 v[66:69], v[154:157], v[216:219], v[66:69]
	v_mfma_f32_16x16x32_bf16 v[118:121], v[150:153], v[182:185], v[118:121]
	v_mfma_f32_16x16x32_bf16 v[114:117], v[158:161], v[182:185], v[114:117]
	v_mfma_f32_16x16x32_bf16 v[102:105], v[150:153], v[194:197], v[102:105]
	v_mfma_f32_16x16x32_bf16 v[98:101], v[158:161], v[194:197], v[98:101]
	v_mfma_f32_16x16x32_bf16 v[86:89], v[150:153], v[212:215], v[86:89]
	v_mfma_f32_16x16x32_bf16 v[82:85], v[158:161], v[212:215], v[82:85]
	v_mfma_f32_16x16x32_bf16 v[70:73], v[150:153], v[220:223], v[70:73]
	v_mfma_f32_16x16x32_bf16 v[66:69], v[158:161], v[220:223], v[66:69]
	s_barrier
	s_add_i32 s42, s42, s85
	s_add_u32 s70, s70, 0x80
	s_addc_u32 s71, s71, 0
	s_mov_b32 m0, s42
	ds_read_b128 v[174:177], v204 offset:49152
	ds_read_b128 v[182:185], v204 offset:50176
	ds_read_b128 v[190:193], v204 offset:51200
	ds_read_b128 v[194:197], v204 offset:52224
	ds_read_b128 v[198:201], v204 offset:53248
	ds_read_b128 v[212:215], v204 offset:54272
	ds_read_b128 v[216:219], v204 offset:55296
	ds_read_b128 v[220:223], v204 offset:56320
	global_load_lds_dwordx4 v164, s[70:71]
	s_add_i32 m0, s42, 0x2000
	s_add_i32 s42, s43, s85
	global_load_lds_dwordx4 v168, s[70:71]
	s_add_u32 s70, s70, 0x40000
	s_addc_u32 s71, s71, 0
	s_mov_b32 m0, s42
	s_nop 0
	global_load_lds_dwordx4 v164, s[70:71]
	s_add_i32 m0, s42, 0x2000
	s_nop 0
	global_load_lds_dwordx4 v168, s[70:71]
	s_mov_b32 m0, s45
	s_nop 0
	global_load_lds_dwordx4 v162, s[98:99]
	s_mov_b32 m0, s50
	s_nop 0
	global_load_lds_dwordx4 v166, s[98:99]
	s_waitcnt vmcnt(8)
	s_waitcnt lgkmcnt(0)
	s_barrier
	s_waitcnt lgkmcnt(0)
	v_mfma_f32_16x16x32_bf16 v[62:65], v[130:133], v[174:177], v[62:65]
	v_mfma_f32_16x16x32_bf16 v[58:61], v[138:141], v[174:177], v[58:61]
	v_mfma_f32_16x16x32_bf16 v[46:49], v[130:133], v[190:193], v[46:49]
	v_mfma_f32_16x16x32_bf16 v[42:45], v[138:141], v[190:193], v[42:45]
	v_mfma_f32_16x16x32_bf16 v[30:33], v[130:133], v[198:201], v[30:33]
	v_mfma_f32_16x16x32_bf16 v[26:29], v[138:141], v[198:201], v[26:29]
	v_mfma_f32_16x16x32_bf16 v[14:17], v[130:133], v[216:219], v[14:17]
	v_mfma_f32_16x16x32_bf16 v[10:13], v[138:141], v[216:219], v[10:13]
	v_mfma_f32_16x16x32_bf16 v[62:65], v[134:137], v[182:185], v[62:65]
	v_mfma_f32_16x16x32_bf16 v[58:61], v[142:145], v[182:185], v[58:61]
	v_mfma_f32_16x16x32_bf16 v[46:49], v[134:137], v[194:197], v[46:49]
	v_mfma_f32_16x16x32_bf16 v[42:45], v[142:145], v[194:197], v[42:45]
	v_mfma_f32_16x16x32_bf16 v[30:33], v[134:137], v[212:215], v[30:33]
	v_mfma_f32_16x16x32_bf16 v[26:29], v[142:145], v[212:215], v[26:29]
	v_mfma_f32_16x16x32_bf16 v[14:17], v[134:137], v[220:223], v[14:17]
	v_mfma_f32_16x16x32_bf16 v[10:13], v[142:145], v[220:223], v[10:13]
	v_mfma_f32_16x16x32_bf16 v[54:57], v[146:149], v[174:177], v[54:57]
	v_mfma_f32_16x16x32_bf16 v[50:53], v[154:157], v[174:177], v[50:53]
	v_mfma_f32_16x16x32_bf16 v[38:41], v[146:149], v[190:193], v[38:41]
	v_mfma_f32_16x16x32_bf16 v[34:37], v[154:157], v[190:193], v[34:37]
	v_mfma_f32_16x16x32_bf16 v[22:25], v[146:149], v[198:201], v[22:25]
	v_mfma_f32_16x16x32_bf16 v[18:21], v[154:157], v[198:201], v[18:21]
	v_mfma_f32_16x16x32_bf16 v[6:9], v[146:149], v[216:219], v[6:9]
	v_mfma_f32_16x16x32_bf16 v[2:5], v[154:157], v[216:219], v[2:5]
	v_mfma_f32_16x16x32_bf16 v[54:57], v[150:153], v[182:185], v[54:57]
	v_mfma_f32_16x16x32_bf16 v[50:53], v[158:161], v[182:185], v[50:53]
	v_mfma_f32_16x16x32_bf16 v[38:41], v[150:153], v[194:197], v[38:41]
	v_mfma_f32_16x16x32_bf16 v[34:37], v[158:161], v[194:197], v[34:37]
	v_mfma_f32_16x16x32_bf16 v[22:25], v[150:153], v[212:215], v[22:25]
	v_mfma_f32_16x16x32_bf16 v[18:21], v[158:161], v[212:215], v[18:21]
	v_mfma_f32_16x16x32_bf16 v[6:9], v[150:153], v[220:223], v[6:9]
	v_mfma_f32_16x16x32_bf16 v[2:5], v[158:161], v[220:223], v[2:5]
	s_barrier
	s_add_i32 s79, s79, 2
	s_add_u32 s77, s77, 0x100
	s_addc_u32 s78, s78, 0
	s_add_u32 s68, s68, 0x100
	s_addc_u32 s69, s69, 0
	s_cmp_gt_u32 s79, 13
	s_cbranch_scc0 .LBB0_465
	s_and_b64 vcc, exec, s[48:49]
	s_cbranch_vccz .LBB0_468
	s_barrier

; #define PG8_STAGE(bufoff, gbase, voff) do { _Pragma("unroll") for (int _i = 0; _i < 2; ++_i) \
;         __builtin_amdgcn_global_load_lds((const unsigned*)((const char*)(gbase) + (voff)[_i]), (LAS unsigned*)(lds + (bufoff) + ldsw + _i * 8192), 16, 0, 0); } while (0)
; #define PG8_LDA(dst, b, h) do { _Pragma("unroll") for (int m = 0; m < 4; ++m) _Pragma("unroll") for (int k = 0; k < 2; ++k) dst[m][k] = *(const LAS bf16x8*)(lds + PG8_SA(b, h) + aoff + m * 2048 + k * 1024); } while (0)
; #define PG8_LDB(dst, b, h) do { _Pragma("unroll") for (int n = 0; n < 2; ++n) _Pragma("unroll") for (int k = 0; k < 2; ++k) dst[n][k] = *(const LAS bf16x8*)(lds + PG8_SB(b, h) + boff + n * 2048 + k * 1024); } while (0)
; #define PG8_MMA(ai, bj, At, Bt) do { __builtin_amdgcn_s_setprio(1); _Pragma("unroll") for (int m = 0; m < 4; ++m) _Pragma("unroll") for (int n = 0; n < 2; ++n) _Pragma("unroll") for (int k = 0; k < 2; ++k) \
;         acc[ai][bj][m][n] = __builtin_amdgcn_mfma_f32_16x16x32_bf16(Bt[n][k], At[m][k], acc[ai][bj][m][n], 0, 0, 0); __builtin_amdgcn_s_setprio(0); } while (0)
; #define PG8_WAIT_V(n) asm volatile("s_waitcnt vmcnt(" #n ")" ::: "memory")
; #define PG8_WAIT_L(n) asm volatile("s_waitcnt lgkmcnt(" #n ")" ::: "memory")
; #define PG8_BAR __builtin_amdgcn_s_barrier()
; #define PG8_SCHED __builtin_amdgcn_sched_barrier(0)
; template <class Epi, class Sched>
; DI void gemm_phase(LAS unsigned char* lds, const int K, const Sched& S, const Epi& E) {
;     ...
;         for (int t = 0; t < nt; t += 2) {
;             const bool last = (t == nt - 2);
;             const char* a1 = cA + (size_t)(t + 1) * kstep;
;             const char* a2 = last ? nA : cA + (size_t)(t + 2) * kstep; const char* b2 = last ? nB : cB + (size_t)(t + 2) * kstep;
;             const char* a3 = a2 + kstep; const char* b3 = b2 + kstep;
;             PG8_LDB(B0, 0, 0); PG8_LDB(B1, 0, 1); PG8_SCHED; PG8_LDA(At, 0, 0); PG8_STAGE(PG8_SA(1, 1), a1 + hstep, voffA);
;             PG8_WAIT_V(8); PG8_WAIT_L(0); PG8_BAR; PG8_MMA(0, 0, At, B0); PG8_MMA(0, 1, At, B1); PG8_BAR; PG8_SCHED;
;             PG8_LDA(At, 0, 1); PG8_STAGE(PG8_SB(0, 0), b2, voffB); PG8_STAGE(PG8_SB(0, 1), b2 + hstep, voffB); PG8_STAGE(PG8_SA(0, 0), a2, voffA);
;             PG8_WAIT_V(8); PG8_WAIT_L(0); PG8_BAR; PG8_MMA(1, 0, At, B0); PG8_MMA(1, 1, At, B1); PG8_BAR; PG8_SCHED;
.LBB0_648:
	s_add_u32 s66, s64, 0xfffc0080
	s_addc_u32 s67, s65, -1
	s_add_i32 s92, 0, 0x10000
	s_cmp_eq_u32 s63, 12
	s_cselect_b32 s69, s59, s67
	s_cselect_b32 s68, s58, s66
	v_add_u32_e32 v1, s92, v154
	s_cselect_b32 s67, s61, s57
	s_cselect_b32 s66, s60, s55
	s_add_i32 s95, 0, 0x14000
	ds_read_b128 v[142:145], v1
	s_waitcnt lgkmcnt(0)
	ds_read_b128 v[146:149], v1 offset:1024
	ds_read_b128 v[156:159], v1 offset:2048
	ds_read_b128 v[160:163], v1 offset:3072
	v_add_u32_e32 v1, s95, v154
	ds_read_b128 v[164:167], v1
	ds_read_b128 v[168:171], v1 offset:1024
	ds_read_b128 v[172:175], v1 offset:2048
	ds_read_b128 v[182:185], v1 offset:3072
	s_add_i32 m0, s76, 0xc000
	ds_read_b128 v[190:193], v155
	ds_read_b128 v[194:197], v155 offset:1024
	ds_read_b128 v[198:201], v155 offset:2048
	ds_read_b128 v[202:205], v155 offset:3072
	ds_read_b128 v[212:215], v155 offset:4096
	ds_read_b128 v[216:219], v155 offset:5120
	ds_read_b128 v[220:223], v155 offset:6144
	ds_read_b128 v[224:227], v155 offset:7168
	global_load_lds_dwordx4 v140, s[64:65]
	s_add_i32 m0, s76, 0xe000
	s_nop 0
	global_load_lds_dwordx4 v138, s[64:65]
	s_waitcnt vmcnt(8)
	s_waitcnt lgkmcnt(0)
	s_barrier
	s_waitcnt lgkmcnt(0)
	v_mfma_f32_16x16x32_bf16 v[126:129], v[142:145], v[190:193], v[126:129]
	v_mfma_f32_16x16x32_bf16 v[122:125], v[156:159], v[190:193], v[122:125]
	v_mfma_f32_16x16x32_bf16 v[110:113], v[142:145], v[198:201], v[110:113]
	v_mfma_f32_16x16x32_bf16 v[106:109], v[156:159], v[198:201], v[106:109]
	v_mfma_f32_16x16x32_bf16 v[94:97], v[142:145], v[212:215], v[94:97]
	v_mfma_f32_16x16x32_bf16 v[90:93], v[156:159], v[212:215], v[90:93]
	v_mfma_f32_16x16x32_bf16 v[78:81], v[142:145], v[220:223], v[78:81]
	v_mfma_f32_16x16x32_bf16 v[74:77], v[156:159], v[220:223], v[74:77]
	v_mfma_f32_16x16x32_bf16 v[126:129], v[146:149], v[194:197], v[126:129]
	v_mfma_f32_16x16x32_bf16 v[122:125], v[160:163], v[194:197], v[122:125]
	v_mfma_f32_16x16x32_bf16 v[110:113], v[146:149], v[202:205], v[110:113]
	v_mfma_f32_16x16x32_bf16 v[106:109], v[160:163], v[202:205], v[106:109]
	v_mfma_f32_16x16x32_bf16 v[94:97], v[146:149], v[216:219], v[94:97]
	v_mfma_f32_16x16x32_bf16 v[90:93], v[160:163], v[216:219], v[90:93]
	v_mfma_f32_16x16x32_bf16 v[78:81], v[146:149], v[224:227], v[78:81]
	v_mfma_f32_16x16x32_bf16 v[74:77], v[160:163], v[224:227], v[74:77]
	v_mfma_f32_16x16x32_bf16 v[118:121], v[164:167], v[190:193], v[118:121]
	v_mfma_f32_16x16x32_bf16 v[114:117], v[172:175], v[190:193], v[114:117]
	v_mfma_f32_16x16x32_bf16 v[102:105], v[164:167], v[198:201], v[102:105]
	v_mfma_f32_16x16x32_bf16 v[98:101], v[172:175], v[198:201], v[98:101]
	v_mfma_f32_16x16x32_bf16 v[86:89], v[164:167], v[212:215], v[86:89]
	v_mfma_f32_16x16x32_bf16 v[82:85], v[172:175], v[212:215], v[82:85]
	v_mfma_f32_16x16x32_bf16 v[70:73], v[164:167], v[220:223], v[70:73]
	v_mfma_f32_16x16x32_bf16 v[66:69], v[172:175], v[220:223], v[66:69]
	v_mfma_f32_16x16x32_bf16 v[118:121], v[168:171], v[194:197], v[118:121]
	v_mfma_f32_16x16x32_bf16 v[114:117], v[182:185], v[194:197], v[114:117]
	v_mfma_f32_16x16x32_bf16 v[102:105], v[168:171], v[202:205], v[102:105]
	v_mfma_f32_16x16x32_bf16 v[98:101], v[182:185], v[202:205], v[98:101]
	v_mfma_f32_16x16x32_bf16 v[86:89], v[168:171], v[216:219], v[86:89]
	v_mfma_f32_16x16x32_bf16 v[82:85], v[182:185], v[216:219], v[82:85]
	v_mfma_f32_16x16x32_bf16 v[70:73], v[168:171], v[224:227], v[70:73]
	v_mfma_f32_16x16x32_bf16 v[66:69], v[182:185], v[224:227], v[66:69]
	s_barrier
	s_add_i32 s92, s92, s75
	s_mov_b32 m0, s92
	ds_read_b128 v[190:193], v155 offset:16384
	ds_read_b128 v[194:197], v155 offset:17408
	ds_read_b128 v[198:201], v155 offset:18432
	ds_read_b128 v[202:205], v155 offset:19456
	ds_read_b128 v[212:215], v155 offset:20480
	ds_read_b128 v[216:219], v155 offset:21504
	ds_read_b128 v[220:223], v155 offset:22528
	ds_read_b128 v[224:227], v155 offset:23552
	global_load_lds_dwordx4 v132, s[66:67]
	s_add_i32 m0, s92, 0x2000
	s_add_u32 vcc_lo, s66, 0x40000
	s_addc_u32 vcc_hi, s67, 0
	s_add_i32 s92, s95, s75
	global_load_lds_dwordx4 v136, s[66:67]
	s_mov_b32 m0, s92
	s_nop 0
	global_load_lds_dwordx4 v132, vcc
	s_add_i32 m0, s92, 0x2000
	s_nop 0
	global_load_lds_dwordx4 v136, vcc
	s_add_u32 s98, s68, s90
	s_addc_u32 s99, s69, s91
	s_waitcnt vmcnt(6)
	s_waitcnt lgkmcnt(0)
	s_barrier
	s_waitcnt lgkmcnt(0)
	v_mfma_f32_16x16x32_bf16 v[62:65], v[142:145], v[190:193], v[62:65]
	v_mfma_f32_16x16x32_bf16 v[58:61], v[156:159], v[190:193], v[58:61]
	v_mfma_f32_16x16x32_bf16 v[46:49], v[142:145], v[198:201], v[46:49]
	v_mfma_f32_16x16x32_bf16 v[42:45], v[156:159], v[198:201], v[42:45]
	v_mfma_f32_16x16x32_bf16 v[30:33], v[142:145], v[212:215], v[30:33]
	v_mfma_f32_16x16x32_bf16 v[26:29], v[156:159], v[212:215], v[26:29]
	v_mfma_f32_16x16x32_bf16 v[14:17], v[142:145], v[220:223], v[14:17]
	v_mfma_f32_16x16x32_bf16 v[10:13], v[156:159], v[220:223], v[10:13]
	v_mfma_f32_16x16x32_bf16 v[62:65], v[146:149], v[194:197], v[62:65]
	v_mfma_f32_16x16x32_bf16 v[58:61], v[160:163], v[194:197], v[58:61]
	v_mfma_f32_16x16x32_bf16 v[46:49], v[146:149], v[202:205], v[46:49]
	v_mfma_f32_16x16x32_bf16 v[42:45], v[160:163], v[202:205], v[42:45]
	v_mfma_f32_16x16x32_bf16 v[30:33], v[146:149], v[216:219], v[30:33]
	v_mfma_f32_16x16x32_bf16 v[26:29], v[160:163], v[216:219], v[26:29]
	v_mfma_f32_16x16x32_bf16 v[14:17], v[146:149], v[224:227], v[14:17]
	v_mfma_f32_16x16x32_bf16 v[10:13], v[160:163], v[224:227], v[10:13]
	v_mfma_f32_16x16x32_bf16 v[54:57], v[164:167], v[190:193], v[54:57]
	v_mfma_f32_16x16x32_bf16 v[50:53], v[172:175], v[190:193], v[50:53]
	v_mfma_f32_16x16x32_bf16 v[38:41], v[164:167], v[198:201], v[38:41]
	v_mfma_f32_16x16x32_bf16 v[34:37], v[172:175], v[198:201], v[34:37]
	v_mfma_f32_16x16x32_bf16 v[22:25], v[164:167], v[212:215], v[22:25]
	v_mfma_f32_16x16x32_bf16 v[18:21], v[172:175], v[212:215], v[18:21]
	v_mfma_f32_16x16x32_bf16 v[6:9], v[164:167], v[220:223], v[6:9]
	v_mfma_f32_16x16x32_bf16 v[2:5], v[172:175], v[220:223], v[2:5]
	v_mfma_f32_16x16x32_bf16 v[54:57], v[168:171], v[194:197], v[54:57]
	v_mfma_f32_16x16x32_bf16 v[50:53], v[182:185], v[194:197], v[50:53]
	v_mfma_f32_16x16x32_bf16 v[38:41], v[168:171], v[202:205], v[38:41]
	v_mfma_f32_16x16x32_bf16 v[34:37], v[182:185], v[202:205], v[34:37]
	v_mfma_f32_16x16x32_bf16 v[22:25], v[168:171], v[216:219], v[22:25]
	v_mfma_f32_16x16x32_bf16 v[18:21], v[182:185], v[216:219], v[18:21]
	v_mfma_f32_16x16x32_bf16 v[6:9], v[168:171], v[224:227], v[6:9]
	v_mfma_f32_16x16x32_bf16 v[2:5], v[182:185], v[224:227], v[2:5]
	s_barrier
; #define PG8_STAGE(bufoff, gbase, voff) do { _Pragma("unroll") for (int _i = 0; _i < 2; ++_i) \
;         __builtin_amdgcn_global_load_lds((const unsigned*)((const char*)(gbase) + (voff)[_i]), (LAS unsigned*)(lds + (bufoff) + ldsw + _i * 8192), 16, 0, 0); } while (0)
; #define PG8_LDA(dst, b, h) do { _Pragma("unroll") for (int m = 0; m < 4; ++m) _Pragma("unroll") for (int k = 0; k < 2; ++k) dst[m][k] = *(const LAS bf16x8*)(lds + PG8_SA(b, h) + aoff + m * 2048 + k * 1024); } while (0)
; #define PG8_LDB(dst, b, h) do { _Pragma("unroll") for (int n = 0; n < 2; ++n) _Pragma("unroll") for (int k = 0; k < 2; ++k) dst[n][k] = *(const LAS bf16x8*)(lds + PG8_SB(b, h) + boff + n * 2048 + k * 1024); } while (0)
; #define PG8_MMA(ai, bj, At, Bt) do { __builtin_amdgcn_s_setprio(1); _Pragma("unroll") for (int m = 0; m < 4; ++m) _Pragma("unroll") for (int n = 0; n < 2; ++n) _Pragma("unroll") for (int k = 0; k < 2; ++k) \
;         acc[ai][bj][m][n] = __builtin_amdgcn_mfma_f32_16x16x32_bf16(Bt[n][k], At[m][k], acc[ai][bj][m][n], 0, 0, 0); __builtin_amdgcn_s_setprio(0); } while (0)
; #define PG8_WAIT_V(n) asm volatile("s_waitcnt vmcnt(" #n ")" ::: "memory")
; #define PG8_WAIT_L(n) asm volatile("s_waitcnt lgkmcnt(" #n ")" ::: "memory")
; #define PG8_BAR __builtin_amdgcn_s_barrier()
; #define PG8_SCHED __builtin_amdgcn_sched_barrier(0)
; template <class Epi, class Sched>
; DI void gemm_phase(LAS unsigned char* lds, const int K, const Sched& S, const Epi& E) {
;     ...
;             PG8_LDB(B0, 1, 0); PG8_LDB(B1, 1, 1); PG8_SCHED; PG8_LDA(At, 1, 0); PG8_STAGE(PG8_SA(0, 1), a2 + hstep, voffA);
;             PG8_WAIT_V(8); PG8_WAIT_L(0); PG8_BAR; PG8_MMA(0, 0, At, B0); PG8_MMA(0, 1, At, B1); PG8_BAR; PG8_SCHED;
;             PG8_LDA(At, 1, 1); PG8_STAGE(PG8_SB(1, 0), b3, voffB); PG8_STAGE(PG8_SB(1, 1), b3 + hstep, voffB); PG8_STAGE(PG8_SA(1, 0), a3, voffA);
;             PG8_WAIT_V(8); PG8_WAIT_L(0); PG8_BAR; PG8_MMA(1, 0, At, B0); PG8_MMA(1, 1, At, B1); PG8_BAR; PG8_SCHED;
;         }
;         if (wr == 0) PG8_BAR;
	s_add_i32 s92, 0, 0x18000
	v_add_u32_e32 v1, s92, v154
	s_add_i32 s95, 0, 0x1c000
	ds_read_b128 v[142:145], v1
	ds_read_b128 v[146:149], v1 offset:1024
	ds_read_b128 v[156:159], v1 offset:2048
	ds_read_b128 v[160:163], v1 offset:3072
	v_add_u32_e32 v1, s95, v154
	ds_read_b128 v[164:167], v1
	ds_read_b128 v[168:171], v1 offset:1024
	ds_read_b128 v[172:175], v1 offset:2048
	ds_read_b128 v[182:185], v1 offset:3072
	s_mov_b32 m0, s76
	ds_read_b128 v[190:193], v155 offset:32768
	ds_read_b128 v[194:197], v155 offset:33792
	ds_read_b128 v[198:201], v155 offset:34816
	ds_read_b128 v[202:205], v155 offset:35840
	ds_read_b128 v[212:215], v155 offset:36864
	ds_read_b128 v[216:219], v155 offset:37888
	ds_read_b128 v[220:223], v155 offset:38912
	ds_read_b128 v[224:227], v155 offset:39936
	global_load_lds_dwordx4 v130, s[68:69]
	s_mov_b32 m0, s77
	s_nop 0
	global_load_lds_dwordx4 v134, s[68:69]
	s_add_u32 s68, s68, 0x40000
	s_addc_u32 s69, s69, 0
	s_mov_b32 m0, s78
	s_nop 0
	global_load_lds_dwordx4 v130, s[68:69]
	s_mov_b32 m0, s79
	s_nop 0
	global_load_lds_dwordx4 v134, s[68:69]
	s_waitcnt vmcnt(8)
	s_waitcnt lgkmcnt(0)
	s_barrier
	s_waitcnt lgkmcnt(0)
	v_mfma_f32_16x16x32_bf16 v[126:129], v[142:145], v[190:193], v[126:129]
	v_mfma_f32_16x16x32_bf16 v[122:125], v[156:159], v[190:193], v[122:125]
	v_mfma_f32_16x16x32_bf16 v[110:113], v[142:145], v[198:201], v[110:113]
	v_mfma_f32_16x16x32_bf16 v[106:109], v[156:159], v[198:201], v[106:109]
	v_mfma_f32_16x16x32_bf16 v[94:97], v[142:145], v[212:215], v[94:97]
	v_mfma_f32_16x16x32_bf16 v[90:93], v[156:159], v[212:215], v[90:93]
	v_mfma_f32_16x16x32_bf16 v[78:81], v[142:145], v[220:223], v[78:81]
	v_mfma_f32_16x16x32_bf16 v[74:77], v[156:159], v[220:223], v[74:77]
	v_mfma_f32_16x16x32_bf16 v[126:129], v[146:149], v[194:197], v[126:129]
	v_mfma_f32_16x16x32_bf16 v[122:125], v[160:163], v[194:197], v[122:125]
	v_mfma_f32_16x16x32_bf16 v[110:113], v[146:149], v[202:205], v[110:113]
	v_mfma_f32_16x16x32_bf16 v[106:109], v[160:163], v[202:205], v[106:109]
	v_mfma_f32_16x16x32_bf16 v[94:97], v[146:149], v[216:219], v[94:97]
	v_mfma_f32_16x16x32_bf16 v[90:93], v[160:163], v[216:219], v[90:93]
	v_mfma_f32_16x16x32_bf16 v[78:81], v[146:149], v[224:227], v[78:81]
	v_mfma_f32_16x16x32_bf16 v[74:77], v[160:163], v[224:227], v[74:77]
	v_mfma_f32_16x16x32_bf16 v[118:121], v[164:167], v[190:193], v[118:121]
	v_mfma_f32_16x16x32_bf16 v[114:117], v[172:175], v[190:193], v[114:117]
	v_mfma_f32_16x16x32_bf16 v[102:105], v[164:167], v[198:201], v[102:105]
	v_mfma_f32_16x16x32_bf16 v[98:101], v[172:175], v[198:201], v[98:101]
	v_mfma_f32_16x16x32_bf16 v[86:89], v[164:167], v[212:215], v[86:89]
	v_mfma_f32_16x16x32_bf16 v[82:85], v[172:175], v[212:215], v[82:85]
	v_mfma_f32_16x16x32_bf16 v[70:73], v[164:167], v[220:223], v[70:73]
	v_mfma_f32_16x16x32_bf16 v[66:69], v[172:175], v[220:223], v[66:69]
	v_mfma_f32_16x16x32_bf16 v[118:121], v[168:171], v[194:197], v[118:121]
	v_mfma_f32_16x16x32_bf16 v[114:117], v[182:185], v[194:197], v[114:117]
	v_mfma_f32_16x16x32_bf16 v[102:105], v[168:171], v[202:205], v[102:105]
	v_mfma_f32_16x16x32_bf16 v[98:101], v[182:185], v[202:205], v[98:101]
	v_mfma_f32_16x16x32_bf16 v[86:89], v[168:171], v[216:219], v[86:89]
	v_mfma_f32_16x16x32_bf16 v[82:85], v[182:185], v[216:219], v[82:85]
	v_mfma_f32_16x16x32_bf16 v[70:73], v[168:171], v[224:227], v[70:73]
	v_mfma_f32_16x16x32_bf16 v[66:69], v[182:185], v[224:227], v[66:69]
	s_barrier
	s_add_i32 s68, s92, s75
	s_add_u32 s66, s66, 0x80
	s_addc_u32 s67, s67, 0
	s_mov_b32 m0, s68
	ds_read_b128 v[190:193], v155 offset:49152
	ds_read_b128 v[194:197], v155 offset:50176
	ds_read_b128 v[198:201], v155 offset:51200
	ds_read_b128 v[202:205], v155 offset:52224
	ds_read_b128 v[212:215], v155 offset:53248
	ds_read_b128 v[216:219], v155 offset:54272
	ds_read_b128 v[220:223], v155 offset:55296
	ds_read_b128 v[224:227], v155 offset:56320
	global_load_lds_dwordx4 v132, s[66:67]
	s_add_i32 m0, s68, 0x2000
	s_add_i32 s68, s95, s75
	global_load_lds_dwordx4 v136, s[66:67]
	s_add_u32 s66, s66, 0x40000
	s_addc_u32 s67, s67, 0
	s_mov_b32 m0, s68
	s_nop 0
	global_load_lds_dwordx4 v132, s[66:67]
	s_add_i32 m0, s68, 0x2000
	s_nop 0
	global_load_lds_dwordx4 v136, s[66:67]
	s_mov_b32 m0, s83
	s_nop 0
	global_load_lds_dwordx4 v130, s[98:99]
	s_mov_b32 m0, s84
	s_nop 0
	global_load_lds_dwordx4 v134, s[98:99]
	s_waitcnt vmcnt(8)
	s_waitcnt lgkmcnt(0)
	s_barrier
	s_waitcnt lgkmcnt(0)
	v_mfma_f32_16x16x32_bf16 v[62:65], v[142:145], v[190:193], v[62:65]
	v_mfma_f32_16x16x32_bf16 v[58:61], v[156:159], v[190:193], v[58:61]
	v_mfma_f32_16x16x32_bf16 v[46:49], v[142:145], v[198:201], v[46:49]
	v_mfma_f32_16x16x32_bf16 v[42:45], v[156:159], v[198:201], v[42:45]
	v_mfma_f32_16x16x32_bf16 v[30:33], v[142:145], v[212:215], v[30:33]
	v_mfma_f32_16x16x32_bf16 v[26:29], v[156:159], v[212:215], v[26:29]
	v_mfma_f32_16x16x32_bf16 v[14:17], v[142:145], v[220:223], v[14:17]
	v_mfma_f32_16x16x32_bf16 v[10:13], v[156:159], v[220:223], v[10:13]
	v_mfma_f32_16x16x32_bf16 v[62:65], v[146:149], v[194:197], v[62:65]
	v_mfma_f32_16x16x32_bf16 v[58:61], v[160:163], v[194:197], v[58:61]
	v_mfma_f32_16x16x32_bf16 v[46:49], v[146:149], v[202:205], v[46:49]
	v_mfma_f32_16x16x32_bf16 v[42:45], v[160:163], v[202:205], v[42:45]
	v_mfma_f32_16x16x32_bf16 v[30:33], v[146:149], v[216:219], v[30:33]
	v_mfma_f32_16x16x32_bf16 v[26:29], v[160:163], v[216:219], v[26:29]
	v_mfma_f32_16x16x32_bf16 v[14:17], v[146:149], v[224:227], v[14:17]
	v_mfma_f32_16x16x32_bf16 v[10:13], v[160:163], v[224:227], v[10:13]
	v_mfma_f32_16x16x32_bf16 v[54:57], v[164:167], v[190:193], v[54:57]
	v_mfma_f32_16x16x32_bf16 v[50:53], v[172:175], v[190:193], v[50:53]
	v_mfma_f32_16x16x32_bf16 v[38:41], v[164:167], v[198:201], v[38:41]
	v_mfma_f32_16x16x32_bf16 v[34:37], v[172:175], v[198:201], v[34:37]
	v_mfma_f32_16x16x32_bf16 v[22:25], v[164:167], v[212:215], v[22:25]
	v_mfma_f32_16x16x32_bf16 v[18:21], v[172:175], v[212:215], v[18:21]
	v_mfma_f32_16x16x32_bf16 v[6:9], v[164:167], v[220:223], v[6:9]
	v_mfma_f32_16x16x32_bf16 v[2:5], v[172:175], v[220:223], v[2:5]
	v_mfma_f32_16x16x32_bf16 v[54:57], v[168:171], v[194:197], v[54:57]
	v_mfma_f32_16x16x32_bf16 v[50:53], v[182:185], v[194:197], v[50:53]
	v_mfma_f32_16x16x32_bf16 v[38:41], v[168:171], v[202:205], v[38:41]
	v_mfma_f32_16x16x32_bf16 v[34:37], v[182:185], v[202:205], v[34:37]
	v_mfma_f32_16x16x32_bf16 v[22:25], v[168:171], v[216:219], v[22:25]
	v_mfma_f32_16x16x32_bf16 v[18:21], v[182:185], v[216:219], v[18:21]
	v_mfma_f32_16x16x32_bf16 v[6:9], v[168:171], v[224:227], v[6:9]
	v_mfma_f32_16x16x32_bf16 v[2:5], v[182:185], v[224:227], v[2:5]
	s_barrier
	s_add_i32 s63, s63, 2
	s_add_u32 s55, s55, 0x100
	s_addc_u32 s57, s57, 0
	s_add_u32 s64, s64, 0x100
	s_addc_u32 s65, s65, 0
	s_cmp_gt_u32 s63, 13
	s_cbranch_scc0 .LBB0_648
	s_and_b64 vcc, exec, s[46:47]
	s_cbranch_vccz .LBB0_651
	s_barrier

; #define PG8_STAGE(bufoff, gbase, voff) do { _Pragma("unroll") for (int _i = 0; _i < 2; ++_i) \
;         __builtin_amdgcn_global_load_lds((const unsigned*)((const char*)(gbase) + (voff)[_i]), (LAS unsigned*)(lds + (bufoff) + ldsw + _i * 8192), 16, 0, 0); } while (0)
; #define PG8_LDA(dst, b, h) do { _Pragma("unroll") for (int m = 0; m < 4; ++m) _Pragma("unroll") for (int k = 0; k < 2; ++k) dst[m][k] = *(const LAS bf16x8*)(lds + PG8_SA(b, h) + aoff + m * 2048 + k * 1024); } while (0)
; #define PG8_LDB(dst, b, h) do { _Pragma("unroll") for (int n = 0; n < 2; ++n) _Pragma("unroll") for (int k = 0; k < 2; ++k) dst[n][k] = *(const LAS bf16x8*)(lds + PG8_SB(b, h) + boff + n * 2048 + k * 1024); } while (0)
; #define PG8_MMA(ai, bj, At, Bt) do { __builtin_amdgcn_s_setprio(1); _Pragma("unroll") for (int m = 0; m < 4; ++m) _Pragma("unroll") for (int n = 0; n < 2; ++n) _Pragma("unroll") for (int k = 0; k < 2; ++k) \
;         acc[ai][bj][m][n] = __builtin_amdgcn_mfma_f32_16x16x32_bf16(Bt[n][k], At[m][k], acc[ai][bj][m][n], 0, 0, 0); __builtin_amdgcn_s_setprio(0); } while (0)
; #define PG8_WAIT_V(n) asm volatile("s_waitcnt vmcnt(" #n ")" ::: "memory")
; #define PG8_WAIT_L(n) asm volatile("s_waitcnt lgkmcnt(" #n ")" ::: "memory")
; #define PG8_BAR __builtin_amdgcn_s_barrier()
; #define PG8_SCHED __builtin_amdgcn_sched_barrier(0)
; template <class Epi, class Sched>
; DI void gemm_phase(LAS unsigned char* lds, const int K, const Sched& S, const Epi& E) {
;     ...
;         for (int t = 0; t < nt; t += 2) {
;             const bool last = (t == nt - 2);
;             const char* a1 = cA + (size_t)(t + 1) * kstep;
;             const char* a2 = last ? nA : cA + (size_t)(t + 2) * kstep; const char* b2 = last ? nB : cB + (size_t)(t + 2) * kstep;
;             const char* a3 = a2 + kstep; const char* b3 = b2 + kstep;
;             PG8_LDB(B0, 0, 0); PG8_LDB(B1, 0, 1); PG8_SCHED; PG8_LDA(At, 0, 0); PG8_STAGE(PG8_SA(1, 1), a1 + hstep, voffA);
;             PG8_WAIT_V(8); PG8_WAIT_L(0); PG8_BAR; PG8_MMA(0, 0, At, B0); PG8_MMA(0, 1, At, B1); PG8_BAR; PG8_SCHED;
;             PG8_LDA(At, 0, 1); PG8_STAGE(PG8_SB(0, 0), b2, voffB); PG8_STAGE(PG8_SB(0, 1), b2 + hstep, voffB); PG8_STAGE(PG8_SA(0, 0), a2, voffA);
;             PG8_WAIT_V(8); PG8_WAIT_L(0); PG8_BAR; PG8_MMA(1, 0, At, B0); PG8_MMA(1, 1, At, B1); PG8_BAR; PG8_SCHED;
.LBB0_784:
	s_add_u32 s48, s44, 0xfffc0080
	s_addc_u32 s49, s45, -1
	s_add_i32 s77, 0, 0x10000
	s_cmp_eq_u32 s76, 12
	s_cselect_b32 s75, s69, s49
	s_cselect_b32 s74, s68, s48
	s_cselect_b32 s73, s71, s67
	s_cselect_b32 s72, s70, s65
	s_add_i32 s48, 0, 0x14000
	v_add_u32_e32 v142, s77, v199
	v_add_u32_e32 v158, s48, v199
	ds_read_b128 v[130:133], v142
	ds_read_b128 v[134:137], v142 offset:1024
	ds_read_b128 v[138:141], v142 offset:2048
	ds_read_b128 v[142:145], v142 offset:3072
	ds_read_b128 v[146:149], v158
	ds_read_b128 v[150:153], v158 offset:1024
	ds_read_b128 v[154:157], v158 offset:2048
	ds_read_b128 v[158:161], v158 offset:3072
	s_add_i32 m0, s80, 0xc000
	ds_read_b128 v[174:177], v200
	ds_read_b128 v[182:185], v200 offset:1024
	ds_read_b128 v[190:193], v200 offset:2048
	ds_read_b128 v[194:197], v200 offset:3072
	ds_read_b128 v[202:205], v200 offset:4096
	ds_read_b128 v[212:215], v200 offset:5120
	ds_read_b128 v[216:219], v200 offset:6144
	ds_read_b128 v[220:223], v200 offset:7168
	global_load_lds_dwordx4 v172, s[44:45]
	s_add_i32 m0, s80, 0xe000
	s_nop 0
	global_load_lds_dwordx4 v170, s[44:45]
	s_waitcnt vmcnt(8)
	s_waitcnt lgkmcnt(0)
	s_barrier
	s_waitcnt lgkmcnt(0)
	v_mfma_f32_16x16x32_bf16 v[126:129], v[130:133], v[174:177], v[126:129]
	v_mfma_f32_16x16x32_bf16 v[122:125], v[138:141], v[174:177], v[122:125]
	v_mfma_f32_16x16x32_bf16 v[118:121], v[130:133], v[190:193], v[118:121]
	v_mfma_f32_16x16x32_bf16 v[114:117], v[138:141], v[190:193], v[114:117]
	v_mfma_f32_16x16x32_bf16 v[110:113], v[130:133], v[202:205], v[110:113]
	v_mfma_f32_16x16x32_bf16 v[106:109], v[138:141], v[202:205], v[106:109]
	v_mfma_f32_16x16x32_bf16 v[102:105], v[130:133], v[216:219], v[102:105]
	v_mfma_f32_16x16x32_bf16 v[98:101], v[138:141], v[216:219], v[98:101]
	v_mfma_f32_16x16x32_bf16 v[126:129], v[134:137], v[182:185], v[126:129]
	v_mfma_f32_16x16x32_bf16 v[122:125], v[142:145], v[182:185], v[122:125]
	v_mfma_f32_16x16x32_bf16 v[118:121], v[134:137], v[194:197], v[118:121]
	v_mfma_f32_16x16x32_bf16 v[114:117], v[142:145], v[194:197], v[114:117]
	v_mfma_f32_16x16x32_bf16 v[110:113], v[134:137], v[212:215], v[110:113]
	v_mfma_f32_16x16x32_bf16 v[106:109], v[142:145], v[212:215], v[106:109]
	v_mfma_f32_16x16x32_bf16 v[102:105], v[134:137], v[220:223], v[102:105]
	v_mfma_f32_16x16x32_bf16 v[98:101], v[142:145], v[220:223], v[98:101]
	v_mfma_f32_16x16x32_bf16 v[94:97], v[146:149], v[174:177], v[94:97]
	v_mfma_f32_16x16x32_bf16 v[90:93], v[154:157], v[174:177], v[90:93]
	v_mfma_f32_16x16x32_bf16 v[86:89], v[146:149], v[190:193], v[86:89]
	v_mfma_f32_16x16x32_bf16 v[82:85], v[154:157], v[190:193], v[82:85]
	v_mfma_f32_16x16x32_bf16 v[78:81], v[146:149], v[202:205], v[78:81]
	v_mfma_f32_16x16x32_bf16 v[74:77], v[154:157], v[202:205], v[74:77]
	v_mfma_f32_16x16x32_bf16 v[70:73], v[146:149], v[216:219], v[70:73]
	v_mfma_f32_16x16x32_bf16 v[66:69], v[154:157], v[216:219], v[66:69]
	v_mfma_f32_16x16x32_bf16 v[94:97], v[150:153], v[182:185], v[94:97]
	v_mfma_f32_16x16x32_bf16 v[90:93], v[158:161], v[182:185], v[90:93]
	v_mfma_f32_16x16x32_bf16 v[86:89], v[150:153], v[194:197], v[86:89]
	v_mfma_f32_16x16x32_bf16 v[82:85], v[158:161], v[194:197], v[82:85]
	v_mfma_f32_16x16x32_bf16 v[78:81], v[150:153], v[212:215], v[78:81]
	v_mfma_f32_16x16x32_bf16 v[74:77], v[158:161], v[212:215], v[74:77]
	v_mfma_f32_16x16x32_bf16 v[70:73], v[150:153], v[220:223], v[70:73]
	v_mfma_f32_16x16x32_bf16 v[66:69], v[158:161], v[220:223], v[66:69]
	s_barrier
	s_add_i32 s49, s77, s79
	s_mov_b32 m0, s49
	ds_read_b128 v[174:177], v200 offset:16384
	ds_read_b128 v[182:185], v200 offset:17408
	ds_read_b128 v[190:193], v200 offset:18432
	ds_read_b128 v[194:197], v200 offset:19456
	ds_read_b128 v[202:205], v200 offset:20480
	ds_read_b128 v[212:215], v200 offset:21504
	ds_read_b128 v[216:219], v200 offset:22528
	ds_read_b128 v[220:223], v200 offset:23552
	global_load_lds_dwordx4 v164, s[72:73]
	s_add_i32 m0, s49, 0x2000
	s_add_u32 vcc_lo, s72, 0x40000
	s_addc_u32 vcc_hi, s73, 0
	s_add_i32 s48, s48, s79
	global_load_lds_dwordx4 v168, s[72:73]
	s_mov_b32 m0, s48
	s_nop 0
	global_load_lds_dwordx4 v164, vcc
	s_add_i32 m0, s48, 0x2000
	s_nop 0
	global_load_lds_dwordx4 v168, vcc
	s_add_u32 s98, s74, s90
	s_addc_u32 s99, s75, s91
	s_waitcnt vmcnt(6)
	s_waitcnt lgkmcnt(0)
	s_barrier
	s_waitcnt lgkmcnt(0)
	v_mfma_f32_16x16x32_bf16 v[62:65], v[130:133], v[174:177], v[62:65]
	v_mfma_f32_16x16x32_bf16 v[58:61], v[138:141], v[174:177], v[58:61]
	v_mfma_f32_16x16x32_bf16 v[54:57], v[130:133], v[190:193], v[54:57]
	v_mfma_f32_16x16x32_bf16 v[50:53], v[138:141], v[190:193], v[50:53]
	v_mfma_f32_16x16x32_bf16 v[46:49], v[130:133], v[202:205], v[46:49]
	v_mfma_f32_16x16x32_bf16 v[42:45], v[138:141], v[202:205], v[42:45]
	v_mfma_f32_16x16x32_bf16 v[38:41], v[130:133], v[216:219], v[38:41]
	v_mfma_f32_16x16x32_bf16 v[34:37], v[138:141], v[216:219], v[34:37]
	v_mfma_f32_16x16x32_bf16 v[62:65], v[134:137], v[182:185], v[62:65]
	v_mfma_f32_16x16x32_bf16 v[58:61], v[142:145], v[182:185], v[58:61]
	v_mfma_f32_16x16x32_bf16 v[54:57], v[134:137], v[194:197], v[54:57]
	v_mfma_f32_16x16x32_bf16 v[50:53], v[142:145], v[194:197], v[50:53]
	v_mfma_f32_16x16x32_bf16 v[46:49], v[134:137], v[212:215], v[46:49]
	v_mfma_f32_16x16x32_bf16 v[42:45], v[142:145], v[212:215], v[42:45]
	v_mfma_f32_16x16x32_bf16 v[38:41], v[134:137], v[220:223], v[38:41]
	v_mfma_f32_16x16x32_bf16 v[34:37], v[142:145], v[220:223], v[34:37]
	v_mfma_f32_16x16x32_bf16 v[30:33], v[146:149], v[174:177], v[30:33]
	v_mfma_f32_16x16x32_bf16 v[26:29], v[154:157], v[174:177], v[26:29]
	v_mfma_f32_16x16x32_bf16 v[22:25], v[146:149], v[190:193], v[22:25]
	v_mfma_f32_16x16x32_bf16 v[18:21], v[154:157], v[190:193], v[18:21]
	v_mfma_f32_16x16x32_bf16 v[14:17], v[146:149], v[202:205], v[14:17]
	v_mfma_f32_16x16x32_bf16 v[10:13], v[154:157], v[202:205], v[10:13]
	v_mfma_f32_16x16x32_bf16 v[6:9], v[146:149], v[216:219], v[6:9]
	v_mfma_f32_16x16x32_bf16 v[2:5], v[154:157], v[216:219], v[2:5]
	v_mfma_f32_16x16x32_bf16 v[30:33], v[150:153], v[182:185], v[30:33]
	v_mfma_f32_16x16x32_bf16 v[26:29], v[158:161], v[182:185], v[26:29]
	v_mfma_f32_16x16x32_bf16 v[22:25], v[150:153], v[194:197], v[22:25]
	v_mfma_f32_16x16x32_bf16 v[18:21], v[158:161], v[194:197], v[18:21]
	v_mfma_f32_16x16x32_bf16 v[14:17], v[150:153], v[212:215], v[14:17]
	v_mfma_f32_16x16x32_bf16 v[10:13], v[158:161], v[212:215], v[10:13]
	v_mfma_f32_16x16x32_bf16 v[6:9], v[150:153], v[220:223], v[6:9]
	v_mfma_f32_16x16x32_bf16 v[2:5], v[158:161], v[220:223], v[2:5]
	s_barrier
; #define PG8_STAGE(bufoff, gbase, voff) do { _Pragma("unroll") for (int _i = 0; _i < 2; ++_i) \
;         __builtin_amdgcn_global_load_lds((const unsigned*)((const char*)(gbase) + (voff)[_i]), (LAS unsigned*)(lds + (bufoff) + ldsw + _i * 8192), 16, 0, 0); } while (0)
; #define PG8_LDA(dst, b, h) do { _Pragma("unroll") for (int m = 0; m < 4; ++m) _Pragma("unroll") for (int k = 0; k < 2; ++k) dst[m][k] = *(const LAS bf16x8*)(lds + PG8_SA(b, h) + aoff + m * 2048 + k * 1024); } while (0)
; #define PG8_LDB(dst, b, h) do { _Pragma("unroll") for (int n = 0; n < 2; ++n) _Pragma("unroll") for (int k = 0; k < 2; ++k) dst[n][k] = *(const LAS bf16x8*)(lds + PG8_SB(b, h) + boff + n * 2048 + k * 1024); } while (0)
; #define PG8_MMA(ai, bj, At, Bt) do { __builtin_amdgcn_s_setprio(1); _Pragma("unroll") for (int m = 0; m < 4; ++m) _Pragma("unroll") for (int n = 0; n < 2; ++n) _Pragma("unroll") for (int k = 0; k < 2; ++k) \
;         acc[ai][bj][m][n] = __builtin_amdgcn_mfma_f32_16x16x32_bf16(Bt[n][k], At[m][k], acc[ai][bj][m][n], 0, 0, 0); __builtin_amdgcn_s_setprio(0); } while (0)
; #define PG8_WAIT_V(n) asm volatile("s_waitcnt vmcnt(" #n ")" ::: "memory")
; #define PG8_WAIT_L(n) asm volatile("s_waitcnt lgkmcnt(" #n ")" ::: "memory")
; #define PG8_BAR __builtin_amdgcn_s_barrier()
; #define PG8_SCHED __builtin_amdgcn_sched_barrier(0)
; template <class Epi, class Sched>
; DI void gemm_phase(LAS unsigned char* lds, const int K, const Sched& S, const Epi& E) {
;     ...
;             PG8_LDB(B0, 1, 0); PG8_LDB(B1, 1, 1); PG8_SCHED; PG8_LDA(At, 1, 0); PG8_STAGE(PG8_SA(0, 1), a2 + hstep, voffA);
;             PG8_WAIT_V(8); PG8_WAIT_L(0); PG8_BAR; PG8_MMA(0, 0, At, B0); PG8_MMA(0, 1, At, B1); PG8_BAR; PG8_SCHED;
;             PG8_LDA(At, 1, 1); PG8_STAGE(PG8_SB(1, 0), b3, voffB); PG8_STAGE(PG8_SB(1, 1), b3 + hstep, voffB); PG8_STAGE(PG8_SA(1, 0), a3, voffA);
;             PG8_WAIT_V(8); PG8_WAIT_L(0); PG8_BAR; PG8_MMA(1, 0, At, B0); PG8_MMA(1, 1, At, B1); PG8_BAR; PG8_SCHED;
;         }
;         if (wr == 0) PG8_BAR;
	s_add_i32 s48, 0, 0x18000
	s_add_i32 s49, 0, 0x1c000
	v_add_u32_e32 v142, s48, v199
	v_add_u32_e32 v158, s49, v199
	ds_read_b128 v[130:133], v142
	ds_read_b128 v[134:137], v142 offset:1024
	ds_read_b128 v[138:141], v142 offset:2048
	ds_read_b128 v[142:145], v142 offset:3072
	ds_read_b128 v[146:149], v158
	ds_read_b128 v[150:153], v158 offset:1024
	ds_read_b128 v[154:157], v158 offset:2048
	ds_read_b128 v[158:161], v158 offset:3072
	s_mov_b32 m0, s80
	ds_read_b128 v[174:177], v200 offset:32768
	ds_read_b128 v[182:185], v200 offset:33792
	ds_read_b128 v[190:193], v200 offset:34816
	ds_read_b128 v[194:197], v200 offset:35840
	ds_read_b128 v[202:205], v200 offset:36864
	ds_read_b128 v[212:215], v200 offset:37888
	ds_read_b128 v[216:219], v200 offset:38912
	ds_read_b128 v[220:223], v200 offset:39936
	global_load_lds_dwordx4 v162, s[74:75]
	s_mov_b32 m0, s81
	s_nop 0
	global_load_lds_dwordx4 v166, s[74:75]
	s_add_u32 s74, s74, 0x40000
	s_addc_u32 s75, s75, 0
	s_mov_b32 m0, s85
	s_nop 0
	global_load_lds_dwordx4 v162, s[74:75]
	s_mov_b32 m0, s86
	s_nop 0
	global_load_lds_dwordx4 v166, s[74:75]
	s_waitcnt vmcnt(8)
	s_waitcnt lgkmcnt(0)
	s_barrier
	s_waitcnt lgkmcnt(0)
	v_mfma_f32_16x16x32_bf16 v[126:129], v[130:133], v[174:177], v[126:129]
	v_mfma_f32_16x16x32_bf16 v[122:125], v[138:141], v[174:177], v[122:125]
	v_mfma_f32_16x16x32_bf16 v[118:121], v[130:133], v[190:193], v[118:121]
	v_mfma_f32_16x16x32_bf16 v[114:117], v[138:141], v[190:193], v[114:117]
	v_mfma_f32_16x16x32_bf16 v[110:113], v[130:133], v[202:205], v[110:113]
	v_mfma_f32_16x16x32_bf16 v[106:109], v[138:141], v[202:205], v[106:109]
	v_mfma_f32_16x16x32_bf16 v[102:105], v[130:133], v[216:219], v[102:105]
	v_mfma_f32_16x16x32_bf16 v[98:101], v[138:141], v[216:219], v[98:101]
	v_mfma_f32_16x16x32_bf16 v[126:129], v[134:137], v[182:185], v[126:129]
	v_mfma_f32_16x16x32_bf16 v[122:125], v[142:145], v[182:185], v[122:125]
	v_mfma_f32_16x16x32_bf16 v[118:121], v[134:137], v[194:197], v[118:121]
	v_mfma_f32_16x16x32_bf16 v[114:117], v[142:145], v[194:197], v[114:117]
	v_mfma_f32_16x16x32_bf16 v[110:113], v[134:137], v[212:215], v[110:113]
	v_mfma_f32_16x16x32_bf16 v[106:109], v[142:145], v[212:215], v[106:109]
	v_mfma_f32_16x16x32_bf16 v[102:105], v[134:137], v[220:223], v[102:105]
	v_mfma_f32_16x16x32_bf16 v[98:101], v[142:145], v[220:223], v[98:101]
	v_mfma_f32_16x16x32_bf16 v[94:97], v[146:149], v[174:177], v[94:97]
	v_mfma_f32_16x16x32_bf16 v[90:93], v[154:157], v[174:177], v[90:93]
	v_mfma_f32_16x16x32_bf16 v[86:89], v[146:149], v[190:193], v[86:89]
	v_mfma_f32_16x16x32_bf16 v[82:85], v[154:157], v[190:193], v[82:85]
	v_mfma_f32_16x16x32_bf16 v[78:81], v[146:149], v[202:205], v[78:81]
	v_mfma_f32_16x16x32_bf16 v[74:77], v[154:157], v[202:205], v[74:77]
	v_mfma_f32_16x16x32_bf16 v[70:73], v[146:149], v[216:219], v[70:73]
	v_mfma_f32_16x16x32_bf16 v[66:69], v[154:157], v[216:219], v[66:69]
	v_mfma_f32_16x16x32_bf16 v[94:97], v[150:153], v[182:185], v[94:97]
	v_mfma_f32_16x16x32_bf16 v[90:93], v[158:161], v[182:185], v[90:93]
	v_mfma_f32_16x16x32_bf16 v[86:89], v[150:153], v[194:197], v[86:89]
	v_mfma_f32_16x16x32_bf16 v[82:85], v[158:161], v[194:197], v[82:85]
	v_mfma_f32_16x16x32_bf16 v[78:81], v[150:153], v[212:215], v[78:81]
	v_mfma_f32_16x16x32_bf16 v[74:77], v[158:161], v[212:215], v[74:77]
	v_mfma_f32_16x16x32_bf16 v[70:73], v[150:153], v[220:223], v[70:73]
	v_mfma_f32_16x16x32_bf16 v[66:69], v[158:161], v[220:223], v[66:69]
	s_barrier
	s_add_i32 s48, s48, s79
	s_add_u32 s72, s72, 0x80
	s_addc_u32 s73, s73, 0
	s_mov_b32 m0, s48
	ds_read_b128 v[174:177], v200 offset:49152
	ds_read_b128 v[182:185], v200 offset:50176
	ds_read_b128 v[190:193], v200 offset:51200
	ds_read_b128 v[194:197], v200 offset:52224
	ds_read_b128 v[202:205], v200 offset:53248
	ds_read_b128 v[212:215], v200 offset:54272
	ds_read_b128 v[216:219], v200 offset:55296
	ds_read_b128 v[220:223], v200 offset:56320
	global_load_lds_dwordx4 v164, s[72:73]
	s_add_i32 m0, s48, 0x2000
	s_add_i32 s48, s49, s79
	global_load_lds_dwordx4 v168, s[72:73]
	s_add_u32 s72, s72, 0x40000
	s_addc_u32 s73, s73, 0
	s_mov_b32 m0, s48
	s_nop 0
	global_load_lds_dwordx4 v164, s[72:73]
	s_add_i32 m0, s48, 0x2000
	s_nop 0
	global_load_lds_dwordx4 v168, s[72:73]
	s_mov_b32 m0, s94
	s_nop 0
	global_load_lds_dwordx4 v162, s[98:99]
	s_mov_b32 m0, s95
	s_nop 0
	global_load_lds_dwordx4 v166, s[98:99]
	s_waitcnt vmcnt(8)
	s_waitcnt lgkmcnt(0)
	s_barrier
	s_waitcnt lgkmcnt(0)
	v_mfma_f32_16x16x32_bf16 v[62:65], v[130:133], v[174:177], v[62:65]
	v_mfma_f32_16x16x32_bf16 v[58:61], v[138:141], v[174:177], v[58:61]
	v_mfma_f32_16x16x32_bf16 v[54:57], v[130:133], v[190:193], v[54:57]
	v_mfma_f32_16x16x32_bf16 v[50:53], v[138:141], v[190:193], v[50:53]
	v_mfma_f32_16x16x32_bf16 v[46:49], v[130:133], v[202:205], v[46:49]
	v_mfma_f32_16x16x32_bf16 v[42:45], v[138:141], v[202:205], v[42:45]
	v_mfma_f32_16x16x32_bf16 v[38:41], v[130:133], v[216:219], v[38:41]
	v_mfma_f32_16x16x32_bf16 v[34:37], v[138:141], v[216:219], v[34:37]
	v_mfma_f32_16x16x32_bf16 v[62:65], v[134:137], v[182:185], v[62:65]
	v_mfma_f32_16x16x32_bf16 v[58:61], v[142:145], v[182:185], v[58:61]
	v_mfma_f32_16x16x32_bf16 v[54:57], v[134:137], v[194:197], v[54:57]
	v_mfma_f32_16x16x32_bf16 v[50:53], v[142:145], v[194:197], v[50:53]
	v_mfma_f32_16x16x32_bf16 v[46:49], v[134:137], v[212:215], v[46:49]
	v_mfma_f32_16x16x32_bf16 v[42:45], v[142:145], v[212:215], v[42:45]
	v_mfma_f32_16x16x32_bf16 v[38:41], v[134:137], v[220:223], v[38:41]
	v_mfma_f32_16x16x32_bf16 v[34:37], v[142:145], v[220:223], v[34:37]
	v_mfma_f32_16x16x32_bf16 v[30:33], v[146:149], v[174:177], v[30:33]
	v_mfma_f32_16x16x32_bf16 v[26:29], v[154:157], v[174:177], v[26:29]
	v_mfma_f32_16x16x32_bf16 v[22:25], v[146:149], v[190:193], v[22:25]
	v_mfma_f32_16x16x32_bf16 v[18:21], v[154:157], v[190:193], v[18:21]
	v_mfma_f32_16x16x32_bf16 v[14:17], v[146:149], v[202:205], v[14:17]
	v_mfma_f32_16x16x32_bf16 v[10:13], v[154:157], v[202:205], v[10:13]
	v_mfma_f32_16x16x32_bf16 v[6:9], v[146:149], v[216:219], v[6:9]
	v_mfma_f32_16x16x32_bf16 v[2:5], v[154:157], v[216:219], v[2:5]
	v_mfma_f32_16x16x32_bf16 v[30:33], v[150:153], v[182:185], v[30:33]
	v_mfma_f32_16x16x32_bf16 v[26:29], v[158:161], v[182:185], v[26:29]
	v_mfma_f32_16x16x32_bf16 v[22:25], v[150:153], v[194:197], v[22:25]
	v_mfma_f32_16x16x32_bf16 v[18:21], v[158:161], v[194:197], v[18:21]
	v_mfma_f32_16x16x32_bf16 v[14:17], v[150:153], v[212:215], v[14:17]
	v_mfma_f32_16x16x32_bf16 v[10:13], v[158:161], v[212:215], v[10:13]
	v_mfma_f32_16x16x32_bf16 v[6:9], v[150:153], v[220:223], v[6:9]
	v_mfma_f32_16x16x32_bf16 v[2:5], v[158:161], v[220:223], v[2:5]
	s_barrier
	s_add_i32 s76, s76, 2
	s_add_u32 s65, s65, 0x100
	s_addc_u32 s67, s67, 0
	s_add_u32 s44, s44, 0x100
	s_addc_u32 s45, s45, 0
	s_cmp_gt_u32 s76, 13
	s_cbranch_scc0 .LBB0_784
	s_and_b64 vcc, exec, s[58:59]
	s_cbranch_vccz .LBB0_787
	s_barrier

; #define PG8_STAGE(bufoff, gbase, voff) do { _Pragma("unroll") for (int _i = 0; _i < 2; ++_i) \
;         __builtin_amdgcn_global_load_lds((const unsigned*)((const char*)(gbase) + (voff)[_i]), (LAS unsigned*)(lds + (bufoff) + ldsw + _i * 8192), 16, 0, 0); } while (0)
; #define PG8_LDA(dst, b, h) do { _Pragma("unroll") for (int m = 0; m < 4; ++m) _Pragma("unroll") for (int k = 0; k < 2; ++k) dst[m][k] = *(const LAS bf16x8*)(lds + PG8_SA(b, h) + aoff + m * 2048 + k * 1024); } while (0)
; #define PG8_LDB(dst, b, h) do { _Pragma("unroll") for (int n = 0; n < 2; ++n) _Pragma("unroll") for (int k = 0; k < 2; ++k) dst[n][k] = *(const LAS bf16x8*)(lds + PG8_SB(b, h) + boff + n * 2048 + k * 1024); } while (0)
; #define PG8_MMA(ai, bj, At, Bt) do { __builtin_amdgcn_s_setprio(1); _Pragma("unroll") for (int m = 0; m < 4; ++m) _Pragma("unroll") for (int n = 0; n < 2; ++n) _Pragma("unroll") for (int k = 0; k < 2; ++k) \
;         acc[ai][bj][m][n] = __builtin_amdgcn_mfma_f32_16x16x32_bf16(Bt[n][k], At[m][k], acc[ai][bj][m][n], 0, 0, 0); __builtin_amdgcn_s_setprio(0); } while (0)
; #define PG8_WAIT_V(n) asm volatile("s_waitcnt vmcnt(" #n ")" ::: "memory")
; #define PG8_WAIT_L(n) asm volatile("s_waitcnt lgkmcnt(" #n ")" ::: "memory")
; #define PG8_BAR __builtin_amdgcn_s_barrier()
; #define PG8_SCHED __builtin_amdgcn_sched_barrier(0)
; template <class Epi, class Sched>
; DI void gemm_phase(LAS unsigned char* lds, const int K, const Sched& S, const Epi& E) {
;     ...
;         for (int t = 0; t < nt; t += 2) {
;             const bool last = (t == nt - 2);
;             const char* a1 = cA + (size_t)(t + 1) * kstep;
;             const char* a2 = last ? nA : cA + (size_t)(t + 2) * kstep; const char* b2 = last ? nB : cB + (size_t)(t + 2) * kstep;
;             const char* a3 = a2 + kstep; const char* b3 = b2 + kstep;
;             PG8_LDB(B0, 0, 0); PG8_LDB(B1, 0, 1); PG8_SCHED; PG8_LDA(At, 0, 0); PG8_STAGE(PG8_SA(1, 1), a1 + hstep, voffA);
;             PG8_WAIT_V(8); PG8_WAIT_L(0); PG8_BAR; PG8_MMA(0, 0, At, B0); PG8_MMA(0, 1, At, B1); PG8_BAR; PG8_SCHED;
;             PG8_LDA(At, 0, 1); PG8_STAGE(PG8_SB(0, 0), b2, voffB); PG8_STAGE(PG8_SB(0, 1), b2 + hstep, voffB); PG8_STAGE(PG8_SA(0, 0), a2, voffA);
;             PG8_WAIT_V(8); PG8_WAIT_L(0); PG8_BAR; PG8_MMA(1, 0, At, B0); PG8_MMA(1, 1, At, B1); PG8_BAR; PG8_SCHED;
.LBB0_945:
	s_add_u32 s48, s62, 0xfffc0080
	s_addc_u32 s49, s63, -1
	s_add_i32 s84, 0, 0x10000
	s_cmp_eq_u32 s83, 12
	s_cselect_b32 s67, s59, s49
	s_cselect_b32 s66, s58, s48
	v_add_u32_e32 v145, s84, v143
	s_cselect_b32 s65, s61, s57
	s_cselect_b32 s64, s60, s55
	s_add_i32 s48, 0, 0x14000
	ds_read_b128 v[146:149], v145
	ds_read_b128 v[150:153], v145 offset:1024
	ds_read_b128 v[154:157], v145 offset:2048
	ds_read_b128 v[158:161], v145 offset:3072
	v_add_u32_e32 v145, s48, v143
	ds_read_b128 v[162:165], v145
	ds_read_b128 v[166:169], v145 offset:1024
	ds_read_b128 v[170:173], v145 offset:2048
	ds_read_b128 v[174:177], v145 offset:3072
	s_add_i32 m0, s53, 0xc000
	ds_read_b128 v[182:185], v144
	ds_read_b128 v[190:193], v144 offset:1024
	ds_read_b128 v[194:197], v144 offset:2048
	ds_read_b128 v[198:201], v144 offset:3072
	ds_read_b128 v[202:205], v144 offset:4096
	ds_read_b128 v[212:215], v144 offset:5120
	ds_read_b128 v[216:219], v144 offset:6144
	ds_read_b128 v[220:223], v144 offset:7168
	global_load_lds_dwordx4 v140, s[62:63]
	s_add_i32 m0, s53, 0xe000
	s_nop 0
	global_load_lds_dwordx4 v138, s[62:63]
	s_waitcnt vmcnt(8)
	s_waitcnt lgkmcnt(0)
	s_barrier
	s_waitcnt lgkmcnt(0)
	v_mfma_f32_16x16x32_bf16 v[126:129], v[146:149], v[182:185], v[126:129]
	v_mfma_f32_16x16x32_bf16 v[122:125], v[154:157], v[182:185], v[122:125]
	v_mfma_f32_16x16x32_bf16 v[118:121], v[146:149], v[194:197], v[118:121]
	v_mfma_f32_16x16x32_bf16 v[114:117], v[154:157], v[194:197], v[114:117]
	v_mfma_f32_16x16x32_bf16 v[102:105], v[146:149], v[202:205], v[102:105]
	v_mfma_f32_16x16x32_bf16 v[98:101], v[154:157], v[202:205], v[98:101]
	v_mfma_f32_16x16x32_bf16 v[86:89], v[146:149], v[216:219], v[86:89]
	v_mfma_f32_16x16x32_bf16 v[82:85], v[154:157], v[216:219], v[82:85]
	v_mfma_f32_16x16x32_bf16 v[126:129], v[150:153], v[190:193], v[126:129]
	v_mfma_f32_16x16x32_bf16 v[122:125], v[158:161], v[190:193], v[122:125]
	v_mfma_f32_16x16x32_bf16 v[118:121], v[150:153], v[198:201], v[118:121]
	v_mfma_f32_16x16x32_bf16 v[114:117], v[158:161], v[198:201], v[114:117]
	v_mfma_f32_16x16x32_bf16 v[102:105], v[150:153], v[212:215], v[102:105]
	v_mfma_f32_16x16x32_bf16 v[98:101], v[158:161], v[212:215], v[98:101]
	v_mfma_f32_16x16x32_bf16 v[86:89], v[150:153], v[220:223], v[86:89]
	v_mfma_f32_16x16x32_bf16 v[82:85], v[158:161], v[220:223], v[82:85]
	v_mfma_f32_16x16x32_bf16 v[110:113], v[162:165], v[182:185], v[110:113]
	v_mfma_f32_16x16x32_bf16 v[106:109], v[170:173], v[182:185], v[106:109]
	v_mfma_f32_16x16x32_bf16 v[94:97], v[162:165], v[194:197], v[94:97]
	v_mfma_f32_16x16x32_bf16 v[90:93], v[170:173], v[194:197], v[90:93]
	v_mfma_f32_16x16x32_bf16 v[78:81], v[162:165], v[202:205], v[78:81]
	v_mfma_f32_16x16x32_bf16 v[74:77], v[170:173], v[202:205], v[74:77]
	v_mfma_f32_16x16x32_bf16 v[70:73], v[162:165], v[216:219], v[70:73]
	v_mfma_f32_16x16x32_bf16 v[66:69], v[170:173], v[216:219], v[66:69]
	v_mfma_f32_16x16x32_bf16 v[110:113], v[166:169], v[190:193], v[110:113]
	v_mfma_f32_16x16x32_bf16 v[106:109], v[174:177], v[190:193], v[106:109]
	v_mfma_f32_16x16x32_bf16 v[94:97], v[166:169], v[198:201], v[94:97]
	v_mfma_f32_16x16x32_bf16 v[90:93], v[174:177], v[198:201], v[90:93]
	v_mfma_f32_16x16x32_bf16 v[78:81], v[166:169], v[212:215], v[78:81]
	v_mfma_f32_16x16x32_bf16 v[74:77], v[174:177], v[212:215], v[74:77]
	v_mfma_f32_16x16x32_bf16 v[70:73], v[166:169], v[220:223], v[70:73]
	v_mfma_f32_16x16x32_bf16 v[66:69], v[174:177], v[220:223], v[66:69]
	s_barrier
	s_add_i32 s49, s84, s71
	s_mov_b32 m0, s49
	ds_read_b128 v[182:185], v144 offset:16384
	ds_read_b128 v[190:193], v144 offset:17408
	ds_read_b128 v[194:197], v144 offset:18432
	ds_read_b128 v[198:201], v144 offset:19456
	ds_read_b128 v[202:205], v144 offset:20480
	ds_read_b128 v[212:215], v144 offset:21504
	ds_read_b128 v[216:219], v144 offset:22528
	ds_read_b128 v[220:223], v144 offset:23552
	global_load_lds_dwordx4 v134, s[64:65]
	s_add_i32 m0, s49, 0x2000
	s_add_u32 s84, s64, 0x40000
	s_addc_u32 s85, s65, 0
	s_add_i32 s48, s48, s71
	global_load_lds_dwordx4 v130, s[64:65]
	s_mov_b32 m0, s48
	s_nop 0
	global_load_lds_dwordx4 v134, s[84:85]
	s_add_i32 m0, s48, 0x2000
	s_nop 0
	global_load_lds_dwordx4 v130, s[84:85]
	s_add_u32 s98, s66, s90
	s_addc_u32 s99, s67, s91
	s_waitcnt vmcnt(6)
	s_waitcnt lgkmcnt(0)
	s_barrier
	s_waitcnt lgkmcnt(0)
	v_mfma_f32_16x16x32_bf16 v[62:65], v[146:149], v[182:185], v[62:65]
	v_mfma_f32_16x16x32_bf16 v[58:61], v[154:157], v[182:185], v[58:61]
	v_mfma_f32_16x16x32_bf16 v[54:57], v[146:149], v[194:197], v[54:57]
	v_mfma_f32_16x16x32_bf16 v[50:53], v[154:157], v[194:197], v[50:53]
	v_mfma_f32_16x16x32_bf16 v[38:41], v[146:149], v[202:205], v[38:41]
	v_mfma_f32_16x16x32_bf16 v[34:37], v[154:157], v[202:205], v[34:37]
	v_mfma_f32_16x16x32_bf16 v[22:25], v[146:149], v[216:219], v[22:25]
	v_mfma_f32_16x16x32_bf16 v[18:21], v[154:157], v[216:219], v[18:21]
	v_mfma_f32_16x16x32_bf16 v[62:65], v[150:153], v[190:193], v[62:65]
	v_mfma_f32_16x16x32_bf16 v[58:61], v[158:161], v[190:193], v[58:61]
	v_mfma_f32_16x16x32_bf16 v[54:57], v[150:153], v[198:201], v[54:57]
	v_mfma_f32_16x16x32_bf16 v[50:53], v[158:161], v[198:201], v[50:53]
	v_mfma_f32_16x16x32_bf16 v[38:41], v[150:153], v[212:215], v[38:41]
	v_mfma_f32_16x16x32_bf16 v[34:37], v[158:161], v[212:215], v[34:37]
	v_mfma_f32_16x16x32_bf16 v[22:25], v[150:153], v[220:223], v[22:25]
	v_mfma_f32_16x16x32_bf16 v[18:21], v[158:161], v[220:223], v[18:21]
	v_mfma_f32_16x16x32_bf16 v[46:49], v[162:165], v[182:185], v[46:49]
	v_mfma_f32_16x16x32_bf16 v[42:45], v[170:173], v[182:185], v[42:45]
	v_mfma_f32_16x16x32_bf16 v[30:33], v[162:165], v[194:197], v[30:33]
	v_mfma_f32_16x16x32_bf16 v[26:29], v[170:173], v[194:197], v[26:29]
	v_mfma_f32_16x16x32_bf16 v[14:17], v[162:165], v[202:205], v[14:17]
	v_mfma_f32_16x16x32_bf16 v[10:13], v[170:173], v[202:205], v[10:13]
	v_mfma_f32_16x16x32_bf16 v[6:9], v[162:165], v[216:219], v[6:9]
	v_mfma_f32_16x16x32_bf16 v[2:5], v[170:173], v[216:219], v[2:5]
	v_mfma_f32_16x16x32_bf16 v[46:49], v[166:169], v[190:193], v[46:49]
	v_mfma_f32_16x16x32_bf16 v[42:45], v[174:177], v[190:193], v[42:45]
	v_mfma_f32_16x16x32_bf16 v[30:33], v[166:169], v[198:201], v[30:33]
	v_mfma_f32_16x16x32_bf16 v[26:29], v[174:177], v[198:201], v[26:29]
	v_mfma_f32_16x16x32_bf16 v[14:17], v[166:169], v[212:215], v[14:17]
	v_mfma_f32_16x16x32_bf16 v[10:13], v[174:177], v[212:215], v[10:13]
	v_mfma_f32_16x16x32_bf16 v[6:9], v[166:169], v[220:223], v[6:9]
	v_mfma_f32_16x16x32_bf16 v[2:5], v[174:177], v[220:223], v[2:5]
	s_barrier
; #define PG8_STAGE(bufoff, gbase, voff) do { _Pragma("unroll") for (int _i = 0; _i < 2; ++_i) \
;         __builtin_amdgcn_global_load_lds((const unsigned*)((const char*)(gbase) + (voff)[_i]), (LAS unsigned*)(lds + (bufoff) + ldsw + _i * 8192), 16, 0, 0); } while (0)
; #define PG8_LDA(dst, b, h) do { _Pragma("unroll") for (int m = 0; m < 4; ++m) _Pragma("unroll") for (int k = 0; k < 2; ++k) dst[m][k] = *(const LAS bf16x8*)(lds + PG8_SA(b, h) + aoff + m * 2048 + k * 1024); } while (0)
; #define PG8_LDB(dst, b, h) do { _Pragma("unroll") for (int n = 0; n < 2; ++n) _Pragma("unroll") for (int k = 0; k < 2; ++k) dst[n][k] = *(const LAS bf16x8*)(lds + PG8_SB(b, h) + boff + n * 2048 + k * 1024); } while (0)
; #define PG8_MMA(ai, bj, At, Bt) do { __builtin_amdgcn_s_setprio(1); _Pragma("unroll") for (int m = 0; m < 4; ++m) _Pragma("unroll") for (int n = 0; n < 2; ++n) _Pragma("unroll") for (int k = 0; k < 2; ++k) \
;         acc[ai][bj][m][n] = __builtin_amdgcn_mfma_f32_16x16x32_bf16(Bt[n][k], At[m][k], acc[ai][bj][m][n], 0, 0, 0); __builtin_amdgcn_s_setprio(0); } while (0)
; #define PG8_WAIT_V(n) asm volatile("s_waitcnt vmcnt(" #n ")" ::: "memory")
; #define PG8_WAIT_L(n) asm volatile("s_waitcnt lgkmcnt(" #n ")" ::: "memory")
; #define PG8_BAR __builtin_amdgcn_s_barrier()
; #define PG8_SCHED __builtin_amdgcn_sched_barrier(0)
; template <class Epi, class Sched>
; DI void gemm_phase(LAS unsigned char* lds, const int K, const Sched& S, const Epi& E) {
;     ...
;             PG8_LDB(B0, 1, 0); PG8_LDB(B1, 1, 1); PG8_SCHED; PG8_LDA(At, 1, 0); PG8_STAGE(PG8_SA(0, 1), a2 + hstep, voffA);
;             PG8_WAIT_V(8); PG8_WAIT_L(0); PG8_BAR; PG8_MMA(0, 0, At, B0); PG8_MMA(0, 1, At, B1); PG8_BAR; PG8_SCHED;
;             PG8_LDA(At, 1, 1); PG8_STAGE(PG8_SB(1, 0), b3, voffB); PG8_STAGE(PG8_SB(1, 1), b3 + hstep, voffB); PG8_STAGE(PG8_SA(1, 0), a3, voffA);
;             PG8_WAIT_V(8); PG8_WAIT_L(0); PG8_BAR; PG8_MMA(1, 0, At, B0); PG8_MMA(1, 1, At, B1); PG8_BAR; PG8_SCHED;
;         }
;         if (wr == 0) PG8_BAR;
	s_add_i32 s48, 0, 0x18000
	v_add_u32_e32 v145, s48, v143
	s_add_i32 s49, 0, 0x1c000
	ds_read_b128 v[146:149], v145
	ds_read_b128 v[150:153], v145 offset:1024
	ds_read_b128 v[154:157], v145 offset:2048
	ds_read_b128 v[158:161], v145 offset:3072
	v_add_u32_e32 v145, s49, v143
	ds_read_b128 v[162:165], v145
	ds_read_b128 v[166:169], v145 offset:1024
	ds_read_b128 v[170:173], v145 offset:2048
	ds_read_b128 v[174:177], v145 offset:3072
	s_mov_b32 m0, s53
	ds_read_b128 v[182:185], v144 offset:32768
	ds_read_b128 v[190:193], v144 offset:33792
	ds_read_b128 v[194:197], v144 offset:34816
	ds_read_b128 v[198:201], v144 offset:35840
	ds_read_b128 v[202:205], v144 offset:36864
	ds_read_b128 v[212:215], v144 offset:37888
	ds_read_b128 v[216:219], v144 offset:38912
	ds_read_b128 v[220:223], v144 offset:39936
	global_load_lds_dwordx4 v136, s[66:67]
	s_mov_b32 m0, s73
	s_nop 0
	global_load_lds_dwordx4 v132, s[66:67]
	s_add_u32 s66, s66, 0x40000
	s_addc_u32 s67, s67, 0
	s_mov_b32 m0, s74
	s_nop 0
	global_load_lds_dwordx4 v136, s[66:67]
	s_mov_b32 m0, s75
	s_nop 0
	global_load_lds_dwordx4 v132, s[66:67]
	s_waitcnt vmcnt(8)
	s_waitcnt lgkmcnt(0)
	s_barrier
	s_waitcnt lgkmcnt(0)
	v_mfma_f32_16x16x32_bf16 v[126:129], v[146:149], v[182:185], v[126:129]
	v_mfma_f32_16x16x32_bf16 v[122:125], v[154:157], v[182:185], v[122:125]
	v_mfma_f32_16x16x32_bf16 v[118:121], v[146:149], v[194:197], v[118:121]
	v_mfma_f32_16x16x32_bf16 v[114:117], v[154:157], v[194:197], v[114:117]
	v_mfma_f32_16x16x32_bf16 v[102:105], v[146:149], v[202:205], v[102:105]
	v_mfma_f32_16x16x32_bf16 v[98:101], v[154:157], v[202:205], v[98:101]
	v_mfma_f32_16x16x32_bf16 v[86:89], v[146:149], v[216:219], v[86:89]
	v_mfma_f32_16x16x32_bf16 v[82:85], v[154:157], v[216:219], v[82:85]
	v_mfma_f32_16x16x32_bf16 v[126:129], v[150:153], v[190:193], v[126:129]
	v_mfma_f32_16x16x32_bf16 v[122:125], v[158:161], v[190:193], v[122:125]
	v_mfma_f32_16x16x32_bf16 v[118:121], v[150:153], v[198:201], v[118:121]
	v_mfma_f32_16x16x32_bf16 v[114:117], v[158:161], v[198:201], v[114:117]
	v_mfma_f32_16x16x32_bf16 v[102:105], v[150:153], v[212:215], v[102:105]
	v_mfma_f32_16x16x32_bf16 v[98:101], v[158:161], v[212:215], v[98:101]
	v_mfma_f32_16x16x32_bf16 v[86:89], v[150:153], v[220:223], v[86:89]
	v_mfma_f32_16x16x32_bf16 v[82:85], v[158:161], v[220:223], v[82:85]
	v_mfma_f32_16x16x32_bf16 v[110:113], v[162:165], v[182:185], v[110:113]
	v_mfma_f32_16x16x32_bf16 v[106:109], v[170:173], v[182:185], v[106:109]
	v_mfma_f32_16x16x32_bf16 v[94:97], v[162:165], v[194:197], v[94:97]
	v_mfma_f32_16x16x32_bf16 v[90:93], v[170:173], v[194:197], v[90:93]
	v_mfma_f32_16x16x32_bf16 v[78:81], v[162:165], v[202:205], v[78:81]
	v_mfma_f32_16x16x32_bf16 v[74:77], v[170:173], v[202:205], v[74:77]
	v_mfma_f32_16x16x32_bf16 v[70:73], v[162:165], v[216:219], v[70:73]
	v_mfma_f32_16x16x32_bf16 v[66:69], v[170:173], v[216:219], v[66:69]
	v_mfma_f32_16x16x32_bf16 v[110:113], v[166:169], v[190:193], v[110:113]
	v_mfma_f32_16x16x32_bf16 v[106:109], v[174:177], v[190:193], v[106:109]
	v_mfma_f32_16x16x32_bf16 v[94:97], v[166:169], v[198:201], v[94:97]
	v_mfma_f32_16x16x32_bf16 v[90:93], v[174:177], v[198:201], v[90:93]
	v_mfma_f32_16x16x32_bf16 v[78:81], v[166:169], v[212:215], v[78:81]
	v_mfma_f32_16x16x32_bf16 v[74:77], v[174:177], v[212:215], v[74:77]
	v_mfma_f32_16x16x32_bf16 v[70:73], v[166:169], v[220:223], v[70:73]
	v_mfma_f32_16x16x32_bf16 v[66:69], v[174:177], v[220:223], v[66:69]
	s_barrier
	s_add_i32 s48, s48, s71
	s_add_u32 s64, s64, 0x80
	s_addc_u32 s65, s65, 0
	s_mov_b32 m0, s48
	ds_read_b128 v[182:185], v144 offset:49152
	ds_read_b128 v[190:193], v144 offset:50176
	ds_read_b128 v[194:197], v144 offset:51200
	ds_read_b128 v[198:201], v144 offset:52224
	ds_read_b128 v[202:205], v144 offset:53248
	ds_read_b128 v[212:215], v144 offset:54272
	ds_read_b128 v[216:219], v144 offset:55296
	ds_read_b128 v[220:223], v144 offset:56320
	global_load_lds_dwordx4 v134, s[64:65]
	s_add_i32 m0, s48, 0x2000
	s_add_i32 s48, s49, s71
	global_load_lds_dwordx4 v130, s[64:65]
	s_add_u32 s64, s64, 0x40000
	s_addc_u32 s65, s65, 0
	s_mov_b32 m0, s48
	s_nop 0
	global_load_lds_dwordx4 v134, s[64:65]
	s_add_i32 m0, s48, 0x2000
	s_nop 0
	global_load_lds_dwordx4 v130, s[64:65]
	s_mov_b32 m0, s78
	s_nop 0
	global_load_lds_dwordx4 v136, s[98:99]
	s_mov_b32 m0, s79
	s_nop 0
	global_load_lds_dwordx4 v132, s[98:99]
	s_waitcnt vmcnt(8)
	s_waitcnt lgkmcnt(0)
	s_barrier
	s_waitcnt lgkmcnt(0)
	v_mfma_f32_16x16x32_bf16 v[62:65], v[146:149], v[182:185], v[62:65]
	v_mfma_f32_16x16x32_bf16 v[58:61], v[154:157], v[182:185], v[58:61]
	v_mfma_f32_16x16x32_bf16 v[54:57], v[146:149], v[194:197], v[54:57]
	v_mfma_f32_16x16x32_bf16 v[50:53], v[154:157], v[194:197], v[50:53]
	v_mfma_f32_16x16x32_bf16 v[38:41], v[146:149], v[202:205], v[38:41]
	v_mfma_f32_16x16x32_bf16 v[34:37], v[154:157], v[202:205], v[34:37]
	v_mfma_f32_16x16x32_bf16 v[22:25], v[146:149], v[216:219], v[22:25]
	v_mfma_f32_16x16x32_bf16 v[18:21], v[154:157], v[216:219], v[18:21]
	v_mfma_f32_16x16x32_bf16 v[62:65], v[150:153], v[190:193], v[62:65]
	v_mfma_f32_16x16x32_bf16 v[58:61], v[158:161], v[190:193], v[58:61]
	v_mfma_f32_16x16x32_bf16 v[54:57], v[150:153], v[198:201], v[54:57]
	v_mfma_f32_16x16x32_bf16 v[50:53], v[158:161], v[198:201], v[50:53]
	v_mfma_f32_16x16x32_bf16 v[38:41], v[150:153], v[212:215], v[38:41]
	v_mfma_f32_16x16x32_bf16 v[34:37], v[158:161], v[212:215], v[34:37]
	v_mfma_f32_16x16x32_bf16 v[22:25], v[150:153], v[220:223], v[22:25]
	v_mfma_f32_16x16x32_bf16 v[18:21], v[158:161], v[220:223], v[18:21]
	v_mfma_f32_16x16x32_bf16 v[46:49], v[162:165], v[182:185], v[46:49]
	v_mfma_f32_16x16x32_bf16 v[42:45], v[170:173], v[182:185], v[42:45]
	v_mfma_f32_16x16x32_bf16 v[30:33], v[162:165], v[194:197], v[30:33]
	v_mfma_f32_16x16x32_bf16 v[26:29], v[170:173], v[194:197], v[26:29]
	v_mfma_f32_16x16x32_bf16 v[14:17], v[162:165], v[202:205], v[14:17]
	v_mfma_f32_16x16x32_bf16 v[10:13], v[170:173], v[202:205], v[10:13]
	v_mfma_f32_16x16x32_bf16 v[6:9], v[162:165], v[216:219], v[6:9]
	v_mfma_f32_16x16x32_bf16 v[2:5], v[170:173], v[216:219], v[2:5]
	v_mfma_f32_16x16x32_bf16 v[46:49], v[166:169], v[190:193], v[46:49]
	v_mfma_f32_16x16x32_bf16 v[42:45], v[174:177], v[190:193], v[42:45]
	v_mfma_f32_16x16x32_bf16 v[30:33], v[166:169], v[198:201], v[30:33]
	v_mfma_f32_16x16x32_bf16 v[26:29], v[174:177], v[198:201], v[26:29]
	v_mfma_f32_16x16x32_bf16 v[14:17], v[166:169], v[212:215], v[14:17]
	v_mfma_f32_16x16x32_bf16 v[10:13], v[174:177], v[212:215], v[10:13]
	v_mfma_f32_16x16x32_bf16 v[6:9], v[166:169], v[220:223], v[6:9]
	v_mfma_f32_16x16x32_bf16 v[2:5], v[174:177], v[220:223], v[2:5]
	s_barrier
	s_add_i32 s83, s83, 2
	s_add_u32 s55, s55, 0x100
	s_addc_u32 s57, s57, 0
	s_add_u32 s62, s62, 0x100
	s_addc_u32 s63, s63, 0
	s_cmp_gt_u32 s83, 13
	s_cbranch_scc0 .LBB0_945
	s_and_b64 vcc, exec, s[50:51]
	s_cbranch_vccz .LBB0_948
	s_barrier

; #define PG8_STAGE(bufoff, gbase, voff) do { _Pragma("unroll") for (int _i = 0; _i < 2; ++_i) \
;         __builtin_amdgcn_global_load_lds((const unsigned*)((const char*)(gbase) + (voff)[_i]), (LAS unsigned*)(lds + (bufoff) + ldsw + _i * 8192), 16, 0, 0); } while (0)
; #define PG8_LDA(dst, b, h) do { _Pragma("unroll") for (int m = 0; m < 4; ++m) _Pragma("unroll") for (int k = 0; k < 2; ++k) dst[m][k] = *(const LAS bf16x8*)(lds + PG8_SA(b, h) + aoff + m * 2048 + k * 1024); } while (0)
; #define PG8_LDB(dst, b, h) do { _Pragma("unroll") for (int n = 0; n < 2; ++n) _Pragma("unroll") for (int k = 0; k < 2; ++k) dst[n][k] = *(const LAS bf16x8*)(lds + PG8_SB(b, h) + boff + n * 2048 + k * 1024); } while (0)
; #define PG8_MMA(ai, bj, At, Bt) do { __builtin_amdgcn_s_setprio(1); _Pragma("unroll") for (int m = 0; m < 4; ++m) _Pragma("unroll") for (int n = 0; n < 2; ++n) _Pragma("unroll") for (int k = 0; k < 2; ++k) \
;         acc[ai][bj][m][n] = __builtin_amdgcn_mfma_f32_16x16x32_bf16(Bt[n][k], At[m][k], acc[ai][bj][m][n], 0, 0, 0); __builtin_amdgcn_s_setprio(0); } while (0)
; #define PG8_WAIT_V(n) asm volatile("s_waitcnt vmcnt(" #n ")" ::: "memory")
; #define PG8_WAIT_L(n) asm volatile("s_waitcnt lgkmcnt(" #n ")" ::: "memory")
; #define PG8_BAR __builtin_amdgcn_s_barrier()
; #define PG8_SCHED __builtin_amdgcn_sched_barrier(0)
; template <class Epi, class Sched>
; DI void gemm_phase(LAS unsigned char* lds, const int K, const Sched& S, const Epi& E) {
;     ...
;         for (int t = 0; t < nt; t += 2) {
;             const bool last = (t == nt - 2);
;             const char* a1 = cA + (size_t)(t + 1) * kstep;
;             const char* a2 = last ? nA : cA + (size_t)(t + 2) * kstep; const char* b2 = last ? nB : cB + (size_t)(t + 2) * kstep;
;             const char* a3 = a2 + kstep; const char* b3 = b2 + kstep;
;             PG8_LDB(B0, 0, 0); PG8_LDB(B1, 0, 1); PG8_SCHED; PG8_LDA(At, 0, 0); PG8_STAGE(PG8_SA(1, 1), a1 + hstep, voffA);
;             PG8_WAIT_V(8); PG8_WAIT_L(0); PG8_BAR; PG8_MMA(0, 0, At, B0); PG8_MMA(0, 1, At, B1); PG8_BAR; PG8_SCHED;
;             PG8_LDA(At, 0, 1); PG8_STAGE(PG8_SB(0, 0), b2, voffB); PG8_STAGE(PG8_SB(0, 1), b2 + hstep, voffB); PG8_STAGE(PG8_SA(0, 0), a2, voffA);
;             PG8_WAIT_V(8); PG8_WAIT_L(0); PG8_BAR; PG8_MMA(1, 0, At, B0); PG8_MMA(1, 1, At, B1); PG8_BAR; PG8_SCHED;
.LBB0_1086:
	s_add_u32 s48, s68, 0xfffc0080
	s_addc_u32 s49, s69, -1
	s_add_i32 vcc_hi, 0, 0x10000
	s_cmp_eq_u32 vcc_lo, 12
	s_cselect_b32 s73, s65, s49
	s_cselect_b32 s72, s64, s48
	v_add_u32_e32 v145, vcc_hi, v143
	s_cselect_b32 s71, s67, s63
	s_cselect_b32 s70, s66, s61
	s_add_i32 s94, 0, 0x14000
	ds_read_b128 v[146:149], v145
	ds_read_b128 v[150:153], v145 offset:1024
	ds_read_b128 v[154:157], v145 offset:2048
	ds_read_b128 v[158:161], v145 offset:3072
	v_add_u32_e32 v145, s94, v143
	ds_read_b128 v[162:165], v145
	ds_read_b128 v[166:169], v145 offset:1024
	ds_read_b128 v[170:173], v145 offset:2048
	ds_read_b128 v[174:177], v145 offset:3072
	s_add_i32 m0, s59, 0xc000
	ds_read_b128 v[182:185], v144
	ds_read_b128 v[190:193], v144 offset:1024
	ds_read_b128 v[194:197], v144 offset:2048
	ds_read_b128 v[198:201], v144 offset:3072
	ds_read_b128 v[202:205], v144 offset:4096
	ds_read_b128 v[212:215], v144 offset:5120
	ds_read_b128 v[216:219], v144 offset:6144
	ds_read_b128 v[220:223], v144 offset:7168
	global_load_lds_dwordx4 v140, s[68:69]
	s_add_i32 m0, s59, 0xe000
	s_nop 0
	global_load_lds_dwordx4 v138, s[68:69]
	s_waitcnt vmcnt(8)
	s_waitcnt lgkmcnt(0)
	s_barrier
	s_waitcnt lgkmcnt(0)
	v_mfma_f32_16x16x32_bf16 v[126:129], v[146:149], v[182:185], v[126:129]
	v_mfma_f32_16x16x32_bf16 v[122:125], v[154:157], v[182:185], v[122:125]
	v_mfma_f32_16x16x32_bf16 v[118:121], v[146:149], v[194:197], v[118:121]
	v_mfma_f32_16x16x32_bf16 v[114:117], v[154:157], v[194:197], v[114:117]
	v_mfma_f32_16x16x32_bf16 v[102:105], v[146:149], v[202:205], v[102:105]
	v_mfma_f32_16x16x32_bf16 v[98:101], v[154:157], v[202:205], v[98:101]
	v_mfma_f32_16x16x32_bf16 v[86:89], v[146:149], v[216:219], v[86:89]
	v_mfma_f32_16x16x32_bf16 v[82:85], v[154:157], v[216:219], v[82:85]
	v_mfma_f32_16x16x32_bf16 v[126:129], v[150:153], v[190:193], v[126:129]
	v_mfma_f32_16x16x32_bf16 v[122:125], v[158:161], v[190:193], v[122:125]
	v_mfma_f32_16x16x32_bf16 v[118:121], v[150:153], v[198:201], v[118:121]
	v_mfma_f32_16x16x32_bf16 v[114:117], v[158:161], v[198:201], v[114:117]
	v_mfma_f32_16x16x32_bf16 v[102:105], v[150:153], v[212:215], v[102:105]
	v_mfma_f32_16x16x32_bf16 v[98:101], v[158:161], v[212:215], v[98:101]
	v_mfma_f32_16x16x32_bf16 v[86:89], v[150:153], v[220:223], v[86:89]
	v_mfma_f32_16x16x32_bf16 v[82:85], v[158:161], v[220:223], v[82:85]
	v_mfma_f32_16x16x32_bf16 v[110:113], v[162:165], v[182:185], v[110:113]
	v_mfma_f32_16x16x32_bf16 v[106:109], v[170:173], v[182:185], v[106:109]
	v_mfma_f32_16x16x32_bf16 v[94:97], v[162:165], v[194:197], v[94:97]
	v_mfma_f32_16x16x32_bf16 v[90:93], v[170:173], v[194:197], v[90:93]
	v_mfma_f32_16x16x32_bf16 v[78:81], v[162:165], v[202:205], v[78:81]
	v_mfma_f32_16x16x32_bf16 v[74:77], v[170:173], v[202:205], v[74:77]
	v_mfma_f32_16x16x32_bf16 v[70:73], v[162:165], v[216:219], v[70:73]
	v_mfma_f32_16x16x32_bf16 v[66:69], v[170:173], v[216:219], v[66:69]
	v_mfma_f32_16x16x32_bf16 v[110:113], v[166:169], v[190:193], v[110:113]
	v_mfma_f32_16x16x32_bf16 v[106:109], v[174:177], v[190:193], v[106:109]
	v_mfma_f32_16x16x32_bf16 v[94:97], v[166:169], v[198:201], v[94:97]
	v_mfma_f32_16x16x32_bf16 v[90:93], v[174:177], v[198:201], v[90:93]
	v_mfma_f32_16x16x32_bf16 v[78:81], v[166:169], v[212:215], v[78:81]
	v_mfma_f32_16x16x32_bf16 v[74:77], v[174:177], v[212:215], v[74:77]
	v_mfma_f32_16x16x32_bf16 v[70:73], v[166:169], v[220:223], v[70:73]
	v_mfma_f32_16x16x32_bf16 v[66:69], v[174:177], v[220:223], v[66:69]
	s_barrier
	s_add_i32 s48, vcc_hi, s78
	s_mov_b32 m0, s48
	ds_read_b128 v[182:185], v144 offset:16384
	ds_read_b128 v[190:193], v144 offset:17408
	ds_read_b128 v[194:197], v144 offset:18432
	ds_read_b128 v[198:201], v144 offset:19456
	ds_read_b128 v[202:205], v144 offset:20480
	ds_read_b128 v[212:215], v144 offset:21504
	ds_read_b128 v[216:219], v144 offset:22528
	ds_read_b128 v[220:223], v144 offset:23552
	global_load_lds_dwordx4 v134, s[70:71]
	s_add_i32 m0, s48, 0x2000
	s_add_u32 s48, s70, 0x40000
	s_addc_u32 s49, s71, 0
	s_add_i32 s94, s94, s78
	global_load_lds_dwordx4 v130, s[70:71]
	s_mov_b32 m0, s94
	s_nop 0
	global_load_lds_dwordx4 v134, s[48:49]
	s_add_i32 m0, s94, 0x2000
	s_nop 0
	global_load_lds_dwordx4 v130, s[48:49]
	s_add_u32 s98, s72, s90
	s_addc_u32 s99, s73, s91
	s_waitcnt vmcnt(6)
	s_waitcnt lgkmcnt(0)
	s_barrier
	s_waitcnt lgkmcnt(0)
	v_mfma_f32_16x16x32_bf16 v[62:65], v[146:149], v[182:185], v[62:65]
	v_mfma_f32_16x16x32_bf16 v[58:61], v[154:157], v[182:185], v[58:61]
	v_mfma_f32_16x16x32_bf16 v[54:57], v[146:149], v[194:197], v[54:57]
	v_mfma_f32_16x16x32_bf16 v[50:53], v[154:157], v[194:197], v[50:53]
	v_mfma_f32_16x16x32_bf16 v[38:41], v[146:149], v[202:205], v[38:41]
	v_mfma_f32_16x16x32_bf16 v[34:37], v[154:157], v[202:205], v[34:37]
	v_mfma_f32_16x16x32_bf16 v[22:25], v[146:149], v[216:219], v[22:25]
	v_mfma_f32_16x16x32_bf16 v[18:21], v[154:157], v[216:219], v[18:21]
	v_mfma_f32_16x16x32_bf16 v[62:65], v[150:153], v[190:193], v[62:65]
	v_mfma_f32_16x16x32_bf16 v[58:61], v[158:161], v[190:193], v[58:61]
	v_mfma_f32_16x16x32_bf16 v[54:57], v[150:153], v[198:201], v[54:57]
	v_mfma_f32_16x16x32_bf16 v[50:53], v[158:161], v[198:201], v[50:53]
	v_mfma_f32_16x16x32_bf16 v[38:41], v[150:153], v[212:215], v[38:41]
	v_mfma_f32_16x16x32_bf16 v[34:37], v[158:161], v[212:215], v[34:37]
	v_mfma_f32_16x16x32_bf16 v[22:25], v[150:153], v[220:223], v[22:25]
	v_mfma_f32_16x16x32_bf16 v[18:21], v[158:161], v[220:223], v[18:21]
	v_mfma_f32_16x16x32_bf16 v[46:49], v[162:165], v[182:185], v[46:49]
	v_mfma_f32_16x16x32_bf16 v[42:45], v[170:173], v[182:185], v[42:45]
	v_mfma_f32_16x16x32_bf16 v[30:33], v[162:165], v[194:197], v[30:33]
	v_mfma_f32_16x16x32_bf16 v[26:29], v[170:173], v[194:197], v[26:29]
	v_mfma_f32_16x16x32_bf16 v[14:17], v[162:165], v[202:205], v[14:17]
	v_mfma_f32_16x16x32_bf16 v[10:13], v[170:173], v[202:205], v[10:13]
	v_mfma_f32_16x16x32_bf16 v[6:9], v[162:165], v[216:219], v[6:9]
	v_mfma_f32_16x16x32_bf16 v[2:5], v[170:173], v[216:219], v[2:5]
	v_mfma_f32_16x16x32_bf16 v[46:49], v[166:169], v[190:193], v[46:49]
	v_mfma_f32_16x16x32_bf16 v[42:45], v[174:177], v[190:193], v[42:45]
	v_mfma_f32_16x16x32_bf16 v[30:33], v[166:169], v[198:201], v[30:33]
	v_mfma_f32_16x16x32_bf16 v[26:29], v[174:177], v[198:201], v[26:29]
	v_mfma_f32_16x16x32_bf16 v[14:17], v[166:169], v[212:215], v[14:17]
	v_mfma_f32_16x16x32_bf16 v[10:13], v[174:177], v[212:215], v[10:13]
	v_mfma_f32_16x16x32_bf16 v[6:9], v[166:169], v[220:223], v[6:9]
	v_mfma_f32_16x16x32_bf16 v[2:5], v[174:177], v[220:223], v[2:5]
	s_barrier
; #define PG8_STAGE(bufoff, gbase, voff) do { _Pragma("unroll") for (int _i = 0; _i < 2; ++_i) \
;         __builtin_amdgcn_global_load_lds((const unsigned*)((const char*)(gbase) + (voff)[_i]), (LAS unsigned*)(lds + (bufoff) + ldsw + _i * 8192), 16, 0, 0); } while (0)
; #define PG8_LDA(dst, b, h) do { _Pragma("unroll") for (int m = 0; m < 4; ++m) _Pragma("unroll") for (int k = 0; k < 2; ++k) dst[m][k] = *(const LAS bf16x8*)(lds + PG8_SA(b, h) + aoff + m * 2048 + k * 1024); } while (0)
; #define PG8_LDB(dst, b, h) do { _Pragma("unroll") for (int n = 0; n < 2; ++n) _Pragma("unroll") for (int k = 0; k < 2; ++k) dst[n][k] = *(const LAS bf16x8*)(lds + PG8_SB(b, h) + boff + n * 2048 + k * 1024); } while (0)
; #define PG8_MMA(ai, bj, At, Bt) do { __builtin_amdgcn_s_setprio(1); _Pragma("unroll") for (int m = 0; m < 4; ++m) _Pragma("unroll") for (int n = 0; n < 2; ++n) _Pragma("unroll") for (int k = 0; k < 2; ++k) \
;         acc[ai][bj][m][n] = __builtin_amdgcn_mfma_f32_16x16x32_bf16(Bt[n][k], At[m][k], acc[ai][bj][m][n], 0, 0, 0); __builtin_amdgcn_s_setprio(0); } while (0)
; #define PG8_WAIT_V(n) asm volatile("s_waitcnt vmcnt(" #n ")" ::: "memory")
; #define PG8_WAIT_L(n) asm volatile("s_waitcnt lgkmcnt(" #n ")" ::: "memory")
; #define PG8_BAR __builtin_amdgcn_s_barrier()
; #define PG8_SCHED __builtin_amdgcn_sched_barrier(0)
; template <class Epi, class Sched>
; DI void gemm_phase(LAS unsigned char* lds, const int K, const Sched& S, const Epi& E) {
;     ...
;             PG8_LDB(B0, 1, 0); PG8_LDB(B1, 1, 1); PG8_SCHED; PG8_LDA(At, 1, 0); PG8_STAGE(PG8_SA(0, 1), a2 + hstep, voffA);
;             PG8_WAIT_V(8); PG8_WAIT_L(0); PG8_BAR; PG8_MMA(0, 0, At, B0); PG8_MMA(0, 1, At, B1); PG8_BAR; PG8_SCHED;
;             PG8_LDA(At, 1, 1); PG8_STAGE(PG8_SB(1, 0), b3, voffB); PG8_STAGE(PG8_SB(1, 1), b3 + hstep, voffB); PG8_STAGE(PG8_SA(1, 0), a3, voffA);
;             PG8_WAIT_V(8); PG8_WAIT_L(0); PG8_BAR; PG8_MMA(1, 0, At, B0); PG8_MMA(1, 1, At, B1); PG8_BAR; PG8_SCHED;
;         }
;         if (wr == 0) PG8_BAR;
	s_add_i32 s94, 0, 0x18000
	v_add_u32_e32 v145, s94, v143
	s_add_i32 vcc_hi, 0, 0x1c000
	ds_read_b128 v[146:149], v145
	ds_read_b128 v[150:153], v145 offset:1024
	ds_read_b128 v[154:157], v145 offset:2048
	ds_read_b128 v[158:161], v145 offset:3072
	v_add_u32_e32 v145, vcc_hi, v143
	ds_read_b128 v[162:165], v145
	ds_read_b128 v[166:169], v145 offset:1024
	ds_read_b128 v[170:173], v145 offset:2048
	ds_read_b128 v[174:177], v145 offset:3072
	s_mov_b32 m0, s59
	ds_read_b128 v[182:185], v144 offset:32768
	ds_read_b128 v[190:193], v144 offset:33792
	ds_read_b128 v[194:197], v144 offset:34816
	ds_read_b128 v[198:201], v144 offset:35840
	ds_read_b128 v[202:205], v144 offset:36864
	ds_read_b128 v[212:215], v144 offset:37888
	ds_read_b128 v[216:219], v144 offset:38912
	ds_read_b128 v[220:223], v144 offset:39936
	global_load_lds_dwordx4 v136, s[72:73]
	s_mov_b32 m0, s80
	s_nop 0
	global_load_lds_dwordx4 v132, s[72:73]
	s_add_u32 s48, s72, 0x40000
	s_addc_u32 s49, s73, 0
	s_mov_b32 m0, s81
	s_nop 0
	global_load_lds_dwordx4 v136, s[48:49]
	s_mov_b32 m0, s83
	s_nop 0
	global_load_lds_dwordx4 v132, s[48:49]
	s_waitcnt vmcnt(8)
	s_waitcnt lgkmcnt(0)
	s_barrier
	s_waitcnt lgkmcnt(0)
	v_mfma_f32_16x16x32_bf16 v[126:129], v[146:149], v[182:185], v[126:129]
	v_mfma_f32_16x16x32_bf16 v[122:125], v[154:157], v[182:185], v[122:125]
	v_mfma_f32_16x16x32_bf16 v[118:121], v[146:149], v[194:197], v[118:121]
	v_mfma_f32_16x16x32_bf16 v[114:117], v[154:157], v[194:197], v[114:117]
	v_mfma_f32_16x16x32_bf16 v[102:105], v[146:149], v[202:205], v[102:105]
	v_mfma_f32_16x16x32_bf16 v[98:101], v[154:157], v[202:205], v[98:101]
	v_mfma_f32_16x16x32_bf16 v[86:89], v[146:149], v[216:219], v[86:89]
	v_mfma_f32_16x16x32_bf16 v[82:85], v[154:157], v[216:219], v[82:85]
	v_mfma_f32_16x16x32_bf16 v[126:129], v[150:153], v[190:193], v[126:129]
	v_mfma_f32_16x16x32_bf16 v[122:125], v[158:161], v[190:193], v[122:125]
	v_mfma_f32_16x16x32_bf16 v[118:121], v[150:153], v[198:201], v[118:121]
	v_mfma_f32_16x16x32_bf16 v[114:117], v[158:161], v[198:201], v[114:117]
	v_mfma_f32_16x16x32_bf16 v[102:105], v[150:153], v[212:215], v[102:105]
	v_mfma_f32_16x16x32_bf16 v[98:101], v[158:161], v[212:215], v[98:101]
	v_mfma_f32_16x16x32_bf16 v[86:89], v[150:153], v[220:223], v[86:89]
	v_mfma_f32_16x16x32_bf16 v[82:85], v[158:161], v[220:223], v[82:85]
	v_mfma_f32_16x16x32_bf16 v[110:113], v[162:165], v[182:185], v[110:113]
	v_mfma_f32_16x16x32_bf16 v[106:109], v[170:173], v[182:185], v[106:109]
	v_mfma_f32_16x16x32_bf16 v[94:97], v[162:165], v[194:197], v[94:97]
	v_mfma_f32_16x16x32_bf16 v[90:93], v[170:173], v[194:197], v[90:93]
	v_mfma_f32_16x16x32_bf16 v[78:81], v[162:165], v[202:205], v[78:81]
	v_mfma_f32_16x16x32_bf16 v[74:77], v[170:173], v[202:205], v[74:77]
	v_mfma_f32_16x16x32_bf16 v[70:73], v[162:165], v[216:219], v[70:73]
	v_mfma_f32_16x16x32_bf16 v[66:69], v[170:173], v[216:219], v[66:69]
	v_mfma_f32_16x16x32_bf16 v[110:113], v[166:169], v[190:193], v[110:113]
	v_mfma_f32_16x16x32_bf16 v[106:109], v[174:177], v[190:193], v[106:109]
	v_mfma_f32_16x16x32_bf16 v[94:97], v[166:169], v[198:201], v[94:97]
	v_mfma_f32_16x16x32_bf16 v[90:93], v[174:177], v[198:201], v[90:93]
	v_mfma_f32_16x16x32_bf16 v[78:81], v[166:169], v[212:215], v[78:81]
	v_mfma_f32_16x16x32_bf16 v[74:77], v[174:177], v[212:215], v[74:77]
	v_mfma_f32_16x16x32_bf16 v[70:73], v[166:169], v[220:223], v[70:73]
	v_mfma_f32_16x16x32_bf16 v[66:69], v[174:177], v[220:223], v[66:69]
	s_barrier
	s_add_i32 s48, s94, s78
	s_add_u32 s70, s70, 0x80
	s_addc_u32 s71, s71, 0
	s_mov_b32 m0, s48
	ds_read_b128 v[182:185], v144 offset:49152
	ds_read_b128 v[190:193], v144 offset:50176
	ds_read_b128 v[194:197], v144 offset:51200
	ds_read_b128 v[198:201], v144 offset:52224
	ds_read_b128 v[202:205], v144 offset:53248
	ds_read_b128 v[212:215], v144 offset:54272
	ds_read_b128 v[216:219], v144 offset:55296
	ds_read_b128 v[220:223], v144 offset:56320
	global_load_lds_dwordx4 v134, s[70:71]
	s_add_i32 m0, s48, 0x2000
	s_add_u32 s48, s70, 0x40000
	s_addc_u32 s49, s71, 0
	global_load_lds_dwordx4 v130, s[70:71]
	s_add_i32 s70, vcc_hi, s78
	s_mov_b32 m0, s70
	s_nop 0
	global_load_lds_dwordx4 v134, s[48:49]
	s_add_i32 m0, s70, 0x2000
	s_nop 0
	global_load_lds_dwordx4 v130, s[48:49]
	s_mov_b32 m0, s95
	s_nop 0
	global_load_lds_dwordx4 v136, s[98:99]
	s_mov_b32 m0, s42
	s_nop 0
	global_load_lds_dwordx4 v132, s[98:99]
	s_waitcnt vmcnt(8)
	s_waitcnt lgkmcnt(0)
	s_barrier
	s_waitcnt lgkmcnt(0)
	v_mfma_f32_16x16x32_bf16 v[62:65], v[146:149], v[182:185], v[62:65]
	v_mfma_f32_16x16x32_bf16 v[58:61], v[154:157], v[182:185], v[58:61]
	v_mfma_f32_16x16x32_bf16 v[54:57], v[146:149], v[194:197], v[54:57]
	v_mfma_f32_16x16x32_bf16 v[50:53], v[154:157], v[194:197], v[50:53]
	v_mfma_f32_16x16x32_bf16 v[38:41], v[146:149], v[202:205], v[38:41]
	v_mfma_f32_16x16x32_bf16 v[34:37], v[154:157], v[202:205], v[34:37]
	v_mfma_f32_16x16x32_bf16 v[22:25], v[146:149], v[216:219], v[22:25]
	v_mfma_f32_16x16x32_bf16 v[18:21], v[154:157], v[216:219], v[18:21]
	v_mfma_f32_16x16x32_bf16 v[62:65], v[150:153], v[190:193], v[62:65]
	v_mfma_f32_16x16x32_bf16 v[58:61], v[158:161], v[190:193], v[58:61]
	v_mfma_f32_16x16x32_bf16 v[54:57], v[150:153], v[198:201], v[54:57]
	v_mfma_f32_16x16x32_bf16 v[50:53], v[158:161], v[198:201], v[50:53]
	v_mfma_f32_16x16x32_bf16 v[38:41], v[150:153], v[212:215], v[38:41]
	v_mfma_f32_16x16x32_bf16 v[34:37], v[158:161], v[212:215], v[34:37]
	v_mfma_f32_16x16x32_bf16 v[22:25], v[150:153], v[220:223], v[22:25]
	v_mfma_f32_16x16x32_bf16 v[18:21], v[158:161], v[220:223], v[18:21]
	v_mfma_f32_16x16x32_bf16 v[46:49], v[162:165], v[182:185], v[46:49]
	v_mfma_f32_16x16x32_bf16 v[42:45], v[170:173], v[182:185], v[42:45]
	v_mfma_f32_16x16x32_bf16 v[30:33], v[162:165], v[194:197], v[30:33]
	v_mfma_f32_16x16x32_bf16 v[26:29], v[170:173], v[194:197], v[26:29]
	v_mfma_f32_16x16x32_bf16 v[14:17], v[162:165], v[202:205], v[14:17]
	v_mfma_f32_16x16x32_bf16 v[10:13], v[170:173], v[202:205], v[10:13]
	v_mfma_f32_16x16x32_bf16 v[6:9], v[162:165], v[216:219], v[6:9]
	v_mfma_f32_16x16x32_bf16 v[2:5], v[170:173], v[216:219], v[2:5]
	v_mfma_f32_16x16x32_bf16 v[46:49], v[166:169], v[190:193], v[46:49]
	v_mfma_f32_16x16x32_bf16 v[42:45], v[174:177], v[190:193], v[42:45]
	v_mfma_f32_16x16x32_bf16 v[30:33], v[166:169], v[198:201], v[30:33]
	v_mfma_f32_16x16x32_bf16 v[26:29], v[174:177], v[198:201], v[26:29]
	v_mfma_f32_16x16x32_bf16 v[14:17], v[166:169], v[212:215], v[14:17]
	v_mfma_f32_16x16x32_bf16 v[10:13], v[174:177], v[212:215], v[10:13]
	v_mfma_f32_16x16x32_bf16 v[6:9], v[166:169], v[220:223], v[6:9]
	v_mfma_f32_16x16x32_bf16 v[2:5], v[174:177], v[220:223], v[2:5]
	s_barrier
	s_add_i32 vcc_lo, vcc_lo, 2
	s_add_u32 s61, s61, 0x100
	s_addc_u32 s63, s63, 0
	s_add_u32 s68, s68, 0x100
	s_addc_u32 s69, s69, 0
	s_cmp_gt_u32 vcc_lo, 13
	s_cbranch_scc0 .LBB0_1086
	s_and_b64 vcc, exec, s[56:57]
	s_cbranch_vccz .LBB0_1089
	s_barrier

; #define PG8_STAGE(bufoff, gbase, voff) do { _Pragma("unroll") for (int _i = 0; _i < 2; ++_i) \
;         __builtin_amdgcn_global_load_lds((const unsigned*)((const char*)(gbase) + (voff)[_i]), (LAS unsigned*)(lds + (bufoff) + ldsw + _i * 8192), 16, 0, 0); } while (0)
; #define PG8_LDA(dst, b, h) do { _Pragma("unroll") for (int m = 0; m < 4; ++m) _Pragma("unroll") for (int k = 0; k < 2; ++k) dst[m][k] = *(const LAS bf16x8*)(lds + PG8_SA(b, h) + aoff + m * 2048 + k * 1024); } while (0)
; #define PG8_LDB(dst, b, h) do { _Pragma("unroll") for (int n = 0; n < 2; ++n) _Pragma("unroll") for (int k = 0; k < 2; ++k) dst[n][k] = *(const LAS bf16x8*)(lds + PG8_SB(b, h) + boff + n * 2048 + k * 1024); } while (0)
; #define PG8_MMA(ai, bj, At, Bt) do { __builtin_amdgcn_s_setprio(1); _Pragma("unroll") for (int m = 0; m < 4; ++m) _Pragma("unroll") for (int n = 0; n < 2; ++n) _Pragma("unroll") for (int k = 0; k < 2; ++k) \
;         acc[ai][bj][m][n] = __builtin_amdgcn_mfma_f32_16x16x32_bf16(Bt[n][k], At[m][k], acc[ai][bj][m][n], 0, 0, 0); __builtin_amdgcn_s_setprio(0); } while (0)
; #define PG8_WAIT_V(n) asm volatile("s_waitcnt vmcnt(" #n ")" ::: "memory")
; #define PG8_WAIT_L(n) asm volatile("s_waitcnt lgkmcnt(" #n ")" ::: "memory")
; #define PG8_BAR __builtin_amdgcn_s_barrier()
; #define PG8_SCHED __builtin_amdgcn_sched_barrier(0)
; template <class Epi, class Sched>
; DI void gemm_phase(LAS unsigned char* lds, const int K, const Sched& S, const Epi& E) {
;     ...
;         for (int t = 0; t < nt; t += 2) {
;             const bool last = (t == nt - 2);
;             const char* a1 = cA + (size_t)(t + 1) * kstep;
;             const char* a2 = last ? nA : cA + (size_t)(t + 2) * kstep; const char* b2 = last ? nB : cB + (size_t)(t + 2) * kstep;
;             const char* a3 = a2 + kstep; const char* b3 = b2 + kstep;
;             PG8_LDB(B0, 0, 0); PG8_LDB(B1, 0, 1); PG8_SCHED; PG8_LDA(At, 0, 0); PG8_STAGE(PG8_SA(1, 1), a1 + hstep, voffA);
;             PG8_WAIT_V(8); PG8_WAIT_L(0); PG8_BAR; PG8_MMA(0, 0, At, B0); PG8_MMA(0, 1, At, B1); PG8_BAR; PG8_SCHED;
;             PG8_LDA(At, 0, 1); PG8_STAGE(PG8_SB(0, 0), b2, voffB); PG8_STAGE(PG8_SB(0, 1), b2 + hstep, voffB); PG8_STAGE(PG8_SA(0, 0), a2, voffA);
;             PG8_WAIT_V(8); PG8_WAIT_L(0); PG8_BAR; PG8_MMA(1, 0, At, B0); PG8_MMA(1, 1, At, B1); PG8_BAR; PG8_SCHED;
.LBB0_1204:
	s_add_u32 s60, s58, 0x100
	s_addc_u32 s61, s59, 0
	s_add_i32 s48, 0, 0x10000
	s_cmp_eq_u32 s85, 40
	s_cselect_b32 s65, s55, s61
	s_cselect_b32 s64, s54, s60
	v_add_u32_e32 v145, s48, v143
	s_cselect_b32 s63, s57, s84
	s_cselect_b32 s62, s56, s83
	s_add_i32 s86, 0, 0x14000
	ds_read_b128 v[146:149], v145
	ds_read_b128 v[150:153], v145 offset:1024
	ds_read_b128 v[154:157], v145 offset:2048
	ds_read_b128 v[158:161], v145 offset:3072
	v_add_u32_e32 v145, s86, v143
	ds_read_b128 v[162:165], v145
	ds_read_b128 v[166:169], v145 offset:1024
	ds_read_b128 v[170:173], v145 offset:2048
	ds_read_b128 v[174:177], v145 offset:3072
	s_add_i32 m0, s71, 0xc000
	ds_read_b128 v[182:185], v144
	ds_read_b128 v[190:193], v144 offset:1024
	ds_read_b128 v[194:197], v144 offset:2048
	ds_read_b128 v[198:201], v144 offset:3072
	ds_read_b128 v[202:205], v144 offset:4096
	ds_read_b128 v[212:215], v144 offset:5120
	ds_read_b128 v[216:219], v144 offset:6144
	ds_read_b128 v[220:223], v144 offset:7168
	global_load_lds_dwordx4 v140, s[58:59]
	s_add_i32 m0, s71, 0xe000
	s_nop 0
	global_load_lds_dwordx4 v138, s[58:59]
	s_waitcnt vmcnt(8)
	s_waitcnt lgkmcnt(0)
	s_barrier
	s_waitcnt lgkmcnt(0)
	v_mfma_f32_16x16x32_bf16 v[126:129], v[146:149], v[182:185], v[126:129]
	v_mfma_f32_16x16x32_bf16 v[122:125], v[154:157], v[182:185], v[122:125]
	v_mfma_f32_16x16x32_bf16 v[118:121], v[146:149], v[194:197], v[118:121]
	v_mfma_f32_16x16x32_bf16 v[114:117], v[154:157], v[194:197], v[114:117]
	v_mfma_f32_16x16x32_bf16 v[102:105], v[146:149], v[202:205], v[102:105]
	v_mfma_f32_16x16x32_bf16 v[98:101], v[154:157], v[202:205], v[98:101]
	v_mfma_f32_16x16x32_bf16 v[86:89], v[146:149], v[216:219], v[86:89]
	v_mfma_f32_16x16x32_bf16 v[82:85], v[154:157], v[216:219], v[82:85]
	v_mfma_f32_16x16x32_bf16 v[126:129], v[150:153], v[190:193], v[126:129]
	v_mfma_f32_16x16x32_bf16 v[122:125], v[158:161], v[190:193], v[122:125]
	v_mfma_f32_16x16x32_bf16 v[118:121], v[150:153], v[198:201], v[118:121]
	v_mfma_f32_16x16x32_bf16 v[114:117], v[158:161], v[198:201], v[114:117]
	v_mfma_f32_16x16x32_bf16 v[102:105], v[150:153], v[212:215], v[102:105]
	v_mfma_f32_16x16x32_bf16 v[98:101], v[158:161], v[212:215], v[98:101]
	v_mfma_f32_16x16x32_bf16 v[86:89], v[150:153], v[220:223], v[86:89]
	v_mfma_f32_16x16x32_bf16 v[82:85], v[158:161], v[220:223], v[82:85]
	v_mfma_f32_16x16x32_bf16 v[110:113], v[162:165], v[182:185], v[110:113]
	v_mfma_f32_16x16x32_bf16 v[106:109], v[170:173], v[182:185], v[106:109]
	v_mfma_f32_16x16x32_bf16 v[94:97], v[162:165], v[194:197], v[94:97]
	v_mfma_f32_16x16x32_bf16 v[90:93], v[170:173], v[194:197], v[90:93]
	v_mfma_f32_16x16x32_bf16 v[78:81], v[162:165], v[202:205], v[78:81]
	v_mfma_f32_16x16x32_bf16 v[74:77], v[170:173], v[202:205], v[74:77]
	v_mfma_f32_16x16x32_bf16 v[70:73], v[162:165], v[216:219], v[70:73]
	v_mfma_f32_16x16x32_bf16 v[66:69], v[170:173], v[216:219], v[66:69]
	v_mfma_f32_16x16x32_bf16 v[110:113], v[166:169], v[190:193], v[110:113]
	v_mfma_f32_16x16x32_bf16 v[106:109], v[174:177], v[190:193], v[106:109]
	v_mfma_f32_16x16x32_bf16 v[94:97], v[166:169], v[198:201], v[94:97]
	v_mfma_f32_16x16x32_bf16 v[90:93], v[174:177], v[198:201], v[90:93]
	v_mfma_f32_16x16x32_bf16 v[78:81], v[166:169], v[212:215], v[78:81]
	v_mfma_f32_16x16x32_bf16 v[74:77], v[174:177], v[212:215], v[74:77]
	v_mfma_f32_16x16x32_bf16 v[70:73], v[166:169], v[220:223], v[70:73]
	v_mfma_f32_16x16x32_bf16 v[66:69], v[174:177], v[220:223], v[66:69]
	s_barrier
	s_add_i32 s48, s48, s69
	s_mov_b32 m0, s48
	ds_read_b128 v[182:185], v144 offset:16384
	ds_read_b128 v[190:193], v144 offset:17408
	ds_read_b128 v[194:197], v144 offset:18432
	ds_read_b128 v[198:201], v144 offset:19456
	ds_read_b128 v[202:205], v144 offset:20480
	ds_read_b128 v[212:215], v144 offset:21504
	ds_read_b128 v[216:219], v144 offset:22528
	ds_read_b128 v[220:223], v144 offset:23552
	global_load_lds_dwordx4 v134, s[62:63]
	s_add_i32 m0, s48, 0x2000
	s_add_u32 s48, s62, 0xb0000
	s_addc_u32 s49, s63, 0
	s_add_i32 s58, s86, s69
	global_load_lds_dwordx4 v130, s[62:63]
	s_mov_b32 m0, s58
	s_nop 0
	global_load_lds_dwordx4 v134, s[48:49]
	s_add_i32 m0, s58, 0x2000
	s_nop 0
	global_load_lds_dwordx4 v130, s[48:49]
	s_add_u32 s98, s64, s90
	s_addc_u32 s99, s65, s91
	s_waitcnt vmcnt(6)
	s_waitcnt lgkmcnt(0)
	s_barrier
	s_waitcnt lgkmcnt(0)
	v_mfma_f32_16x16x32_bf16 v[62:65], v[146:149], v[182:185], v[62:65]
	v_mfma_f32_16x16x32_bf16 v[58:61], v[154:157], v[182:185], v[58:61]
	v_mfma_f32_16x16x32_bf16 v[54:57], v[146:149], v[194:197], v[54:57]
	v_mfma_f32_16x16x32_bf16 v[50:53], v[154:157], v[194:197], v[50:53]
	v_mfma_f32_16x16x32_bf16 v[38:41], v[146:149], v[202:205], v[38:41]
	v_mfma_f32_16x16x32_bf16 v[34:37], v[154:157], v[202:205], v[34:37]
	v_mfma_f32_16x16x32_bf16 v[22:25], v[146:149], v[216:219], v[22:25]
	v_mfma_f32_16x16x32_bf16 v[18:21], v[154:157], v[216:219], v[18:21]
	v_mfma_f32_16x16x32_bf16 v[62:65], v[150:153], v[190:193], v[62:65]
	v_mfma_f32_16x16x32_bf16 v[58:61], v[158:161], v[190:193], v[58:61]
	v_mfma_f32_16x16x32_bf16 v[54:57], v[150:153], v[198:201], v[54:57]
	v_mfma_f32_16x16x32_bf16 v[50:53], v[158:161], v[198:201], v[50:53]
	v_mfma_f32_16x16x32_bf16 v[38:41], v[150:153], v[212:215], v[38:41]
	v_mfma_f32_16x16x32_bf16 v[34:37], v[158:161], v[212:215], v[34:37]
	v_mfma_f32_16x16x32_bf16 v[22:25], v[150:153], v[220:223], v[22:25]
	v_mfma_f32_16x16x32_bf16 v[18:21], v[158:161], v[220:223], v[18:21]
	v_mfma_f32_16x16x32_bf16 v[46:49], v[162:165], v[182:185], v[46:49]
	v_mfma_f32_16x16x32_bf16 v[42:45], v[170:173], v[182:185], v[42:45]
	v_mfma_f32_16x16x32_bf16 v[30:33], v[162:165], v[194:197], v[30:33]
	v_mfma_f32_16x16x32_bf16 v[26:29], v[170:173], v[194:197], v[26:29]
	v_mfma_f32_16x16x32_bf16 v[14:17], v[162:165], v[202:205], v[14:17]
	v_mfma_f32_16x16x32_bf16 v[10:13], v[170:173], v[202:205], v[10:13]
	v_mfma_f32_16x16x32_bf16 v[6:9], v[162:165], v[216:219], v[6:9]
	v_mfma_f32_16x16x32_bf16 v[2:5], v[170:173], v[216:219], v[2:5]
	v_mfma_f32_16x16x32_bf16 v[46:49], v[166:169], v[190:193], v[46:49]
	v_mfma_f32_16x16x32_bf16 v[42:45], v[174:177], v[190:193], v[42:45]
	v_mfma_f32_16x16x32_bf16 v[30:33], v[166:169], v[198:201], v[30:33]
	v_mfma_f32_16x16x32_bf16 v[26:29], v[174:177], v[198:201], v[26:29]
	v_mfma_f32_16x16x32_bf16 v[14:17], v[166:169], v[212:215], v[14:17]
	v_mfma_f32_16x16x32_bf16 v[10:13], v[174:177], v[212:215], v[10:13]
	v_mfma_f32_16x16x32_bf16 v[6:9], v[166:169], v[220:223], v[6:9]
	v_mfma_f32_16x16x32_bf16 v[2:5], v[174:177], v[220:223], v[2:5]
	s_barrier
; #define PG8_STAGE(bufoff, gbase, voff) do { _Pragma("unroll") for (int _i = 0; _i < 2; ++_i) \
;         __builtin_amdgcn_global_load_lds((const unsigned*)((const char*)(gbase) + (voff)[_i]), (LAS unsigned*)(lds + (bufoff) + ldsw + _i * 8192), 16, 0, 0); } while (0)
; #define PG8_LDA(dst, b, h) do { _Pragma("unroll") for (int m = 0; m < 4; ++m) _Pragma("unroll") for (int k = 0; k < 2; ++k) dst[m][k] = *(const LAS bf16x8*)(lds + PG8_SA(b, h) + aoff + m * 2048 + k * 1024); } while (0)
; #define PG8_LDB(dst, b, h) do { _Pragma("unroll") for (int n = 0; n < 2; ++n) _Pragma("unroll") for (int k = 0; k < 2; ++k) dst[n][k] = *(const LAS bf16x8*)(lds + PG8_SB(b, h) + boff + n * 2048 + k * 1024); } while (0)
; #define PG8_MMA(ai, bj, At, Bt) do { __builtin_amdgcn_s_setprio(1); _Pragma("unroll") for (int m = 0; m < 4; ++m) _Pragma("unroll") for (int n = 0; n < 2; ++n) _Pragma("unroll") for (int k = 0; k < 2; ++k) \
;         acc[ai][bj][m][n] = __builtin_amdgcn_mfma_f32_16x16x32_bf16(Bt[n][k], At[m][k], acc[ai][bj][m][n], 0, 0, 0); __builtin_amdgcn_s_setprio(0); } while (0)
; #define PG8_WAIT_V(n) asm volatile("s_waitcnt vmcnt(" #n ")" ::: "memory")
; #define PG8_WAIT_L(n) asm volatile("s_waitcnt lgkmcnt(" #n ")" ::: "memory")
; #define PG8_BAR __builtin_amdgcn_s_barrier()
; #define PG8_SCHED __builtin_amdgcn_sched_barrier(0)
; template <class Epi, class Sched>
; DI void gemm_phase(LAS unsigned char* lds, const int K, const Sched& S, const Epi& E) {
;     ...
;             PG8_LDB(B0, 1, 0); PG8_LDB(B1, 1, 1); PG8_SCHED; PG8_LDA(At, 1, 0); PG8_STAGE(PG8_SA(0, 1), a2 + hstep, voffA);
;             PG8_WAIT_V(8); PG8_WAIT_L(0); PG8_BAR; PG8_MMA(0, 0, At, B0); PG8_MMA(0, 1, At, B1); PG8_BAR; PG8_SCHED;
;             PG8_LDA(At, 1, 1); PG8_STAGE(PG8_SB(1, 0), b3, voffB); PG8_STAGE(PG8_SB(1, 1), b3 + hstep, voffB); PG8_STAGE(PG8_SA(1, 0), a3, voffA);
;             PG8_WAIT_V(8); PG8_WAIT_L(0); PG8_BAR; PG8_MMA(1, 0, At, B0); PG8_MMA(1, 1, At, B1); PG8_BAR; PG8_SCHED;
;         }
;         if (wr == 0) PG8_BAR;
	s_add_i32 s58, 0, 0x18000
	v_add_u32_e32 v145, s58, v143
	s_add_i32 s59, 0, 0x1c000
	ds_read_b128 v[146:149], v145
	ds_read_b128 v[150:153], v145 offset:1024
	ds_read_b128 v[154:157], v145 offset:2048
	ds_read_b128 v[158:161], v145 offset:3072
	v_add_u32_e32 v145, s59, v143
	ds_read_b128 v[162:165], v145
	ds_read_b128 v[166:169], v145 offset:1024
	ds_read_b128 v[170:173], v145 offset:2048
	ds_read_b128 v[174:177], v145 offset:3072
	s_mov_b32 m0, s71
	ds_read_b128 v[182:185], v144 offset:32768
	ds_read_b128 v[190:193], v144 offset:33792
	ds_read_b128 v[194:197], v144 offset:34816
	ds_read_b128 v[198:201], v144 offset:35840
	ds_read_b128 v[202:205], v144 offset:36864
	ds_read_b128 v[212:215], v144 offset:37888
	ds_read_b128 v[216:219], v144 offset:38912
	ds_read_b128 v[220:223], v144 offset:39936
	global_load_lds_dwordx4 v136, s[64:65]
	s_mov_b32 m0, s72
	s_nop 0
	global_load_lds_dwordx4 v132, s[64:65]
	s_add_u32 s48, s64, 0xb0000
	s_addc_u32 s49, s65, 0
	s_mov_b32 m0, s73
	s_nop 0
	global_load_lds_dwordx4 v136, s[48:49]
	s_mov_b32 m0, s74
	s_nop 0
	global_load_lds_dwordx4 v132, s[48:49]
	s_waitcnt vmcnt(8)
	s_waitcnt lgkmcnt(0)
	s_barrier
	s_waitcnt lgkmcnt(0)
	v_mfma_f32_16x16x32_bf16 v[126:129], v[146:149], v[182:185], v[126:129]
	v_mfma_f32_16x16x32_bf16 v[122:125], v[154:157], v[182:185], v[122:125]
	v_mfma_f32_16x16x32_bf16 v[118:121], v[146:149], v[194:197], v[118:121]
	v_mfma_f32_16x16x32_bf16 v[114:117], v[154:157], v[194:197], v[114:117]
	v_mfma_f32_16x16x32_bf16 v[102:105], v[146:149], v[202:205], v[102:105]
	v_mfma_f32_16x16x32_bf16 v[98:101], v[154:157], v[202:205], v[98:101]
	v_mfma_f32_16x16x32_bf16 v[86:89], v[146:149], v[216:219], v[86:89]
	v_mfma_f32_16x16x32_bf16 v[82:85], v[154:157], v[216:219], v[82:85]
	v_mfma_f32_16x16x32_bf16 v[126:129], v[150:153], v[190:193], v[126:129]
	v_mfma_f32_16x16x32_bf16 v[122:125], v[158:161], v[190:193], v[122:125]
	v_mfma_f32_16x16x32_bf16 v[118:121], v[150:153], v[198:201], v[118:121]
	v_mfma_f32_16x16x32_bf16 v[114:117], v[158:161], v[198:201], v[114:117]
	v_mfma_f32_16x16x32_bf16 v[102:105], v[150:153], v[212:215], v[102:105]
	v_mfma_f32_16x16x32_bf16 v[98:101], v[158:161], v[212:215], v[98:101]
	v_mfma_f32_16x16x32_bf16 v[86:89], v[150:153], v[220:223], v[86:89]
	v_mfma_f32_16x16x32_bf16 v[82:85], v[158:161], v[220:223], v[82:85]
	v_mfma_f32_16x16x32_bf16 v[110:113], v[162:165], v[182:185], v[110:113]
	v_mfma_f32_16x16x32_bf16 v[106:109], v[170:173], v[182:185], v[106:109]
	v_mfma_f32_16x16x32_bf16 v[94:97], v[162:165], v[194:197], v[94:97]
	v_mfma_f32_16x16x32_bf16 v[90:93], v[170:173], v[194:197], v[90:93]
	v_mfma_f32_16x16x32_bf16 v[78:81], v[162:165], v[202:205], v[78:81]
	v_mfma_f32_16x16x32_bf16 v[74:77], v[170:173], v[202:205], v[74:77]
	v_mfma_f32_16x16x32_bf16 v[70:73], v[162:165], v[216:219], v[70:73]
	v_mfma_f32_16x16x32_bf16 v[66:69], v[170:173], v[216:219], v[66:69]
	v_mfma_f32_16x16x32_bf16 v[110:113], v[166:169], v[190:193], v[110:113]
	v_mfma_f32_16x16x32_bf16 v[106:109], v[174:177], v[190:193], v[106:109]
	v_mfma_f32_16x16x32_bf16 v[94:97], v[166:169], v[198:201], v[94:97]
	v_mfma_f32_16x16x32_bf16 v[90:93], v[174:177], v[198:201], v[90:93]
	v_mfma_f32_16x16x32_bf16 v[78:81], v[166:169], v[212:215], v[78:81]
	v_mfma_f32_16x16x32_bf16 v[74:77], v[174:177], v[212:215], v[74:77]
	v_mfma_f32_16x16x32_bf16 v[70:73], v[166:169], v[220:223], v[70:73]
	v_mfma_f32_16x16x32_bf16 v[66:69], v[174:177], v[220:223], v[66:69]
	s_barrier
	s_add_i32 s48, s58, s69
	s_add_u32 s62, s62, 0x80
	s_addc_u32 s63, s63, 0
	s_mov_b32 m0, s48
	ds_read_b128 v[182:185], v144 offset:49152
	ds_read_b128 v[190:193], v144 offset:50176
	ds_read_b128 v[194:197], v144 offset:51200
	ds_read_b128 v[198:201], v144 offset:52224
	ds_read_b128 v[202:205], v144 offset:53248
	ds_read_b128 v[212:215], v144 offset:54272
	ds_read_b128 v[216:219], v144 offset:55296
	ds_read_b128 v[220:223], v144 offset:56320
	global_load_lds_dwordx4 v134, s[62:63]
	s_add_i32 m0, s48, 0x2000
	s_add_u32 s48, s62, 0xb0000
	s_addc_u32 s49, s63, 0
	s_add_i32 s58, s59, s69
	global_load_lds_dwordx4 v130, s[62:63]
	s_mov_b32 m0, s58
	s_nop 0
	global_load_lds_dwordx4 v134, s[48:49]
	s_add_i32 m0, s58, 0x2000
	s_nop 0
	global_load_lds_dwordx4 v130, s[48:49]
	s_mov_b32 m0, s77
	s_nop 0
	global_load_lds_dwordx4 v136, s[98:99]
	s_mov_b32 m0, s78
	s_nop 0
	global_load_lds_dwordx4 v132, s[98:99]
	s_waitcnt vmcnt(8)
	s_waitcnt lgkmcnt(0)
	s_barrier
	s_waitcnt lgkmcnt(0)
	v_mfma_f32_16x16x32_bf16 v[62:65], v[146:149], v[182:185], v[62:65]
	v_mfma_f32_16x16x32_bf16 v[58:61], v[154:157], v[182:185], v[58:61]
	v_mfma_f32_16x16x32_bf16 v[54:57], v[146:149], v[194:197], v[54:57]
	v_mfma_f32_16x16x32_bf16 v[50:53], v[154:157], v[194:197], v[50:53]
	v_mfma_f32_16x16x32_bf16 v[38:41], v[146:149], v[202:205], v[38:41]
	v_mfma_f32_16x16x32_bf16 v[34:37], v[154:157], v[202:205], v[34:37]
	v_mfma_f32_16x16x32_bf16 v[22:25], v[146:149], v[216:219], v[22:25]
	v_mfma_f32_16x16x32_bf16 v[18:21], v[154:157], v[216:219], v[18:21]
	v_mfma_f32_16x16x32_bf16 v[62:65], v[150:153], v[190:193], v[62:65]
	v_mfma_f32_16x16x32_bf16 v[58:61], v[158:161], v[190:193], v[58:61]
	v_mfma_f32_16x16x32_bf16 v[54:57], v[150:153], v[198:201], v[54:57]
	v_mfma_f32_16x16x32_bf16 v[50:53], v[158:161], v[198:201], v[50:53]
	v_mfma_f32_16x16x32_bf16 v[38:41], v[150:153], v[212:215], v[38:41]
	v_mfma_f32_16x16x32_bf16 v[34:37], v[158:161], v[212:215], v[34:37]
	v_mfma_f32_16x16x32_bf16 v[22:25], v[150:153], v[220:223], v[22:25]
	v_mfma_f32_16x16x32_bf16 v[18:21], v[158:161], v[220:223], v[18:21]
	v_mfma_f32_16x16x32_bf16 v[46:49], v[162:165], v[182:185], v[46:49]
	v_mfma_f32_16x16x32_bf16 v[42:45], v[170:173], v[182:185], v[42:45]
	v_mfma_f32_16x16x32_bf16 v[30:33], v[162:165], v[194:197], v[30:33]
	v_mfma_f32_16x16x32_bf16 v[26:29], v[170:173], v[194:197], v[26:29]
	v_mfma_f32_16x16x32_bf16 v[14:17], v[162:165], v[202:205], v[14:17]
	v_mfma_f32_16x16x32_bf16 v[10:13], v[170:173], v[202:205], v[10:13]
	v_mfma_f32_16x16x32_bf16 v[6:9], v[162:165], v[216:219], v[6:9]
	v_mfma_f32_16x16x32_bf16 v[2:5], v[170:173], v[216:219], v[2:5]
	v_mfma_f32_16x16x32_bf16 v[46:49], v[166:169], v[190:193], v[46:49]
	v_mfma_f32_16x16x32_bf16 v[42:45], v[174:177], v[190:193], v[42:45]
	v_mfma_f32_16x16x32_bf16 v[30:33], v[166:169], v[198:201], v[30:33]
	v_mfma_f32_16x16x32_bf16 v[26:29], v[174:177], v[198:201], v[26:29]
	v_mfma_f32_16x16x32_bf16 v[14:17], v[166:169], v[212:215], v[14:17]
	v_mfma_f32_16x16x32_bf16 v[10:13], v[174:177], v[212:215], v[10:13]
	v_mfma_f32_16x16x32_bf16 v[6:9], v[166:169], v[220:223], v[6:9]
	v_mfma_f32_16x16x32_bf16 v[2:5], v[174:177], v[220:223], v[2:5]
	s_barrier
	s_add_i32 s85, s85, 2
	s_add_u32 s83, s83, 0x100
	s_addc_u32 s84, s84, 0
	s_cmp_gt_u32 s85, 41
	s_mov_b64 s[58:59], s[60:61]
	s_cbranch_scc0 .LBB0_1204
	s_and_b64 vcc, exec, s[52:53]
	s_cbranch_vccz .LBB0_1207
	s_barrier
